# v18 with every s_setprio removed from the 8-phase K-loop stages (no priority flips at all in GEMM loops)
# speedup vs baseline: 1.0057x; 1.0010x over previous
.LBB0_285:
	ds_read_b128 v[154:157], v151
	ds_read_b128 v[158:161], v151 offset:1024
	ds_read_b128 v[164:167], v151 offset:2048
	ds_read_b128 v[168:171], v151 offset:3072
	ds_read_b128 v[172:175], v152
	ds_read_b128 v[176:179], v152 offset:1024
	ds_read_b128 v[180:183], v152 offset:2048
	ds_read_b128 v[184:187], v152 offset:3072
	s_add_u32 s36, s34, 0xfff80080
	s_addc_u32 s37, s35, -1
	s_cmp_eq_u32 s53, 28
	s_cselect_b32 s39, s16, s37
	s_cselect_b32 s38, s17, s36
	s_cselect_b32 s37, s18, s25
	s_cselect_b32 s36, s19, s23
	v_lshl_add_u64 v[146:147], s[34:35], 0, v[138:139]
	s_add_i32 m0, s31, 0xc000
	ds_read_b128 v[188:191], v153
	ds_read_b128 v[192:195], v153 offset:1024
	ds_read_b128 v[196:199], v153 offset:2048
	ds_read_b128 v[200:203], v153 offset:3072
	ds_read_b128 v[204:207], v153 offset:4096
	ds_read_b128 v[208:211], v153 offset:5120
	ds_read_b128 v[212:215], v153 offset:6144
	ds_read_b128 v[216:219], v153 offset:7168
	global_load_lds_dwordx4 v[146:147], off
	v_lshl_add_u64 v[146:147], s[34:35], 0, v[140:141]
	s_add_i32 m0, s31, 0xe000
	s_nop 0
	global_load_lds_dwordx4 v[146:147], off
	s_waitcnt vmcnt(8)
	s_waitcnt lgkmcnt(0)
	s_waitcnt lgkmcnt(0)
	v_mfma_f32_16x16x32_bf16 v[126:129], v[154:157], v[188:191], v[126:129]
	v_mfma_f32_16x16x32_bf16 v[122:125], v[164:167], v[188:191], v[122:125]
	v_mfma_f32_16x16x32_bf16 v[110:113], v[154:157], v[196:199], v[110:113]
	v_mfma_f32_16x16x32_bf16 v[106:109], v[164:167], v[196:199], v[106:109]
	s_barrier
	v_mfma_f32_16x16x32_bf16 v[94:97], v[154:157], v[204:207], v[94:97]
	v_mfma_f32_16x16x32_bf16 v[90:93], v[164:167], v[204:207], v[90:93]
	v_mfma_f32_16x16x32_bf16 v[78:81], v[154:157], v[212:215], v[78:81]
	v_mfma_f32_16x16x32_bf16 v[74:77], v[164:167], v[212:215], v[74:77]
	v_mfma_f32_16x16x32_bf16 v[126:129], v[158:161], v[192:195], v[126:129]
	v_mfma_f32_16x16x32_bf16 v[122:125], v[168:171], v[192:195], v[122:125]
	v_mfma_f32_16x16x32_bf16 v[110:113], v[158:161], v[200:203], v[110:113]
	v_mfma_f32_16x16x32_bf16 v[106:109], v[168:171], v[200:203], v[106:109]
	v_mfma_f32_16x16x32_bf16 v[94:97], v[158:161], v[208:211], v[94:97]
	v_mfma_f32_16x16x32_bf16 v[90:93], v[168:171], v[208:211], v[90:93]
	v_mfma_f32_16x16x32_bf16 v[78:81], v[158:161], v[216:219], v[78:81]
	v_mfma_f32_16x16x32_bf16 v[74:77], v[168:171], v[216:219], v[74:77]
	v_mfma_f32_16x16x32_bf16 v[118:121], v[172:175], v[188:191], v[118:121]
	v_mfma_f32_16x16x32_bf16 v[114:117], v[180:183], v[188:191], v[114:117]
	v_mfma_f32_16x16x32_bf16 v[102:105], v[172:175], v[196:199], v[102:105]
	v_mfma_f32_16x16x32_bf16 v[98:101], v[180:183], v[196:199], v[98:101]
	v_mfma_f32_16x16x32_bf16 v[86:89], v[172:175], v[204:207], v[86:89]
	v_mfma_f32_16x16x32_bf16 v[82:85], v[180:183], v[204:207], v[82:85]
	v_mfma_f32_16x16x32_bf16 v[70:73], v[172:175], v[212:215], v[70:73]
	v_mfma_f32_16x16x32_bf16 v[66:69], v[180:183], v[212:215], v[66:69]
	v_mfma_f32_16x16x32_bf16 v[118:121], v[176:179], v[192:195], v[118:121]
	v_mfma_f32_16x16x32_bf16 v[114:117], v[184:187], v[192:195], v[114:117]
	v_mfma_f32_16x16x32_bf16 v[102:105], v[176:179], v[200:203], v[102:105]
	v_mfma_f32_16x16x32_bf16 v[98:101], v[184:187], v[200:203], v[98:101]
	v_mfma_f32_16x16x32_bf16 v[86:89], v[176:179], v[208:211], v[86:89]
	v_mfma_f32_16x16x32_bf16 v[82:85], v[184:187], v[208:211], v[82:85]
	v_mfma_f32_16x16x32_bf16 v[70:73], v[176:179], v[216:219], v[70:73]
	v_mfma_f32_16x16x32_bf16 v[66:69], v[184:187], v[216:219], v[66:69]
	s_barrier
	s_add_i32 s54, s15, s44
	v_lshl_add_u64 v[146:147], s[36:37], 0, v[134:135]
	s_mov_b32 m0, s54
	ds_read_b128 v[188:191], v153 offset:16384
	ds_read_b128 v[192:195], v153 offset:17408
	ds_read_b128 v[196:199], v153 offset:18432
	ds_read_b128 v[200:203], v153 offset:19456
	ds_read_b128 v[204:207], v153 offset:20480
	ds_read_b128 v[208:211], v153 offset:21504
	ds_read_b128 v[212:215], v153 offset:22528
	ds_read_b128 v[216:219], v153 offset:23552
	global_load_lds_dwordx4 v[146:147], off
	s_add_i32 m0, s54, 0x2000
	s_add_u32 s54, s36, 0x80000
	v_lshl_add_u64 v[220:221], s[36:37], 0, v[130:131]
	s_addc_u32 s55, s37, 0
	s_add_i32 s56, s51, s44
	global_load_lds_dwordx4 v[220:221], off
	v_lshl_add_u64 v[222:223], s[54:55], 0, v[134:135]
	s_mov_b32 m0, s56
	v_lshl_add_u64 v[224:225], s[38:39], 0, v[132:133]
	global_load_lds_dwordx4 v[222:223], off
	v_lshl_add_u64 v[222:223], s[54:55], 0, v[130:131]
	s_add_i32 m0, s56, 0x2000
	s_nop 0
	global_load_lds_dwordx4 v[222:223], off
	v_lshl_add_u64 v[222:223], s[38:39], 0, v[136:137]
	s_mov_b32 m0, s31
	s_nop 0
	global_load_lds_dwordx4 v[222:223], off
	s_mov_b32 m0, s47
	s_nop 0
	global_load_lds_dwordx4 v[224:225], off
	s_waitcnt vmcnt(8)
	s_waitcnt lgkmcnt(0)
	s_waitcnt lgkmcnt(0)
	v_mfma_f32_16x16x32_bf16 v[62:65], v[154:157], v[188:191], v[62:65]
	v_mfma_f32_16x16x32_bf16 v[58:61], v[164:167], v[188:191], v[58:61]
	v_mfma_f32_16x16x32_bf16 v[46:49], v[154:157], v[196:199], v[46:49]
	v_mfma_f32_16x16x32_bf16 v[42:45], v[164:167], v[196:199], v[42:45]
	s_barrier
	v_mfma_f32_16x16x32_bf16 v[30:33], v[154:157], v[204:207], v[30:33]
	v_mfma_f32_16x16x32_bf16 v[26:29], v[164:167], v[204:207], v[26:29]
	v_mfma_f32_16x16x32_bf16 v[14:17], v[154:157], v[212:215], v[14:17]
	v_mfma_f32_16x16x32_bf16 v[10:13], v[164:167], v[212:215], v[10:13]
	v_mfma_f32_16x16x32_bf16 v[62:65], v[158:161], v[192:195], v[62:65]
	v_mfma_f32_16x16x32_bf16 v[58:61], v[168:171], v[192:195], v[58:61]
	v_mfma_f32_16x16x32_bf16 v[46:49], v[158:161], v[200:203], v[46:49]
	v_mfma_f32_16x16x32_bf16 v[42:45], v[168:171], v[200:203], v[42:45]
	v_mfma_f32_16x16x32_bf16 v[30:33], v[158:161], v[208:211], v[30:33]
	v_mfma_f32_16x16x32_bf16 v[26:29], v[168:171], v[208:211], v[26:29]
	v_mfma_f32_16x16x32_bf16 v[14:17], v[158:161], v[216:219], v[14:17]
	v_mfma_f32_16x16x32_bf16 v[10:13], v[168:171], v[216:219], v[10:13]
	v_mfma_f32_16x16x32_bf16 v[54:57], v[172:175], v[188:191], v[54:57]
	v_mfma_f32_16x16x32_bf16 v[50:53], v[180:183], v[188:191], v[50:53]
	v_mfma_f32_16x16x32_bf16 v[38:41], v[172:175], v[196:199], v[38:41]
	v_mfma_f32_16x16x32_bf16 v[34:37], v[180:183], v[196:199], v[34:37]
	v_mfma_f32_16x16x32_bf16 v[22:25], v[172:175], v[204:207], v[22:25]
	v_mfma_f32_16x16x32_bf16 v[18:21], v[180:183], v[204:207], v[18:21]
	v_mfma_f32_16x16x32_bf16 v[6:9], v[172:175], v[212:215], v[6:9]
	v_mfma_f32_16x16x32_bf16 v[2:5], v[180:183], v[212:215], v[2:5]
	v_mfma_f32_16x16x32_bf16 v[54:57], v[176:179], v[192:195], v[54:57]
	v_mfma_f32_16x16x32_bf16 v[50:53], v[184:187], v[192:195], v[50:53]
	v_mfma_f32_16x16x32_bf16 v[38:41], v[176:179], v[200:203], v[38:41]
	v_mfma_f32_16x16x32_bf16 v[34:37], v[184:187], v[200:203], v[34:37]
	v_mfma_f32_16x16x32_bf16 v[22:25], v[176:179], v[208:211], v[22:25]
	v_mfma_f32_16x16x32_bf16 v[18:21], v[184:187], v[208:211], v[18:21]
	v_mfma_f32_16x16x32_bf16 v[6:9], v[176:179], v[216:219], v[6:9]
	v_mfma_f32_16x16x32_bf16 v[2:5], v[184:187], v[216:219], v[2:5]
	s_barrier
	s_add_i32 s54, 0, 0x18000
	v_add_u32_e32 v163, s54, v149
	s_add_i32 s55, 0, 0x1c000
	ds_read_b128 v[154:157], v163
	ds_read_b128 v[158:161], v163 offset:1024
	ds_read_b128 v[164:167], v163 offset:2048
	ds_read_b128 v[168:171], v163 offset:3072
	v_add_u32_e32 v163, s55, v149
	ds_read_b128 v[172:175], v163
	ds_read_b128 v[176:179], v163 offset:1024
	ds_read_b128 v[180:183], v163 offset:2048
	ds_read_b128 v[184:187], v163 offset:3072
	s_add_u32 s38, s38, 0x80000
	s_addc_u32 s39, s39, 0
	s_mov_b32 m0, s48
	v_lshl_add_u64 v[226:227], s[38:39], 0, v[136:137]
	ds_read_b128 v[188:191], v153 offset:32768
	ds_read_b128 v[192:195], v153 offset:33792
	ds_read_b128 v[196:199], v153 offset:34816
	ds_read_b128 v[200:203], v153 offset:35840
	ds_read_b128 v[204:207], v153 offset:36864
	ds_read_b128 v[208:211], v153 offset:37888
	ds_read_b128 v[212:215], v153 offset:38912
	ds_read_b128 v[216:219], v153 offset:39936
	global_load_lds_dwordx4 v[226:227], off
	v_lshl_add_u64 v[226:227], s[38:39], 0, v[132:133]
	s_mov_b32 m0, s49
	s_nop 0
	global_load_lds_dwordx4 v[226:227], off
	s_waitcnt vmcnt(8)
	s_waitcnt lgkmcnt(0)
	s_waitcnt lgkmcnt(0)
	v_mfma_f32_16x16x32_bf16 v[126:129], v[154:157], v[188:191], v[126:129]
	v_mfma_f32_16x16x32_bf16 v[122:125], v[164:167], v[188:191], v[122:125]
	v_mfma_f32_16x16x32_bf16 v[110:113], v[154:157], v[196:199], v[110:113]
	v_mfma_f32_16x16x32_bf16 v[106:109], v[164:167], v[196:199], v[106:109]
	s_barrier
	v_mfma_f32_16x16x32_bf16 v[94:97], v[154:157], v[204:207], v[94:97]
	v_mfma_f32_16x16x32_bf16 v[90:93], v[164:167], v[204:207], v[90:93]
	v_mfma_f32_16x16x32_bf16 v[78:81], v[154:157], v[212:215], v[78:81]
	v_mfma_f32_16x16x32_bf16 v[74:77], v[164:167], v[212:215], v[74:77]
	v_mfma_f32_16x16x32_bf16 v[126:129], v[158:161], v[192:195], v[126:129]
	v_mfma_f32_16x16x32_bf16 v[122:125], v[168:171], v[192:195], v[122:125]
	v_mfma_f32_16x16x32_bf16 v[110:113], v[158:161], v[200:203], v[110:113]
	v_mfma_f32_16x16x32_bf16 v[106:109], v[168:171], v[200:203], v[106:109]
	v_mfma_f32_16x16x32_bf16 v[94:97], v[158:161], v[208:211], v[94:97]
	v_mfma_f32_16x16x32_bf16 v[90:93], v[168:171], v[208:211], v[90:93]
	v_mfma_f32_16x16x32_bf16 v[78:81], v[158:161], v[216:219], v[78:81]
	v_mfma_f32_16x16x32_bf16 v[74:77], v[168:171], v[216:219], v[74:77]
	v_mfma_f32_16x16x32_bf16 v[118:121], v[172:175], v[188:191], v[118:121]
	v_mfma_f32_16x16x32_bf16 v[114:117], v[180:183], v[188:191], v[114:117]
	v_mfma_f32_16x16x32_bf16 v[102:105], v[172:175], v[196:199], v[102:105]
	v_mfma_f32_16x16x32_bf16 v[98:101], v[180:183], v[196:199], v[98:101]
	v_mfma_f32_16x16x32_bf16 v[86:89], v[172:175], v[204:207], v[86:89]
	v_mfma_f32_16x16x32_bf16 v[82:85], v[180:183], v[204:207], v[82:85]
	v_mfma_f32_16x16x32_bf16 v[70:73], v[172:175], v[212:215], v[70:73]
	v_mfma_f32_16x16x32_bf16 v[66:69], v[180:183], v[212:215], v[66:69]
	v_mfma_f32_16x16x32_bf16 v[118:121], v[176:179], v[192:195], v[118:121]
	v_mfma_f32_16x16x32_bf16 v[114:117], v[184:187], v[192:195], v[114:117]
	v_mfma_f32_16x16x32_bf16 v[102:105], v[176:179], v[200:203], v[102:105]
	v_mfma_f32_16x16x32_bf16 v[98:101], v[184:187], v[200:203], v[98:101]
	v_mfma_f32_16x16x32_bf16 v[86:89], v[176:179], v[208:211], v[86:89]
	v_mfma_f32_16x16x32_bf16 v[82:85], v[184:187], v[208:211], v[82:85]
	v_mfma_f32_16x16x32_bf16 v[70:73], v[176:179], v[216:219], v[70:73]
	v_mfma_f32_16x16x32_bf16 v[66:69], v[184:187], v[216:219], v[66:69]
	s_barrier
	s_add_i32 s38, s54, s44
	v_lshl_add_u64 v[146:147], v[146:147], 0, s[10:11]
	s_mov_b32 m0, s38
	ds_read_b128 v[188:191], v153 offset:49152
	ds_read_b128 v[192:195], v153 offset:50176
	ds_read_b128 v[196:199], v153 offset:51200
	ds_read_b128 v[200:203], v153 offset:52224
	ds_read_b128 v[204:207], v153 offset:53248
	ds_read_b128 v[208:211], v153 offset:54272
	ds_read_b128 v[212:215], v153 offset:55296
	ds_read_b128 v[216:219], v153 offset:56320
	global_load_lds_dwordx4 v[146:147], off
	s_add_i32 m0, s38, 0x2000
	s_add_u32 s36, s36, 0x80080
	v_lshl_add_u64 v[146:147], v[220:221], 0, s[10:11]
	s_addc_u32 s37, s37, 0
	s_add_i32 s38, s55, s44
	global_load_lds_dwordx4 v[146:147], off
	v_lshl_add_u64 v[146:147], s[36:37], 0, v[134:135]
	s_mov_b32 m0, s38
	s_nop 0
	global_load_lds_dwordx4 v[146:147], off
	v_lshl_add_u64 v[146:147], s[36:37], 0, v[130:131]
	s_add_i32 m0, s38, 0x2000
	s_nop 0
	global_load_lds_dwordx4 v[146:147], off
	v_lshl_add_u64 v[146:147], v[222:223], 0, s[10:11]
	s_mov_b32 m0, s20
	s_nop 0
	global_load_lds_dwordx4 v[146:147], off
	v_lshl_add_u64 v[146:147], v[224:225], 0, s[10:11]
	s_mov_b32 m0, s21
	s_nop 0
	global_load_lds_dwordx4 v[146:147], off
	s_waitcnt vmcnt(8)
	s_waitcnt lgkmcnt(0)
	s_waitcnt lgkmcnt(0)
	v_mfma_f32_16x16x32_bf16 v[62:65], v[154:157], v[188:191], v[62:65]
	v_mfma_f32_16x16x32_bf16 v[58:61], v[164:167], v[188:191], v[58:61]
	v_mfma_f32_16x16x32_bf16 v[46:49], v[154:157], v[196:199], v[46:49]
	v_mfma_f32_16x16x32_bf16 v[42:45], v[164:167], v[196:199], v[42:45]
	s_barrier
	v_mfma_f32_16x16x32_bf16 v[30:33], v[154:157], v[204:207], v[30:33]
	v_mfma_f32_16x16x32_bf16 v[26:29], v[164:167], v[204:207], v[26:29]
	v_mfma_f32_16x16x32_bf16 v[14:17], v[154:157], v[212:215], v[14:17]
	v_mfma_f32_16x16x32_bf16 v[10:13], v[164:167], v[212:215], v[10:13]
	v_mfma_f32_16x16x32_bf16 v[62:65], v[158:161], v[192:195], v[62:65]
	v_mfma_f32_16x16x32_bf16 v[58:61], v[168:171], v[192:195], v[58:61]
	v_mfma_f32_16x16x32_bf16 v[46:49], v[158:161], v[200:203], v[46:49]
	v_mfma_f32_16x16x32_bf16 v[42:45], v[168:171], v[200:203], v[42:45]
	v_mfma_f32_16x16x32_bf16 v[30:33], v[158:161], v[208:211], v[30:33]
	v_mfma_f32_16x16x32_bf16 v[26:29], v[168:171], v[208:211], v[26:29]
	v_mfma_f32_16x16x32_bf16 v[14:17], v[158:161], v[216:219], v[14:17]
	v_mfma_f32_16x16x32_bf16 v[10:13], v[168:171], v[216:219], v[10:13]
	v_mfma_f32_16x16x32_bf16 v[54:57], v[172:175], v[188:191], v[54:57]
	v_mfma_f32_16x16x32_bf16 v[50:53], v[180:183], v[188:191], v[50:53]
	v_mfma_f32_16x16x32_bf16 v[38:41], v[172:175], v[196:199], v[38:41]
	v_mfma_f32_16x16x32_bf16 v[34:37], v[180:183], v[196:199], v[34:37]
	v_mfma_f32_16x16x32_bf16 v[22:25], v[172:175], v[204:207], v[22:25]
	v_mfma_f32_16x16x32_bf16 v[18:21], v[180:183], v[204:207], v[18:21]
	v_mfma_f32_16x16x32_bf16 v[6:9], v[172:175], v[212:215], v[6:9]
	v_mfma_f32_16x16x32_bf16 v[2:5], v[180:183], v[212:215], v[2:5]
	v_mfma_f32_16x16x32_bf16 v[54:57], v[176:179], v[192:195], v[54:57]
	v_mfma_f32_16x16x32_bf16 v[50:53], v[184:187], v[192:195], v[50:53]
	v_mfma_f32_16x16x32_bf16 v[38:41], v[176:179], v[200:203], v[38:41]
	v_mfma_f32_16x16x32_bf16 v[34:37], v[184:187], v[200:203], v[34:37]
	v_mfma_f32_16x16x32_bf16 v[22:25], v[176:179], v[208:211], v[22:25]
	v_mfma_f32_16x16x32_bf16 v[18:21], v[184:187], v[208:211], v[18:21]
	v_mfma_f32_16x16x32_bf16 v[6:9], v[176:179], v[216:219], v[6:9]
	v_mfma_f32_16x16x32_bf16 v[2:5], v[184:187], v[216:219], v[2:5]
	s_barrier
	s_add_i32 s53, s53, 2
	s_add_u32 s34, s34, 0x100
	s_addc_u32 s35, s35, 0
	s_add_u32 s23, s23, 0x100
	s_addc_u32 s25, s25, 0
	s_cmp_gt_u32 s53, 29
	s_cbranch_scc0 .LBB0_285
	s_and_b64 vcc, exec, s[12:13]
	s_cbranch_vccz .LBB0_288
	s_barrier

.LBB0_356:
	ds_read_b128 v[134:137], v213
	ds_read_b128 v[138:141], v213 offset:1024
	ds_read_b128 v[142:145], v213 offset:2048
	ds_read_b128 v[178:181], v213 offset:3072
	ds_read_b128 v[182:185], v214
	ds_read_b128 v[186:189], v214 offset:1024
	ds_read_b128 v[190:193], v214 offset:2048
	ds_read_b128 v[194:197], v214 offset:3072
	s_add_u32 s36, s34, 0x100
	s_addc_u32 s37, s35, 0
	s_add_u32 s16, s3, s34
	s_addc_u32 s17, s14, s35
	s_cmpk_eq_i32 s15, 0x54
	s_cselect_b32 s41, s27, s17
	s_cselect_b32 s17, 0, s36
	s_cselect_b32 s40, s26, s16
	s_cselect_b32 s16, 0, s37
	s_add_u32 s38, s8, s17
	s_addc_u32 s39, s9, s16
	s_mov_b32 m0, s63
	v_lshl_add_u64 v[244:245], v[130:131], 0, s[34:35]
	ds_read_b128 v[198:201], v215
	ds_read_b128 v[202:205], v215 offset:1024
	ds_read_b128 v[206:209], v215 offset:2048
	ds_read_b128 v[224:227], v215 offset:3072
	ds_read_b128 v[228:231], v215 offset:4096
	ds_read_b128 v[232:235], v215 offset:5120
	ds_read_b128 v[236:239], v215 offset:6144
	ds_read_b128 v[240:243], v215 offset:7168
	global_load_lds_dwordx4 v[244:245], off
	v_lshl_add_u64 v[244:245], v[132:133], 0, s[34:35]
	s_mov_b32 m0, s64
	s_nop 0
	global_load_lds_dwordx4 v[244:245], off
	s_waitcnt vmcnt(8)
	s_waitcnt lgkmcnt(0)
	s_waitcnt lgkmcnt(0)
	v_mfma_f32_16x16x32_bf16 v[86:89], v[134:137], v[198:201], v[86:89]
	v_mfma_f32_16x16x32_bf16 v[82:85], v[142:145], v[198:201], v[82:85]
	v_mfma_f32_16x16x32_bf16 v[110:113], v[134:137], v[206:209], v[110:113]
	v_mfma_f32_16x16x32_bf16 v[106:109], v[142:145], v[206:209], v[106:109]
	s_barrier
	v_mfma_f32_16x16x32_bf16 v[118:121], v[134:137], v[228:231], v[118:121]
	v_mfma_f32_16x16x32_bf16 v[114:117], v[142:145], v[228:231], v[114:117]
	v_mfma_f32_16x16x32_bf16 v[126:129], v[134:137], v[236:239], v[126:129]
	v_mfma_f32_16x16x32_bf16 v[122:125], v[142:145], v[236:239], v[122:125]
	v_mfma_f32_16x16x32_bf16 v[86:89], v[138:141], v[202:205], v[86:89]
	v_mfma_f32_16x16x32_bf16 v[82:85], v[178:181], v[202:205], v[82:85]
	v_mfma_f32_16x16x32_bf16 v[110:113], v[138:141], v[224:227], v[110:113]
	v_mfma_f32_16x16x32_bf16 v[106:109], v[178:181], v[224:227], v[106:109]
	v_mfma_f32_16x16x32_bf16 v[118:121], v[138:141], v[232:235], v[118:121]
	v_mfma_f32_16x16x32_bf16 v[114:117], v[178:181], v[232:235], v[114:117]
	v_mfma_f32_16x16x32_bf16 v[126:129], v[138:141], v[240:243], v[126:129]
	v_mfma_f32_16x16x32_bf16 v[122:125], v[178:181], v[240:243], v[122:125]
	v_mfma_f32_16x16x32_bf16 v[26:29], v[182:185], v[198:201], v[26:29]
	v_mfma_f32_16x16x32_bf16 v[30:33], v[190:193], v[198:201], v[30:33]
	v_mfma_f32_16x16x32_bf16 v[42:45], v[182:185], v[206:209], v[42:45]
	v_mfma_f32_16x16x32_bf16 v[50:53], v[190:193], v[206:209], v[50:53]
	v_mfma_f32_16x16x32_bf16 v[66:69], v[182:185], v[228:231], v[66:69]
	v_mfma_f32_16x16x32_bf16 v[70:73], v[190:193], v[228:231], v[70:73]
	v_mfma_f32_16x16x32_bf16 v[90:93], v[182:185], v[236:239], v[90:93]
	v_mfma_f32_16x16x32_bf16 v[94:97], v[190:193], v[236:239], v[94:97]
	v_mfma_f32_16x16x32_bf16 v[26:29], v[186:189], v[202:205], v[26:29]
	v_mfma_f32_16x16x32_bf16 v[30:33], v[194:197], v[202:205], v[30:33]
	v_mfma_f32_16x16x32_bf16 v[42:45], v[186:189], v[224:227], v[42:45]
	v_mfma_f32_16x16x32_bf16 v[50:53], v[194:197], v[224:227], v[50:53]
	v_mfma_f32_16x16x32_bf16 v[66:69], v[186:189], v[232:235], v[66:69]
	v_mfma_f32_16x16x32_bf16 v[70:73], v[194:197], v[232:235], v[70:73]
	v_mfma_f32_16x16x32_bf16 v[90:93], v[186:189], v[240:243], v[90:93]
	v_mfma_f32_16x16x32_bf16 v[94:97], v[194:197], v[240:243], v[94:97]
	s_barrier
	s_mov_b32 m0, s65
	v_lshl_add_u64 v[244:245], s[38:39], 0, v[150:151]
	s_add_u32 s16, s38, 0x160000
	ds_read_b128 v[198:201], v215 offset:16384
	ds_read_b128 v[202:205], v215 offset:17408
	ds_read_b128 v[206:209], v215 offset:18432
	ds_read_b128 v[224:227], v215 offset:19456
	ds_read_b128 v[228:231], v215 offset:20480
	ds_read_b128 v[232:235], v215 offset:21504
	ds_read_b128 v[236:239], v215 offset:22528
	ds_read_b128 v[240:243], v215 offset:23552
	global_load_lds_dwordx4 v[244:245], off
	v_lshl_add_u64 v[246:247], s[38:39], 0, v[146:147]
	s_mov_b32 m0, s66
	s_addc_u32 s17, s39, 0
	global_load_lds_dwordx4 v[246:247], off
	v_lshl_add_u64 v[248:249], s[16:17], 0, v[150:151]
	s_mov_b32 m0, s67
	v_lshl_add_u64 v[250:251], s[40:41], 0, v[148:149]
	global_load_lds_dwordx4 v[248:249], off
	v_lshl_add_u64 v[248:249], s[16:17], 0, v[146:147]
	s_mov_b32 m0, s68
	s_nop 0
	global_load_lds_dwordx4 v[248:249], off
	v_lshl_add_u64 v[248:249], s[40:41], 0, v[152:153]
	s_mov_b32 m0, s51
	s_nop 0
	global_load_lds_dwordx4 v[248:249], off
	s_mov_b32 m0, s52
	s_nop 0
	global_load_lds_dwordx4 v[250:251], off
	s_waitcnt vmcnt(8)
	s_waitcnt lgkmcnt(0)
	s_waitcnt lgkmcnt(0)
	v_mfma_f32_16x16x32_bf16 v[102:105], v[134:137], v[198:201], v[102:105]
	v_mfma_f32_16x16x32_bf16 v[98:101], v[142:145], v[198:201], v[98:101]
	v_mfma_f32_16x16x32_bf16 v[62:65], v[134:137], v[206:209], v[62:65]
	v_mfma_f32_16x16x32_bf16 v[58:61], v[142:145], v[206:209], v[58:61]
	s_barrier
	v_mfma_f32_16x16x32_bf16 v[38:41], v[134:137], v[228:231], v[38:41]
	v_mfma_f32_16x16x32_bf16 v[34:37], v[142:145], v[228:231], v[34:37]
	v_mfma_f32_16x16x32_bf16 v[14:17], v[134:137], v[236:239], v[14:17]
	v_mfma_f32_16x16x32_bf16 v[10:13], v[142:145], v[236:239], v[10:13]
	v_mfma_f32_16x16x32_bf16 v[102:105], v[138:141], v[202:205], v[102:105]
	v_mfma_f32_16x16x32_bf16 v[98:101], v[178:181], v[202:205], v[98:101]
	v_mfma_f32_16x16x32_bf16 v[62:65], v[138:141], v[224:227], v[62:65]
	v_mfma_f32_16x16x32_bf16 v[58:61], v[178:181], v[224:227], v[58:61]
	v_mfma_f32_16x16x32_bf16 v[38:41], v[138:141], v[232:235], v[38:41]
	v_mfma_f32_16x16x32_bf16 v[34:37], v[178:181], v[232:235], v[34:37]
	v_mfma_f32_16x16x32_bf16 v[14:17], v[138:141], v[240:243], v[14:17]
	v_mfma_f32_16x16x32_bf16 v[10:13], v[178:181], v[240:243], v[10:13]
	v_mfma_f32_16x16x32_bf16 v[78:81], v[182:185], v[198:201], v[78:81]
	v_mfma_f32_16x16x32_bf16 v[74:77], v[190:193], v[198:201], v[74:77]
	v_mfma_f32_16x16x32_bf16 v[54:57], v[182:185], v[206:209], v[54:57]
	v_mfma_f32_16x16x32_bf16 v[46:49], v[190:193], v[206:209], v[46:49]
	v_mfma_f32_16x16x32_bf16 v[22:25], v[182:185], v[228:231], v[22:25]
	v_mfma_f32_16x16x32_bf16 v[18:21], v[190:193], v[228:231], v[18:21]
	v_mfma_f32_16x16x32_bf16 v[6:9], v[182:185], v[236:239], v[6:9]
	v_mfma_f32_16x16x32_bf16 v[2:5], v[190:193], v[236:239], v[2:5]
	v_mfma_f32_16x16x32_bf16 v[78:81], v[186:189], v[202:205], v[78:81]
	v_mfma_f32_16x16x32_bf16 v[74:77], v[194:197], v[202:205], v[74:77]
	v_mfma_f32_16x16x32_bf16 v[54:57], v[186:189], v[224:227], v[54:57]
	v_mfma_f32_16x16x32_bf16 v[46:49], v[194:197], v[224:227], v[46:49]
	v_mfma_f32_16x16x32_bf16 v[22:25], v[186:189], v[232:235], v[22:25]
	v_mfma_f32_16x16x32_bf16 v[18:21], v[194:197], v[232:235], v[18:21]
	v_mfma_f32_16x16x32_bf16 v[6:9], v[186:189], v[240:243], v[6:9]
	v_mfma_f32_16x16x32_bf16 v[2:5], v[194:197], v[240:243], v[2:5]
	s_barrier
	ds_read_b128 v[134:137], v219
	ds_read_b128 v[138:141], v219 offset:1024
	ds_read_b128 v[142:145], v219 offset:2048
	ds_read_b128 v[178:181], v219 offset:3072
	ds_read_b128 v[182:185], v220
	ds_read_b128 v[186:189], v220 offset:1024
	ds_read_b128 v[190:193], v220 offset:2048
	ds_read_b128 v[194:197], v220 offset:3072
	s_add_u32 s16, s40, 0x160000
	s_addc_u32 s17, s41, 0
	s_mov_b32 m0, s53
	v_lshl_add_u64 v[252:253], s[16:17], 0, v[152:153]
	ds_read_b128 v[198:201], v215 offset:32768
	ds_read_b128 v[202:205], v215 offset:33792
	ds_read_b128 v[206:209], v215 offset:34816
	ds_read_b128 v[224:227], v215 offset:35840
	ds_read_b128 v[228:231], v215 offset:36864
	ds_read_b128 v[232:235], v215 offset:37888
	ds_read_b128 v[236:239], v215 offset:38912
	ds_read_b128 v[240:243], v215 offset:39936
	global_load_lds_dwordx4 v[252:253], off
	v_lshl_add_u64 v[252:253], s[16:17], 0, v[148:149]
	s_mov_b32 m0, s54
	s_nop 0
	global_load_lds_dwordx4 v[252:253], off
	s_waitcnt vmcnt(8)
	s_waitcnt lgkmcnt(0)
	s_waitcnt lgkmcnt(0)
	v_mfma_f32_16x16x32_bf16 v[86:89], v[134:137], v[198:201], v[86:89]
	v_mfma_f32_16x16x32_bf16 v[82:85], v[142:145], v[198:201], v[82:85]
	v_mfma_f32_16x16x32_bf16 v[110:113], v[134:137], v[206:209], v[110:113]
	v_mfma_f32_16x16x32_bf16 v[106:109], v[142:145], v[206:209], v[106:109]
	s_barrier
	v_mfma_f32_16x16x32_bf16 v[118:121], v[134:137], v[228:231], v[118:121]
	v_mfma_f32_16x16x32_bf16 v[114:117], v[142:145], v[228:231], v[114:117]
	v_mfma_f32_16x16x32_bf16 v[126:129], v[134:137], v[236:239], v[126:129]
	v_mfma_f32_16x16x32_bf16 v[122:125], v[142:145], v[236:239], v[122:125]
	v_mfma_f32_16x16x32_bf16 v[86:89], v[138:141], v[202:205], v[86:89]
	v_mfma_f32_16x16x32_bf16 v[82:85], v[178:181], v[202:205], v[82:85]
	v_mfma_f32_16x16x32_bf16 v[110:113], v[138:141], v[224:227], v[110:113]
	v_mfma_f32_16x16x32_bf16 v[106:109], v[178:181], v[224:227], v[106:109]
	v_mfma_f32_16x16x32_bf16 v[118:121], v[138:141], v[232:235], v[118:121]
	v_mfma_f32_16x16x32_bf16 v[114:117], v[178:181], v[232:235], v[114:117]
	v_mfma_f32_16x16x32_bf16 v[126:129], v[138:141], v[240:243], v[126:129]
	v_mfma_f32_16x16x32_bf16 v[122:125], v[178:181], v[240:243], v[122:125]
	v_mfma_f32_16x16x32_bf16 v[26:29], v[182:185], v[198:201], v[26:29]
	v_mfma_f32_16x16x32_bf16 v[30:33], v[190:193], v[198:201], v[30:33]
	v_mfma_f32_16x16x32_bf16 v[42:45], v[182:185], v[206:209], v[42:45]
	v_mfma_f32_16x16x32_bf16 v[50:53], v[190:193], v[206:209], v[50:53]
	v_mfma_f32_16x16x32_bf16 v[66:69], v[182:185], v[228:231], v[66:69]
	v_mfma_f32_16x16x32_bf16 v[70:73], v[190:193], v[228:231], v[70:73]
	v_mfma_f32_16x16x32_bf16 v[90:93], v[182:185], v[236:239], v[90:93]
	v_mfma_f32_16x16x32_bf16 v[94:97], v[190:193], v[236:239], v[94:97]
	v_mfma_f32_16x16x32_bf16 v[26:29], v[186:189], v[202:205], v[26:29]
	v_mfma_f32_16x16x32_bf16 v[30:33], v[194:197], v[202:205], v[30:33]
	v_mfma_f32_16x16x32_bf16 v[42:45], v[186:189], v[224:227], v[42:45]
	v_mfma_f32_16x16x32_bf16 v[50:53], v[194:197], v[224:227], v[50:53]
	v_mfma_f32_16x16x32_bf16 v[66:69], v[186:189], v[232:235], v[66:69]
	v_mfma_f32_16x16x32_bf16 v[70:73], v[194:197], v[232:235], v[70:73]
	v_mfma_f32_16x16x32_bf16 v[90:93], v[186:189], v[240:243], v[90:93]
	v_mfma_f32_16x16x32_bf16 v[94:97], v[194:197], v[240:243], v[94:97]
	s_barrier
	s_mov_b32 m0, s69
	v_lshl_add_u64 v[244:245], v[244:245], 0, s[22:23]
	s_add_u32 s16, s38, 0x160080
	ds_read_b128 v[198:201], v215 offset:49152
	ds_read_b128 v[202:205], v215 offset:50176
	ds_read_b128 v[206:209], v215 offset:51200
	ds_read_b128 v[224:227], v215 offset:52224
	ds_read_b128 v[228:231], v215 offset:53248
	ds_read_b128 v[232:235], v215 offset:54272
	ds_read_b128 v[236:239], v215 offset:55296
	ds_read_b128 v[240:243], v215 offset:56320
	global_load_lds_dwordx4 v[244:245], off
	v_lshl_add_u64 v[244:245], v[246:247], 0, s[22:23]
	s_mov_b32 m0, s73
	s_addc_u32 s17, s39, 0
	global_load_lds_dwordx4 v[244:245], off
	v_lshl_add_u64 v[244:245], s[16:17], 0, v[150:151]
	s_mov_b32 m0, s74
	s_nop 0
	global_load_lds_dwordx4 v[244:245], off
	v_lshl_add_u64 v[244:245], s[16:17], 0, v[146:147]
	s_mov_b32 m0, s75
	s_nop 0
	global_load_lds_dwordx4 v[244:245], off
	v_lshl_add_u64 v[244:245], v[248:249], 0, s[22:23]
	s_mov_b32 m0, s60
	s_nop 0
	global_load_lds_dwordx4 v[244:245], off
	v_lshl_add_u64 v[244:245], v[250:251], 0, s[22:23]
	s_mov_b32 m0, s61
	s_nop 0
	global_load_lds_dwordx4 v[244:245], off
	s_waitcnt vmcnt(8)
	s_waitcnt lgkmcnt(0)
	s_waitcnt lgkmcnt(0)
	v_mfma_f32_16x16x32_bf16 v[102:105], v[134:137], v[198:201], v[102:105]
	v_mfma_f32_16x16x32_bf16 v[98:101], v[142:145], v[198:201], v[98:101]
	v_mfma_f32_16x16x32_bf16 v[62:65], v[134:137], v[206:209], v[62:65]
	v_mfma_f32_16x16x32_bf16 v[58:61], v[142:145], v[206:209], v[58:61]
	s_barrier
	v_mfma_f32_16x16x32_bf16 v[38:41], v[134:137], v[228:231], v[38:41]
	v_mfma_f32_16x16x32_bf16 v[34:37], v[142:145], v[228:231], v[34:37]
	v_mfma_f32_16x16x32_bf16 v[14:17], v[134:137], v[236:239], v[14:17]
	v_mfma_f32_16x16x32_bf16 v[10:13], v[142:145], v[236:239], v[10:13]
	v_mfma_f32_16x16x32_bf16 v[102:105], v[138:141], v[202:205], v[102:105]
	v_mfma_f32_16x16x32_bf16 v[98:101], v[178:181], v[202:205], v[98:101]
	v_mfma_f32_16x16x32_bf16 v[62:65], v[138:141], v[224:227], v[62:65]
	v_mfma_f32_16x16x32_bf16 v[58:61], v[178:181], v[224:227], v[58:61]
	v_mfma_f32_16x16x32_bf16 v[38:41], v[138:141], v[232:235], v[38:41]
	v_mfma_f32_16x16x32_bf16 v[34:37], v[178:181], v[232:235], v[34:37]
	v_mfma_f32_16x16x32_bf16 v[14:17], v[138:141], v[240:243], v[14:17]
	v_mfma_f32_16x16x32_bf16 v[10:13], v[178:181], v[240:243], v[10:13]
	v_mfma_f32_16x16x32_bf16 v[78:81], v[182:185], v[198:201], v[78:81]
	v_mfma_f32_16x16x32_bf16 v[74:77], v[190:193], v[198:201], v[74:77]
	v_mfma_f32_16x16x32_bf16 v[54:57], v[182:185], v[206:209], v[54:57]
	v_mfma_f32_16x16x32_bf16 v[46:49], v[190:193], v[206:209], v[46:49]
	v_mfma_f32_16x16x32_bf16 v[22:25], v[182:185], v[228:231], v[22:25]
	v_mfma_f32_16x16x32_bf16 v[18:21], v[190:193], v[228:231], v[18:21]
	v_mfma_f32_16x16x32_bf16 v[6:9], v[182:185], v[236:239], v[6:9]
	v_mfma_f32_16x16x32_bf16 v[2:5], v[190:193], v[236:239], v[2:5]
	v_mfma_f32_16x16x32_bf16 v[78:81], v[186:189], v[202:205], v[78:81]
	v_mfma_f32_16x16x32_bf16 v[74:77], v[194:197], v[202:205], v[74:77]
	v_mfma_f32_16x16x32_bf16 v[54:57], v[186:189], v[224:227], v[54:57]
	v_mfma_f32_16x16x32_bf16 v[46:49], v[194:197], v[224:227], v[46:49]
	v_mfma_f32_16x16x32_bf16 v[22:25], v[186:189], v[232:235], v[22:25]
	v_mfma_f32_16x16x32_bf16 v[18:21], v[194:197], v[232:235], v[18:21]
	v_mfma_f32_16x16x32_bf16 v[6:9], v[186:189], v[240:243], v[6:9]
	v_mfma_f32_16x16x32_bf16 v[2:5], v[194:197], v[240:243], v[2:5]
	s_barrier
	s_add_i32 s15, s15, 2
	s_cmpk_gt_u32 s15, 0x55
	s_mov_b64 s[34:35], s[36:37]
	s_cbranch_scc0 .LBB0_356
	s_and_b64 vcc, exec, s[24:25]
	s_cbranch_vccz .LBB0_359
	s_barrier

.LBB0_466:
	ds_read_b128 v[130:133], v170
	ds_read_b128 v[134:137], v170 offset:1024
	ds_read_b128 v[164:167], v170 offset:2048
	ds_read_b128 v[174:177], v170 offset:3072
	ds_read_b128 v[178:181], v171
	ds_read_b128 v[182:185], v171 offset:1024
	ds_read_b128 v[186:189], v171 offset:2048
	ds_read_b128 v[190:193], v171 offset:3072
	s_add_u32 s19, s42, 0xfff80080
	s_addc_u32 s20, s43, -1
	s_cmp_eq_u32 s18, 28
	s_cselect_b32 s47, s3, s20
	s_cselect_b32 s46, s7, s19
	s_cselect_b32 s45, s14, s17
	s_cselect_b32 s44, s15, s16
	v_lshl_add_u64 v[168:169], s[42:43], 0, v[154:155]
	s_add_i32 m0, s41, 0xc000
	ds_read_b128 v[194:197], v172
	ds_read_b128 v[198:201], v172 offset:1024
	ds_read_b128 v[202:205], v172 offset:2048
	ds_read_b128 v[206:209], v172 offset:3072
	ds_read_b128 v[210:213], v172 offset:4096
	ds_read_b128 v[214:217], v172 offset:5120
	ds_read_b128 v[218:221], v172 offset:6144
	ds_read_b128 v[222:225], v172 offset:7168
	global_load_lds_dwordx4 v[168:169], off
	v_lshl_add_u64 v[168:169], s[42:43], 0, v[156:157]
	s_add_i32 m0, s41, 0xe000
	s_nop 0
	global_load_lds_dwordx4 v[168:169], off
	s_waitcnt vmcnt(8)
	s_waitcnt lgkmcnt(0)
	s_waitcnt lgkmcnt(0)
	v_mfma_f32_16x16x32_bf16 v[126:129], v[130:133], v[194:197], v[126:129]
	v_mfma_f32_16x16x32_bf16 v[122:125], v[164:167], v[194:197], v[122:125]
	v_mfma_f32_16x16x32_bf16 v[110:113], v[130:133], v[202:205], v[110:113]
	v_mfma_f32_16x16x32_bf16 v[106:109], v[164:167], v[202:205], v[106:109]
	s_barrier
	v_mfma_f32_16x16x32_bf16 v[94:97], v[130:133], v[210:213], v[94:97]
	v_mfma_f32_16x16x32_bf16 v[90:93], v[164:167], v[210:213], v[90:93]
	v_mfma_f32_16x16x32_bf16 v[78:81], v[130:133], v[218:221], v[78:81]
	v_mfma_f32_16x16x32_bf16 v[74:77], v[164:167], v[218:221], v[74:77]
	v_mfma_f32_16x16x32_bf16 v[126:129], v[134:137], v[198:201], v[126:129]
	v_mfma_f32_16x16x32_bf16 v[122:125], v[174:177], v[198:201], v[122:125]
	v_mfma_f32_16x16x32_bf16 v[110:113], v[134:137], v[206:209], v[110:113]
	v_mfma_f32_16x16x32_bf16 v[106:109], v[174:177], v[206:209], v[106:109]
	v_mfma_f32_16x16x32_bf16 v[94:97], v[134:137], v[214:217], v[94:97]
	v_mfma_f32_16x16x32_bf16 v[90:93], v[174:177], v[214:217], v[90:93]
	v_mfma_f32_16x16x32_bf16 v[78:81], v[134:137], v[222:225], v[78:81]
	v_mfma_f32_16x16x32_bf16 v[74:77], v[174:177], v[222:225], v[74:77]
	v_mfma_f32_16x16x32_bf16 v[118:121], v[178:181], v[194:197], v[118:121]
	v_mfma_f32_16x16x32_bf16 v[114:117], v[186:189], v[194:197], v[114:117]
	v_mfma_f32_16x16x32_bf16 v[102:105], v[178:181], v[202:205], v[102:105]
	v_mfma_f32_16x16x32_bf16 v[98:101], v[186:189], v[202:205], v[98:101]
	v_mfma_f32_16x16x32_bf16 v[86:89], v[178:181], v[210:213], v[86:89]
	v_mfma_f32_16x16x32_bf16 v[82:85], v[186:189], v[210:213], v[82:85]
	v_mfma_f32_16x16x32_bf16 v[70:73], v[178:181], v[218:221], v[70:73]
	v_mfma_f32_16x16x32_bf16 v[66:69], v[186:189], v[218:221], v[66:69]
	v_mfma_f32_16x16x32_bf16 v[118:121], v[182:185], v[198:201], v[118:121]
	v_mfma_f32_16x16x32_bf16 v[114:117], v[190:193], v[198:201], v[114:117]
	v_mfma_f32_16x16x32_bf16 v[102:105], v[182:185], v[206:209], v[102:105]
	v_mfma_f32_16x16x32_bf16 v[98:101], v[190:193], v[206:209], v[98:101]
	v_mfma_f32_16x16x32_bf16 v[86:89], v[182:185], v[214:217], v[86:89]
	v_mfma_f32_16x16x32_bf16 v[82:85], v[190:193], v[214:217], v[82:85]
	v_mfma_f32_16x16x32_bf16 v[70:73], v[182:185], v[222:225], v[70:73]
	v_mfma_f32_16x16x32_bf16 v[66:69], v[190:193], v[222:225], v[66:69]
	s_barrier
	s_add_i32 s19, s75, s52
	v_lshl_add_u64 v[168:169], s[44:45], 0, v[140:141]
	s_mov_b32 m0, s19
	ds_read_b128 v[194:197], v172 offset:16384
	ds_read_b128 v[198:201], v172 offset:17408
	ds_read_b128 v[202:205], v172 offset:18432
	ds_read_b128 v[206:209], v172 offset:19456
	ds_read_b128 v[210:213], v172 offset:20480
	ds_read_b128 v[214:217], v172 offset:21504
	ds_read_b128 v[218:221], v172 offset:22528
	ds_read_b128 v[222:225], v172 offset:23552
	global_load_lds_dwordx4 v[168:169], off
	s_add_i32 m0, s19, 0x2000
	s_add_u32 s20, s44, 0x80000
	v_lshl_add_u64 v[226:227], s[44:45], 0, v[144:145]
	s_addc_u32 s21, s45, 0
	s_add_i32 s19, s76, s52
	global_load_lds_dwordx4 v[226:227], off
	v_lshl_add_u64 v[228:229], s[20:21], 0, v[140:141]
	s_mov_b32 m0, s19
	v_lshl_add_u64 v[230:231], s[46:47], 0, v[142:143]
	global_load_lds_dwordx4 v[228:229], off
	v_lshl_add_u64 v[228:229], s[20:21], 0, v[144:145]
	s_add_i32 m0, s19, 0x2000
	s_nop 0
	global_load_lds_dwordx4 v[228:229], off
	v_lshl_add_u64 v[228:229], s[46:47], 0, v[138:139]
	s_mov_b32 m0, s41
	s_nop 0
	global_load_lds_dwordx4 v[228:229], off
	s_mov_b32 m0, s53
	s_nop 0
	global_load_lds_dwordx4 v[230:231], off
	s_waitcnt vmcnt(8)
	s_waitcnt lgkmcnt(0)
	s_waitcnt lgkmcnt(0)
	v_mfma_f32_16x16x32_bf16 v[62:65], v[130:133], v[194:197], v[62:65]
	v_mfma_f32_16x16x32_bf16 v[58:61], v[164:167], v[194:197], v[58:61]
	v_mfma_f32_16x16x32_bf16 v[46:49], v[130:133], v[202:205], v[46:49]
	v_mfma_f32_16x16x32_bf16 v[42:45], v[164:167], v[202:205], v[42:45]
	s_barrier
	v_mfma_f32_16x16x32_bf16 v[30:33], v[130:133], v[210:213], v[30:33]
	v_mfma_f32_16x16x32_bf16 v[26:29], v[164:167], v[210:213], v[26:29]
	v_mfma_f32_16x16x32_bf16 v[14:17], v[130:133], v[218:221], v[14:17]
	v_mfma_f32_16x16x32_bf16 v[10:13], v[164:167], v[218:221], v[10:13]
	v_mfma_f32_16x16x32_bf16 v[62:65], v[134:137], v[198:201], v[62:65]
	v_mfma_f32_16x16x32_bf16 v[58:61], v[174:177], v[198:201], v[58:61]
	v_mfma_f32_16x16x32_bf16 v[46:49], v[134:137], v[206:209], v[46:49]
	v_mfma_f32_16x16x32_bf16 v[42:45], v[174:177], v[206:209], v[42:45]
	v_mfma_f32_16x16x32_bf16 v[30:33], v[134:137], v[214:217], v[30:33]
	v_mfma_f32_16x16x32_bf16 v[26:29], v[174:177], v[214:217], v[26:29]
	v_mfma_f32_16x16x32_bf16 v[14:17], v[134:137], v[222:225], v[14:17]
	v_mfma_f32_16x16x32_bf16 v[10:13], v[174:177], v[222:225], v[10:13]
	v_mfma_f32_16x16x32_bf16 v[54:57], v[178:181], v[194:197], v[54:57]
	v_mfma_f32_16x16x32_bf16 v[50:53], v[186:189], v[194:197], v[50:53]
	v_mfma_f32_16x16x32_bf16 v[38:41], v[178:181], v[202:205], v[38:41]
	v_mfma_f32_16x16x32_bf16 v[34:37], v[186:189], v[202:205], v[34:37]
	v_mfma_f32_16x16x32_bf16 v[22:25], v[178:181], v[210:213], v[22:25]
	v_mfma_f32_16x16x32_bf16 v[18:21], v[186:189], v[210:213], v[18:21]
	v_mfma_f32_16x16x32_bf16 v[6:9], v[178:181], v[218:221], v[6:9]
	v_mfma_f32_16x16x32_bf16 v[2:5], v[186:189], v[218:221], v[2:5]
	v_mfma_f32_16x16x32_bf16 v[54:57], v[182:185], v[198:201], v[54:57]
	v_mfma_f32_16x16x32_bf16 v[50:53], v[190:193], v[198:201], v[50:53]
	v_mfma_f32_16x16x32_bf16 v[38:41], v[182:185], v[206:209], v[38:41]
	v_mfma_f32_16x16x32_bf16 v[34:37], v[190:193], v[206:209], v[34:37]
	v_mfma_f32_16x16x32_bf16 v[22:25], v[182:185], v[214:217], v[22:25]
	v_mfma_f32_16x16x32_bf16 v[18:21], v[190:193], v[214:217], v[18:21]
	v_mfma_f32_16x16x32_bf16 v[6:9], v[182:185], v[222:225], v[6:9]
	v_mfma_f32_16x16x32_bf16 v[2:5], v[190:193], v[222:225], v[2:5]
	s_barrier
	s_add_i32 s19, 0, 0x18000
	v_add_u32_e32 v146, s19, v163
	s_add_i32 s31, 0, 0x1c000
	ds_read_b128 v[130:133], v146
	ds_read_b128 v[134:137], v146 offset:1024
	ds_read_b128 v[164:167], v146 offset:2048
	ds_read_b128 v[174:177], v146 offset:3072
	v_add_u32_e32 v146, s31, v163
	ds_read_b128 v[178:181], v146
	ds_read_b128 v[182:185], v146 offset:1024
	ds_read_b128 v[186:189], v146 offset:2048
	ds_read_b128 v[190:193], v146 offset:3072
	s_add_u32 s20, s46, 0x80000
	s_addc_u32 s21, s47, 0
	s_mov_b32 m0, s54
	v_lshl_add_u64 v[232:233], s[20:21], 0, v[138:139]
	ds_read_b128 v[194:197], v172 offset:32768
	ds_read_b128 v[198:201], v172 offset:33792
	ds_read_b128 v[202:205], v172 offset:34816
	ds_read_b128 v[206:209], v172 offset:35840
	ds_read_b128 v[210:213], v172 offset:36864
	ds_read_b128 v[214:217], v172 offset:37888
	ds_read_b128 v[218:221], v172 offset:38912
	ds_read_b128 v[222:225], v172 offset:39936
	global_load_lds_dwordx4 v[232:233], off
	v_lshl_add_u64 v[232:233], s[20:21], 0, v[142:143]
	s_mov_b32 m0, s55
	s_nop 0
	global_load_lds_dwordx4 v[232:233], off
	s_waitcnt vmcnt(8)
	s_waitcnt lgkmcnt(0)
	s_waitcnt lgkmcnt(0)
	v_mfma_f32_16x16x32_bf16 v[126:129], v[130:133], v[194:197], v[126:129]
	v_mfma_f32_16x16x32_bf16 v[122:125], v[164:167], v[194:197], v[122:125]
	v_mfma_f32_16x16x32_bf16 v[110:113], v[130:133], v[202:205], v[110:113]
	v_mfma_f32_16x16x32_bf16 v[106:109], v[164:167], v[202:205], v[106:109]
	s_barrier
	v_mfma_f32_16x16x32_bf16 v[94:97], v[130:133], v[210:213], v[94:97]
	v_mfma_f32_16x16x32_bf16 v[90:93], v[164:167], v[210:213], v[90:93]
	v_mfma_f32_16x16x32_bf16 v[78:81], v[130:133], v[218:221], v[78:81]
	v_mfma_f32_16x16x32_bf16 v[74:77], v[164:167], v[218:221], v[74:77]
	v_mfma_f32_16x16x32_bf16 v[126:129], v[134:137], v[198:201], v[126:129]
	v_mfma_f32_16x16x32_bf16 v[122:125], v[174:177], v[198:201], v[122:125]
	v_mfma_f32_16x16x32_bf16 v[110:113], v[134:137], v[206:209], v[110:113]
	v_mfma_f32_16x16x32_bf16 v[106:109], v[174:177], v[206:209], v[106:109]
	v_mfma_f32_16x16x32_bf16 v[94:97], v[134:137], v[214:217], v[94:97]
	v_mfma_f32_16x16x32_bf16 v[90:93], v[174:177], v[214:217], v[90:93]
	v_mfma_f32_16x16x32_bf16 v[78:81], v[134:137], v[222:225], v[78:81]
	v_mfma_f32_16x16x32_bf16 v[74:77], v[174:177], v[222:225], v[74:77]
	v_mfma_f32_16x16x32_bf16 v[118:121], v[178:181], v[194:197], v[118:121]
	v_mfma_f32_16x16x32_bf16 v[114:117], v[186:189], v[194:197], v[114:117]
	v_mfma_f32_16x16x32_bf16 v[102:105], v[178:181], v[202:205], v[102:105]
	v_mfma_f32_16x16x32_bf16 v[98:101], v[186:189], v[202:205], v[98:101]
	v_mfma_f32_16x16x32_bf16 v[86:89], v[178:181], v[210:213], v[86:89]
	v_mfma_f32_16x16x32_bf16 v[82:85], v[186:189], v[210:213], v[82:85]
	v_mfma_f32_16x16x32_bf16 v[70:73], v[178:181], v[218:221], v[70:73]
	v_mfma_f32_16x16x32_bf16 v[66:69], v[186:189], v[218:221], v[66:69]
	v_mfma_f32_16x16x32_bf16 v[118:121], v[182:185], v[198:201], v[118:121]
	v_mfma_f32_16x16x32_bf16 v[114:117], v[190:193], v[198:201], v[114:117]
	v_mfma_f32_16x16x32_bf16 v[102:105], v[182:185], v[206:209], v[102:105]
	v_mfma_f32_16x16x32_bf16 v[98:101], v[190:193], v[206:209], v[98:101]
	v_mfma_f32_16x16x32_bf16 v[86:89], v[182:185], v[214:217], v[86:89]
	v_mfma_f32_16x16x32_bf16 v[82:85], v[190:193], v[214:217], v[82:85]
	v_mfma_f32_16x16x32_bf16 v[70:73], v[182:185], v[222:225], v[70:73]
	v_mfma_f32_16x16x32_bf16 v[66:69], v[190:193], v[222:225], v[66:69]
	s_barrier
	s_add_i32 s19, s19, s52
	v_lshl_add_u64 v[168:169], v[168:169], 0, s[10:11]
	s_mov_b32 m0, s19
	ds_read_b128 v[194:197], v172 offset:49152
	ds_read_b128 v[198:201], v172 offset:50176
	ds_read_b128 v[202:205], v172 offset:51200
	ds_read_b128 v[206:209], v172 offset:52224
	ds_read_b128 v[210:213], v172 offset:53248
	ds_read_b128 v[214:217], v172 offset:54272
	ds_read_b128 v[218:221], v172 offset:55296
	ds_read_b128 v[222:225], v172 offset:56320
	global_load_lds_dwordx4 v[168:169], off
	s_add_i32 m0, s19, 0x2000
	s_add_u32 s20, s44, 0x80080
	v_lshl_add_u64 v[168:169], v[226:227], 0, s[10:11]
	s_addc_u32 s21, s45, 0
	s_add_i32 s19, s31, s52
	global_load_lds_dwordx4 v[168:169], off
	v_lshl_add_u64 v[168:169], s[20:21], 0, v[140:141]
	s_mov_b32 m0, s19
	s_nop 0
	global_load_lds_dwordx4 v[168:169], off
	v_lshl_add_u64 v[168:169], s[20:21], 0, v[144:145]
	s_add_i32 m0, s19, 0x2000
	s_nop 0
	global_load_lds_dwordx4 v[168:169], off
	v_lshl_add_u64 v[168:169], v[228:229], 0, s[10:11]
	s_mov_b32 m0, s67
	s_nop 0
	global_load_lds_dwordx4 v[168:169], off
	v_lshl_add_u64 v[168:169], v[230:231], 0, s[10:11]
	s_mov_b32 m0, s68
	s_nop 0
	global_load_lds_dwordx4 v[168:169], off
	s_waitcnt vmcnt(8)
	s_waitcnt lgkmcnt(0)
	s_waitcnt lgkmcnt(0)
	v_mfma_f32_16x16x32_bf16 v[62:65], v[130:133], v[194:197], v[62:65]
	v_mfma_f32_16x16x32_bf16 v[58:61], v[164:167], v[194:197], v[58:61]
	v_mfma_f32_16x16x32_bf16 v[46:49], v[130:133], v[202:205], v[46:49]
	v_mfma_f32_16x16x32_bf16 v[42:45], v[164:167], v[202:205], v[42:45]
	s_barrier
	v_mfma_f32_16x16x32_bf16 v[30:33], v[130:133], v[210:213], v[30:33]
	v_mfma_f32_16x16x32_bf16 v[26:29], v[164:167], v[210:213], v[26:29]
	v_mfma_f32_16x16x32_bf16 v[14:17], v[130:133], v[218:221], v[14:17]
	v_mfma_f32_16x16x32_bf16 v[10:13], v[164:167], v[218:221], v[10:13]
	v_mfma_f32_16x16x32_bf16 v[62:65], v[134:137], v[198:201], v[62:65]
	v_mfma_f32_16x16x32_bf16 v[58:61], v[174:177], v[198:201], v[58:61]
	v_mfma_f32_16x16x32_bf16 v[46:49], v[134:137], v[206:209], v[46:49]
	v_mfma_f32_16x16x32_bf16 v[42:45], v[174:177], v[206:209], v[42:45]
	v_mfma_f32_16x16x32_bf16 v[30:33], v[134:137], v[214:217], v[30:33]
	v_mfma_f32_16x16x32_bf16 v[26:29], v[174:177], v[214:217], v[26:29]
	v_mfma_f32_16x16x32_bf16 v[14:17], v[134:137], v[222:225], v[14:17]
	v_mfma_f32_16x16x32_bf16 v[10:13], v[174:177], v[222:225], v[10:13]
	v_mfma_f32_16x16x32_bf16 v[54:57], v[178:181], v[194:197], v[54:57]
	v_mfma_f32_16x16x32_bf16 v[50:53], v[186:189], v[194:197], v[50:53]
	v_mfma_f32_16x16x32_bf16 v[38:41], v[178:181], v[202:205], v[38:41]
	v_mfma_f32_16x16x32_bf16 v[34:37], v[186:189], v[202:205], v[34:37]
	v_mfma_f32_16x16x32_bf16 v[22:25], v[178:181], v[210:213], v[22:25]
	v_mfma_f32_16x16x32_bf16 v[18:21], v[186:189], v[210:213], v[18:21]
	v_mfma_f32_16x16x32_bf16 v[6:9], v[178:181], v[218:221], v[6:9]
	v_mfma_f32_16x16x32_bf16 v[2:5], v[186:189], v[218:221], v[2:5]
	v_mfma_f32_16x16x32_bf16 v[54:57], v[182:185], v[198:201], v[54:57]
	v_mfma_f32_16x16x32_bf16 v[50:53], v[190:193], v[198:201], v[50:53]
	v_mfma_f32_16x16x32_bf16 v[38:41], v[182:185], v[206:209], v[38:41]
	v_mfma_f32_16x16x32_bf16 v[34:37], v[190:193], v[206:209], v[34:37]
	v_mfma_f32_16x16x32_bf16 v[22:25], v[182:185], v[214:217], v[22:25]
	v_mfma_f32_16x16x32_bf16 v[18:21], v[190:193], v[214:217], v[18:21]
	v_mfma_f32_16x16x32_bf16 v[6:9], v[182:185], v[222:225], v[6:9]
	v_mfma_f32_16x16x32_bf16 v[2:5], v[190:193], v[222:225], v[2:5]
	s_barrier
	s_add_i32 s18, s18, 2
	s_add_u32 s42, s42, 0x100
	s_addc_u32 s43, s43, 0
	s_add_u32 s16, s16, 0x100
	s_addc_u32 s17, s17, 0
	s_cmp_gt_u32 s18, 29
	s_cbranch_scc0 .LBB0_466
	s_and_b64 vcc, exec, s[12:13]
	s_cbranch_vccz .LBB0_469
	s_barrier

.LBB0_699:
	ds_read_b128 v[134:137], v214
	ds_read_b128 v[138:141], v214 offset:1024
	ds_read_b128 v[142:145], v214 offset:2048
	ds_read_b128 v[178:181], v214 offset:3072
	ds_read_b128 v[182:185], v215
	ds_read_b128 v[186:189], v215 offset:1024
	ds_read_b128 v[190:193], v215 offset:2048
	ds_read_b128 v[194:197], v215 offset:3072
	s_add_u32 s40, s38, 0x100
	s_addc_u32 s41, s39, 0
	s_add_u32 s18, s15, s38
	s_addc_u32 s19, s16, s39
	s_cmp_eq_u32 s17, 60
	s_cselect_b32 s45, s3, s19
	s_cselect_b32 s19, 0, s40
	s_cselect_b32 s44, s14, s18
	s_cselect_b32 s18, 0, s41
	s_add_u32 s42, s10, s19
	s_addc_u32 s43, s11, s18
	s_mov_b32 m0, s66
	v_lshl_add_u64 v[244:245], v[130:131], 0, s[38:39]
	ds_read_b128 v[198:201], v216
	ds_read_b128 v[202:205], v216 offset:1024
	ds_read_b128 v[206:209], v216 offset:2048
	ds_read_b128 v[224:227], v216 offset:3072
	ds_read_b128 v[228:231], v216 offset:4096
	ds_read_b128 v[232:235], v216 offset:5120
	ds_read_b128 v[236:239], v216 offset:6144
	ds_read_b128 v[240:243], v216 offset:7168
	global_load_lds_dwordx4 v[244:245], off
	v_lshl_add_u64 v[244:245], v[132:133], 0, s[38:39]
	s_mov_b32 m0, s67
	s_nop 0
	global_load_lds_dwordx4 v[244:245], off
	s_waitcnt vmcnt(8)
	s_waitcnt lgkmcnt(0)
	s_waitcnt lgkmcnt(0)
	v_mfma_f32_16x16x32_bf16 v[82:85], v[134:137], v[198:201], v[82:85]
	v_mfma_f32_16x16x32_bf16 v[78:81], v[142:145], v[198:201], v[78:81]
	v_mfma_f32_16x16x32_bf16 v[110:113], v[134:137], v[206:209], v[110:113]
	v_mfma_f32_16x16x32_bf16 v[106:109], v[142:145], v[206:209], v[106:109]
	s_barrier
	v_mfma_f32_16x16x32_bf16 v[118:121], v[134:137], v[228:231], v[118:121]
	v_mfma_f32_16x16x32_bf16 v[114:117], v[142:145], v[228:231], v[114:117]
	v_mfma_f32_16x16x32_bf16 v[126:129], v[134:137], v[236:239], v[126:129]
	v_mfma_f32_16x16x32_bf16 v[122:125], v[142:145], v[236:239], v[122:125]
	v_mfma_f32_16x16x32_bf16 v[82:85], v[138:141], v[202:205], v[82:85]
	v_mfma_f32_16x16x32_bf16 v[78:81], v[178:181], v[202:205], v[78:81]
	v_mfma_f32_16x16x32_bf16 v[110:113], v[138:141], v[224:227], v[110:113]
	v_mfma_f32_16x16x32_bf16 v[106:109], v[178:181], v[224:227], v[106:109]
	v_mfma_f32_16x16x32_bf16 v[118:121], v[138:141], v[232:235], v[118:121]
	v_mfma_f32_16x16x32_bf16 v[114:117], v[178:181], v[232:235], v[114:117]
	v_mfma_f32_16x16x32_bf16 v[126:129], v[138:141], v[240:243], v[126:129]
	v_mfma_f32_16x16x32_bf16 v[122:125], v[178:181], v[240:243], v[122:125]
	v_mfma_f32_16x16x32_bf16 v[22:25], v[182:185], v[198:201], v[22:25]
	v_mfma_f32_16x16x32_bf16 v[26:29], v[190:193], v[198:201], v[26:29]
	v_mfma_f32_16x16x32_bf16 v[42:45], v[182:185], v[206:209], v[42:45]
	v_mfma_f32_16x16x32_bf16 v[46:49], v[190:193], v[206:209], v[46:49]
	v_mfma_f32_16x16x32_bf16 v[62:65], v[182:185], v[228:231], v[62:65]
	v_mfma_f32_16x16x32_bf16 v[70:73], v[190:193], v[228:231], v[70:73]
	v_mfma_f32_16x16x32_bf16 v[90:93], v[182:185], v[236:239], v[90:93]
	v_mfma_f32_16x16x32_bf16 v[94:97], v[190:193], v[236:239], v[94:97]
	v_mfma_f32_16x16x32_bf16 v[22:25], v[186:189], v[202:205], v[22:25]
	v_mfma_f32_16x16x32_bf16 v[26:29], v[194:197], v[202:205], v[26:29]
	v_mfma_f32_16x16x32_bf16 v[42:45], v[186:189], v[224:227], v[42:45]
	v_mfma_f32_16x16x32_bf16 v[46:49], v[194:197], v[224:227], v[46:49]
	v_mfma_f32_16x16x32_bf16 v[62:65], v[186:189], v[232:235], v[62:65]
	v_mfma_f32_16x16x32_bf16 v[70:73], v[194:197], v[232:235], v[70:73]
	v_mfma_f32_16x16x32_bf16 v[90:93], v[186:189], v[240:243], v[90:93]
	v_mfma_f32_16x16x32_bf16 v[94:97], v[194:197], v[240:243], v[94:97]
	s_barrier
	s_mov_b32 m0, s68
	v_lshl_add_u64 v[244:245], s[42:43], 0, v[150:151]
	s_add_u32 s18, s42, 0x100000
	ds_read_b128 v[198:201], v216 offset:16384
	ds_read_b128 v[202:205], v216 offset:17408
	ds_read_b128 v[206:209], v216 offset:18432
	ds_read_b128 v[224:227], v216 offset:19456
	ds_read_b128 v[228:231], v216 offset:20480
	ds_read_b128 v[232:235], v216 offset:21504
	ds_read_b128 v[236:239], v216 offset:22528
	ds_read_b128 v[240:243], v216 offset:23552
	global_load_lds_dwordx4 v[244:245], off
	v_lshl_add_u64 v[246:247], s[42:43], 0, v[146:147]
	s_mov_b32 m0, s69
	s_addc_u32 s19, s43, 0
	global_load_lds_dwordx4 v[246:247], off
	v_lshl_add_u64 v[248:249], s[18:19], 0, v[150:151]
	s_mov_b32 m0, s73
	v_lshl_add_u64 v[250:251], s[44:45], 0, v[148:149]
	global_load_lds_dwordx4 v[248:249], off
	v_lshl_add_u64 v[248:249], s[18:19], 0, v[146:147]
	s_mov_b32 m0, s74
	s_nop 0
	global_load_lds_dwordx4 v[248:249], off
	v_lshl_add_u64 v[248:249], s[44:45], 0, v[152:153]
	s_mov_b32 m0, s9
	s_nop 0
	global_load_lds_dwordx4 v[248:249], off
	s_mov_b32 m0, s55
	s_nop 0
	global_load_lds_dwordx4 v[250:251], off
	s_waitcnt vmcnt(8)
	s_waitcnt lgkmcnt(0)
	s_waitcnt lgkmcnt(0)
	v_mfma_f32_16x16x32_bf16 v[102:105], v[134:137], v[198:201], v[102:105]
	v_mfma_f32_16x16x32_bf16 v[98:101], v[142:145], v[198:201], v[98:101]
	v_mfma_f32_16x16x32_bf16 v[66:69], v[134:137], v[206:209], v[66:69]
	v_mfma_f32_16x16x32_bf16 v[58:61], v[142:145], v[206:209], v[58:61]
	s_barrier
	v_mfma_f32_16x16x32_bf16 v[38:41], v[134:137], v[228:231], v[38:41]
	v_mfma_f32_16x16x32_bf16 v[34:37], v[142:145], v[228:231], v[34:37]
	v_mfma_f32_16x16x32_bf16 v[14:17], v[134:137], v[236:239], v[14:17]
	v_mfma_f32_16x16x32_bf16 v[10:13], v[142:145], v[236:239], v[10:13]
	v_mfma_f32_16x16x32_bf16 v[102:105], v[138:141], v[202:205], v[102:105]
	v_mfma_f32_16x16x32_bf16 v[98:101], v[178:181], v[202:205], v[98:101]
	v_mfma_f32_16x16x32_bf16 v[66:69], v[138:141], v[224:227], v[66:69]
	v_mfma_f32_16x16x32_bf16 v[58:61], v[178:181], v[224:227], v[58:61]
	v_mfma_f32_16x16x32_bf16 v[38:41], v[138:141], v[232:235], v[38:41]
	v_mfma_f32_16x16x32_bf16 v[34:37], v[178:181], v[232:235], v[34:37]
	v_mfma_f32_16x16x32_bf16 v[14:17], v[138:141], v[240:243], v[14:17]
	v_mfma_f32_16x16x32_bf16 v[10:13], v[178:181], v[240:243], v[10:13]
	v_mfma_f32_16x16x32_bf16 v[86:89], v[182:185], v[198:201], v[86:89]
	v_mfma_f32_16x16x32_bf16 v[74:77], v[190:193], v[198:201], v[74:77]
	v_mfma_f32_16x16x32_bf16 v[54:57], v[182:185], v[206:209], v[54:57]
	v_mfma_f32_16x16x32_bf16 v[50:53], v[190:193], v[206:209], v[50:53]
	v_mfma_f32_16x16x32_bf16 v[30:33], v[182:185], v[228:231], v[30:33]
	v_mfma_f32_16x16x32_bf16 v[18:21], v[190:193], v[228:231], v[18:21]
	v_mfma_f32_16x16x32_bf16 v[6:9], v[182:185], v[236:239], v[6:9]
	v_mfma_f32_16x16x32_bf16 v[2:5], v[190:193], v[236:239], v[2:5]
	v_mfma_f32_16x16x32_bf16 v[86:89], v[186:189], v[202:205], v[86:89]
	v_mfma_f32_16x16x32_bf16 v[74:77], v[194:197], v[202:205], v[74:77]
	v_mfma_f32_16x16x32_bf16 v[54:57], v[186:189], v[224:227], v[54:57]
	v_mfma_f32_16x16x32_bf16 v[50:53], v[194:197], v[224:227], v[50:53]
	v_mfma_f32_16x16x32_bf16 v[30:33], v[186:189], v[232:235], v[30:33]
	v_mfma_f32_16x16x32_bf16 v[18:21], v[194:197], v[232:235], v[18:21]
	v_mfma_f32_16x16x32_bf16 v[6:9], v[186:189], v[240:243], v[6:9]
	v_mfma_f32_16x16x32_bf16 v[2:5], v[194:197], v[240:243], v[2:5]
	s_barrier
	s_add_i32 s20, 0, 0x1c000
	v_add_u32_e32 v194, s20, v212
	ds_read_b128 v[134:137], v220
	ds_read_b128 v[138:141], v220 offset:1024
	ds_read_b128 v[142:145], v220 offset:2048
	ds_read_b128 v[178:181], v220 offset:3072
	ds_read_b128 v[182:185], v194
	ds_read_b128 v[186:189], v194 offset:1024
	ds_read_b128 v[190:193], v194 offset:2048
	ds_read_b128 v[194:197], v194 offset:3072
	s_add_u32 s18, s44, 0x100000
	s_addc_u32 s19, s45, 0
	s_mov_b32 m0, s56
	v_lshl_add_u64 v[252:253], s[18:19], 0, v[152:153]
	ds_read_b128 v[198:201], v216 offset:32768
	ds_read_b128 v[202:205], v216 offset:33792
	ds_read_b128 v[206:209], v216 offset:34816
	ds_read_b128 v[224:227], v216 offset:35840
	ds_read_b128 v[228:231], v216 offset:36864
	ds_read_b128 v[232:235], v216 offset:37888
	ds_read_b128 v[236:239], v216 offset:38912
	ds_read_b128 v[240:243], v216 offset:39936
	global_load_lds_dwordx4 v[252:253], off
	v_lshl_add_u64 v[252:253], s[18:19], 0, v[148:149]
	s_mov_b32 m0, s57
	s_nop 0
	global_load_lds_dwordx4 v[252:253], off
	s_waitcnt vmcnt(8)
	s_waitcnt lgkmcnt(0)
	s_waitcnt lgkmcnt(0)
	v_mfma_f32_16x16x32_bf16 v[82:85], v[134:137], v[198:201], v[82:85]
	v_mfma_f32_16x16x32_bf16 v[78:81], v[142:145], v[198:201], v[78:81]
	v_mfma_f32_16x16x32_bf16 v[110:113], v[134:137], v[206:209], v[110:113]
	v_mfma_f32_16x16x32_bf16 v[106:109], v[142:145], v[206:209], v[106:109]
	s_barrier
	v_mfma_f32_16x16x32_bf16 v[118:121], v[134:137], v[228:231], v[118:121]
	v_mfma_f32_16x16x32_bf16 v[114:117], v[142:145], v[228:231], v[114:117]
	v_mfma_f32_16x16x32_bf16 v[126:129], v[134:137], v[236:239], v[126:129]
	v_mfma_f32_16x16x32_bf16 v[122:125], v[142:145], v[236:239], v[122:125]
	v_mfma_f32_16x16x32_bf16 v[82:85], v[138:141], v[202:205], v[82:85]
	v_mfma_f32_16x16x32_bf16 v[78:81], v[178:181], v[202:205], v[78:81]
	v_mfma_f32_16x16x32_bf16 v[110:113], v[138:141], v[224:227], v[110:113]
	v_mfma_f32_16x16x32_bf16 v[106:109], v[178:181], v[224:227], v[106:109]
	v_mfma_f32_16x16x32_bf16 v[118:121], v[138:141], v[232:235], v[118:121]
	v_mfma_f32_16x16x32_bf16 v[114:117], v[178:181], v[232:235], v[114:117]
	v_mfma_f32_16x16x32_bf16 v[126:129], v[138:141], v[240:243], v[126:129]
	v_mfma_f32_16x16x32_bf16 v[122:125], v[178:181], v[240:243], v[122:125]
	v_mfma_f32_16x16x32_bf16 v[22:25], v[182:185], v[198:201], v[22:25]
	v_mfma_f32_16x16x32_bf16 v[26:29], v[190:193], v[198:201], v[26:29]
	v_mfma_f32_16x16x32_bf16 v[42:45], v[182:185], v[206:209], v[42:45]
	v_mfma_f32_16x16x32_bf16 v[46:49], v[190:193], v[206:209], v[46:49]
	v_mfma_f32_16x16x32_bf16 v[62:65], v[182:185], v[228:231], v[62:65]
	v_mfma_f32_16x16x32_bf16 v[70:73], v[190:193], v[228:231], v[70:73]
	v_mfma_f32_16x16x32_bf16 v[90:93], v[182:185], v[236:239], v[90:93]
	v_mfma_f32_16x16x32_bf16 v[94:97], v[190:193], v[236:239], v[94:97]
	v_mfma_f32_16x16x32_bf16 v[22:25], v[186:189], v[202:205], v[22:25]
	v_mfma_f32_16x16x32_bf16 v[26:29], v[194:197], v[202:205], v[26:29]
	v_mfma_f32_16x16x32_bf16 v[42:45], v[186:189], v[224:227], v[42:45]
	v_mfma_f32_16x16x32_bf16 v[46:49], v[194:197], v[224:227], v[46:49]
	v_mfma_f32_16x16x32_bf16 v[62:65], v[186:189], v[232:235], v[62:65]
	v_mfma_f32_16x16x32_bf16 v[70:73], v[194:197], v[232:235], v[70:73]
	v_mfma_f32_16x16x32_bf16 v[90:93], v[186:189], v[240:243], v[90:93]
	v_mfma_f32_16x16x32_bf16 v[94:97], v[194:197], v[240:243], v[94:97]
	s_barrier
	s_add_i32 s18, s75, s54
	v_lshl_add_u64 v[244:245], v[244:245], 0, s[26:27]
	s_mov_b32 m0, s18
	ds_read_b128 v[198:201], v216 offset:49152
	ds_read_b128 v[202:205], v216 offset:50176
	ds_read_b128 v[206:209], v216 offset:51200
	ds_read_b128 v[224:227], v216 offset:52224
	ds_read_b128 v[228:231], v216 offset:53248
	ds_read_b128 v[232:235], v216 offset:54272
	ds_read_b128 v[236:239], v216 offset:55296
	ds_read_b128 v[240:243], v216 offset:56320
	global_load_lds_dwordx4 v[244:245], off
	s_add_i32 m0, s18, 0x2000
	s_add_u32 s18, s42, 0x100080
	v_lshl_add_u64 v[244:245], v[246:247], 0, s[26:27]
	s_addc_u32 s19, s43, 0
	s_add_i32 s20, s20, s54
	global_load_lds_dwordx4 v[244:245], off
	v_lshl_add_u64 v[244:245], s[18:19], 0, v[150:151]
	s_mov_b32 m0, s20
	s_nop 0
	global_load_lds_dwordx4 v[244:245], off
	v_lshl_add_u64 v[244:245], s[18:19], 0, v[146:147]
	s_add_i32 m0, s20, 0x2000
	s_nop 0
	global_load_lds_dwordx4 v[244:245], off
	v_lshl_add_u64 v[244:245], v[248:249], 0, s[26:27]
	s_mov_b32 m0, s63
	s_nop 0
	global_load_lds_dwordx4 v[244:245], off
	v_lshl_add_u64 v[244:245], v[250:251], 0, s[26:27]
	s_mov_b32 m0, s64
	s_nop 0
	global_load_lds_dwordx4 v[244:245], off
	s_waitcnt vmcnt(8)
	s_waitcnt lgkmcnt(0)
	s_waitcnt lgkmcnt(0)
	v_mfma_f32_16x16x32_bf16 v[102:105], v[134:137], v[198:201], v[102:105]
	v_mfma_f32_16x16x32_bf16 v[98:101], v[142:145], v[198:201], v[98:101]
	v_mfma_f32_16x16x32_bf16 v[66:69], v[134:137], v[206:209], v[66:69]
	v_mfma_f32_16x16x32_bf16 v[58:61], v[142:145], v[206:209], v[58:61]
	s_barrier
	v_mfma_f32_16x16x32_bf16 v[38:41], v[134:137], v[228:231], v[38:41]
	v_mfma_f32_16x16x32_bf16 v[34:37], v[142:145], v[228:231], v[34:37]
	v_mfma_f32_16x16x32_bf16 v[14:17], v[134:137], v[236:239], v[14:17]
	v_mfma_f32_16x16x32_bf16 v[10:13], v[142:145], v[236:239], v[10:13]
	v_mfma_f32_16x16x32_bf16 v[102:105], v[138:141], v[202:205], v[102:105]
	v_mfma_f32_16x16x32_bf16 v[98:101], v[178:181], v[202:205], v[98:101]
	v_mfma_f32_16x16x32_bf16 v[66:69], v[138:141], v[224:227], v[66:69]
	v_mfma_f32_16x16x32_bf16 v[58:61], v[178:181], v[224:227], v[58:61]
	v_mfma_f32_16x16x32_bf16 v[38:41], v[138:141], v[232:235], v[38:41]
	v_mfma_f32_16x16x32_bf16 v[34:37], v[178:181], v[232:235], v[34:37]
	v_mfma_f32_16x16x32_bf16 v[14:17], v[138:141], v[240:243], v[14:17]
	v_mfma_f32_16x16x32_bf16 v[10:13], v[178:181], v[240:243], v[10:13]
	v_mfma_f32_16x16x32_bf16 v[86:89], v[182:185], v[198:201], v[86:89]
	v_mfma_f32_16x16x32_bf16 v[74:77], v[190:193], v[198:201], v[74:77]
	v_mfma_f32_16x16x32_bf16 v[54:57], v[182:185], v[206:209], v[54:57]
	v_mfma_f32_16x16x32_bf16 v[50:53], v[190:193], v[206:209], v[50:53]
	v_mfma_f32_16x16x32_bf16 v[30:33], v[182:185], v[228:231], v[30:33]
	v_mfma_f32_16x16x32_bf16 v[18:21], v[190:193], v[228:231], v[18:21]
	v_mfma_f32_16x16x32_bf16 v[6:9], v[182:185], v[236:239], v[6:9]
	v_mfma_f32_16x16x32_bf16 v[2:5], v[190:193], v[236:239], v[2:5]
	v_mfma_f32_16x16x32_bf16 v[86:89], v[186:189], v[202:205], v[86:89]
	v_mfma_f32_16x16x32_bf16 v[74:77], v[194:197], v[202:205], v[74:77]
	v_mfma_f32_16x16x32_bf16 v[54:57], v[186:189], v[224:227], v[54:57]
	v_mfma_f32_16x16x32_bf16 v[50:53], v[194:197], v[224:227], v[50:53]
	v_mfma_f32_16x16x32_bf16 v[30:33], v[186:189], v[232:235], v[30:33]
	v_mfma_f32_16x16x32_bf16 v[18:21], v[194:197], v[232:235], v[18:21]
	v_mfma_f32_16x16x32_bf16 v[6:9], v[186:189], v[240:243], v[6:9]
	v_mfma_f32_16x16x32_bf16 v[2:5], v[194:197], v[240:243], v[2:5]
	s_barrier
	s_add_i32 s17, s17, 2
	s_cmp_gt_u32 s17, 61
	s_mov_b64 s[38:39], s[40:41]
	s_cbranch_scc0 .LBB0_699
	s_and_b64 vcc, exec, s[28:29]
	s_cbranch_vccz .LBB0_702
	s_barrier

.LBB0_877:
	ds_read_b128 v[130:133], v220
	ds_read_b128 v[134:137], v220 offset:1024
	ds_read_b128 v[138:141], v220 offset:2048
	ds_read_b128 v[142:145], v220 offset:3072
	ds_read_b128 v[184:187], v224
	ds_read_b128 v[188:191], v224 offset:1024
	ds_read_b128 v[192:195], v224 offset:2048
	ds_read_b128 v[196:199], v224 offset:3072
	s_add_u32 s14, s36, 0xffea0080
	s_addc_u32 s15, s37, -1
	s_cmpk_eq_i32 s3, 0x54
	s_cselect_b32 s43, s29, s15
	s_cselect_b32 s42, s28, s14
	s_cselect_b32 s41, s9, s39
	s_cselect_b32 s40, s8, s38
	s_mov_b32 m0, s50
	v_lshl_add_u64 v[244:245], s[36:37], 0, v[178:179]
	ds_read_b128 v[200:203], v221
	ds_read_b128 v[204:207], v221 offset:1024
	ds_read_b128 v[208:211], v221 offset:2048
	ds_read_b128 v[212:215], v221 offset:3072
	ds_read_b128 v[228:231], v221 offset:4096
	ds_read_b128 v[232:235], v221 offset:5120
	ds_read_b128 v[236:239], v221 offset:6144
	ds_read_b128 v[240:243], v221 offset:7168
	global_load_lds_dwordx4 v[244:245], off
	v_lshl_add_u64 v[244:245], s[36:37], 0, v[180:181]
	s_mov_b32 m0, s51
	s_nop 0
	global_load_lds_dwordx4 v[244:245], off
	s_waitcnt vmcnt(8)
	s_waitcnt lgkmcnt(0)
	s_waitcnt lgkmcnt(0)
	v_mfma_f32_16x16x32_bf16 v[30:33], v[130:133], v[200:203], v[30:33]
	v_mfma_f32_16x16x32_bf16 v[26:29], v[138:141], v[200:203], v[26:29]
	v_mfma_f32_16x16x32_bf16 v[46:49], v[130:133], v[208:211], v[46:49]
	v_mfma_f32_16x16x32_bf16 v[42:45], v[138:141], v[208:211], v[42:45]
	s_barrier
	v_mfma_f32_16x16x32_bf16 v[62:65], v[130:133], v[228:231], v[62:65]
	v_mfma_f32_16x16x32_bf16 v[58:61], v[138:141], v[228:231], v[58:61]
	v_mfma_f32_16x16x32_bf16 v[94:97], v[130:133], v[236:239], v[94:97]
	v_mfma_f32_16x16x32_bf16 v[90:93], v[138:141], v[236:239], v[90:93]
	v_mfma_f32_16x16x32_bf16 v[30:33], v[134:137], v[204:207], v[30:33]
	v_mfma_f32_16x16x32_bf16 v[26:29], v[142:145], v[204:207], v[26:29]
	v_mfma_f32_16x16x32_bf16 v[46:49], v[134:137], v[212:215], v[46:49]
	v_mfma_f32_16x16x32_bf16 v[42:45], v[142:145], v[212:215], v[42:45]
	v_mfma_f32_16x16x32_bf16 v[62:65], v[134:137], v[232:235], v[62:65]
	v_mfma_f32_16x16x32_bf16 v[58:61], v[142:145], v[232:235], v[58:61]
	v_mfma_f32_16x16x32_bf16 v[94:97], v[134:137], v[240:243], v[94:97]
	v_mfma_f32_16x16x32_bf16 v[90:93], v[142:145], v[240:243], v[90:93]
	v_mfma_f32_16x16x32_bf16 v[2:5], v[184:187], v[200:203], v[2:5]
	v_mfma_f32_16x16x32_bf16 v[6:9], v[192:195], v[200:203], v[6:9]
	v_mfma_f32_16x16x32_bf16 v[10:13], v[184:187], v[208:211], v[10:13]
	v_mfma_f32_16x16x32_bf16 v[14:17], v[192:195], v[208:211], v[14:17]
	v_mfma_f32_16x16x32_bf16 v[18:21], v[184:187], v[228:231], v[18:21]
	v_mfma_f32_16x16x32_bf16 v[22:25], v[192:195], v[228:231], v[22:25]
	v_mfma_f32_16x16x32_bf16 v[34:37], v[184:187], v[236:239], v[34:37]
	v_mfma_f32_16x16x32_bf16 v[38:41], v[192:195], v[236:239], v[38:41]
	v_mfma_f32_16x16x32_bf16 v[2:5], v[188:191], v[204:207], v[2:5]
	v_mfma_f32_16x16x32_bf16 v[6:9], v[196:199], v[204:207], v[6:9]
	v_mfma_f32_16x16x32_bf16 v[10:13], v[188:191], v[212:215], v[10:13]
	v_mfma_f32_16x16x32_bf16 v[14:17], v[196:199], v[212:215], v[14:17]
	v_mfma_f32_16x16x32_bf16 v[18:21], v[188:191], v[232:235], v[18:21]
	v_mfma_f32_16x16x32_bf16 v[22:25], v[196:199], v[232:235], v[22:25]
	v_mfma_f32_16x16x32_bf16 v[34:37], v[188:191], v[240:243], v[34:37]
	v_mfma_f32_16x16x32_bf16 v[38:41], v[196:199], v[240:243], v[38:41]
	s_barrier
	s_mov_b32 m0, s52
	v_lshl_add_u64 v[244:245], s[40:41], 0, v[150:151]
	s_add_u32 s14, s40, 0x160000
	ds_read_b128 v[200:203], v221 offset:16384
	ds_read_b128 v[204:207], v221 offset:17408
	ds_read_b128 v[208:211], v221 offset:18432
	ds_read_b128 v[212:215], v221 offset:19456
	ds_read_b128 v[228:231], v221 offset:20480
	ds_read_b128 v[232:235], v221 offset:21504
	ds_read_b128 v[236:239], v221 offset:22528
	ds_read_b128 v[240:243], v221 offset:23552
	global_load_lds_dwordx4 v[244:245], off
	v_lshl_add_u64 v[246:247], s[40:41], 0, v[146:147]
	s_mov_b32 m0, s53
	s_addc_u32 s15, s41, 0
	global_load_lds_dwordx4 v[246:247], off
	v_lshl_add_u64 v[248:249], s[14:15], 0, v[150:151]
	s_mov_b32 m0, s54
	v_lshl_add_u64 v[250:251], s[42:43], 0, v[148:149]
	global_load_lds_dwordx4 v[248:249], off
	v_lshl_add_u64 v[248:249], s[14:15], 0, v[146:147]
	s_mov_b32 m0, s55
	s_nop 0
	global_load_lds_dwordx4 v[248:249], off
	v_lshl_add_u64 v[248:249], s[42:43], 0, v[152:153]
	s_mov_b32 m0, s61
	s_nop 0
	global_load_lds_dwordx4 v[248:249], off
	s_mov_b32 m0, s62
	s_nop 0
	global_load_lds_dwordx4 v[250:251], off
	s_waitcnt vmcnt(8)
	s_waitcnt lgkmcnt(0)
	s_waitcnt lgkmcnt(0)
	v_mfma_f32_16x16x32_bf16 v[114:117], v[130:133], v[200:203], v[114:117]
	v_mfma_f32_16x16x32_bf16 v[110:113], v[138:141], v[200:203], v[110:113]
	v_mfma_f32_16x16x32_bf16 v[126:129], v[130:133], v[208:211], v[126:129]
	v_mfma_f32_16x16x32_bf16 v[122:125], v[138:141], v[208:211], v[122:125]
	s_barrier
	v_mfma_f32_16x16x32_bf16 v[118:121], v[130:133], v[228:231], v[118:121]
	v_mfma_f32_16x16x32_bf16 v[106:109], v[138:141], v[228:231], v[106:109]
	v_mfma_f32_16x16x32_bf16 v[78:81], v[130:133], v[236:239], v[78:81]
	v_mfma_f32_16x16x32_bf16 v[74:77], v[138:141], v[236:239], v[74:77]
	v_mfma_f32_16x16x32_bf16 v[114:117], v[134:137], v[204:207], v[114:117]
	v_mfma_f32_16x16x32_bf16 v[110:113], v[142:145], v[204:207], v[110:113]
	v_mfma_f32_16x16x32_bf16 v[126:129], v[134:137], v[212:215], v[126:129]
	v_mfma_f32_16x16x32_bf16 v[122:125], v[142:145], v[212:215], v[122:125]
	v_mfma_f32_16x16x32_bf16 v[118:121], v[134:137], v[232:235], v[118:121]
	v_mfma_f32_16x16x32_bf16 v[106:109], v[142:145], v[232:235], v[106:109]
	v_mfma_f32_16x16x32_bf16 v[78:81], v[134:137], v[240:243], v[78:81]
	v_mfma_f32_16x16x32_bf16 v[74:77], v[142:145], v[240:243], v[74:77]
	v_mfma_f32_16x16x32_bf16 v[50:53], v[184:187], v[200:203], v[50:53]
	v_mfma_f32_16x16x32_bf16 v[54:57], v[192:195], v[200:203], v[54:57]
	v_mfma_f32_16x16x32_bf16 v[82:85], v[184:187], v[208:211], v[82:85]
	v_mfma_f32_16x16x32_bf16 v[86:89], v[192:195], v[208:211], v[86:89]
	v_mfma_f32_16x16x32_bf16 v[102:105], v[184:187], v[228:231], v[102:105]
	v_mfma_f32_16x16x32_bf16 v[98:101], v[192:195], v[228:231], v[98:101]
	v_mfma_f32_16x16x32_bf16 v[70:73], v[184:187], v[236:239], v[70:73]
	v_mfma_f32_16x16x32_bf16 v[66:69], v[192:195], v[236:239], v[66:69]
	v_mfma_f32_16x16x32_bf16 v[50:53], v[188:191], v[204:207], v[50:53]
	v_mfma_f32_16x16x32_bf16 v[54:57], v[196:199], v[204:207], v[54:57]
	v_mfma_f32_16x16x32_bf16 v[82:85], v[188:191], v[212:215], v[82:85]
	v_mfma_f32_16x16x32_bf16 v[86:89], v[196:199], v[212:215], v[86:89]
	v_mfma_f32_16x16x32_bf16 v[102:105], v[188:191], v[232:235], v[102:105]
	v_mfma_f32_16x16x32_bf16 v[98:101], v[196:199], v[232:235], v[98:101]
	v_mfma_f32_16x16x32_bf16 v[70:73], v[188:191], v[240:243], v[70:73]
	v_mfma_f32_16x16x32_bf16 v[66:69], v[196:199], v[240:243], v[66:69]
	s_barrier
	v_add_u32_e32 v196, s74, v218
	ds_read_b128 v[130:133], v225
	ds_read_b128 v[134:137], v225 offset:1024
	ds_read_b128 v[138:141], v225 offset:2048
	ds_read_b128 v[142:145], v225 offset:3072
	ds_read_b128 v[184:187], v196
	ds_read_b128 v[188:191], v196 offset:1024
	ds_read_b128 v[192:195], v196 offset:2048
	ds_read_b128 v[196:199], v196 offset:3072
	s_add_u32 s14, s42, 0x160000
	s_addc_u32 s15, s43, 0
	s_mov_b32 m0, s63
	v_lshl_add_u64 v[252:253], s[14:15], 0, v[152:153]
	ds_read_b128 v[200:203], v221 offset:32768
	ds_read_b128 v[204:207], v221 offset:33792
	ds_read_b128 v[208:211], v221 offset:34816
	ds_read_b128 v[212:215], v221 offset:35840
	ds_read_b128 v[228:231], v221 offset:36864
	ds_read_b128 v[232:235], v221 offset:37888
	ds_read_b128 v[236:239], v221 offset:38912
	ds_read_b128 v[240:243], v221 offset:39936
	global_load_lds_dwordx4 v[252:253], off
	v_lshl_add_u64 v[252:253], s[14:15], 0, v[148:149]
	s_mov_b32 m0, s64
	s_nop 0
	global_load_lds_dwordx4 v[252:253], off
	s_waitcnt vmcnt(8)
	s_waitcnt lgkmcnt(0)
	s_waitcnt lgkmcnt(0)
	v_mfma_f32_16x16x32_bf16 v[30:33], v[130:133], v[200:203], v[30:33]
	v_mfma_f32_16x16x32_bf16 v[26:29], v[138:141], v[200:203], v[26:29]
	v_mfma_f32_16x16x32_bf16 v[46:49], v[130:133], v[208:211], v[46:49]
	v_mfma_f32_16x16x32_bf16 v[42:45], v[138:141], v[208:211], v[42:45]
	s_barrier
	v_mfma_f32_16x16x32_bf16 v[62:65], v[130:133], v[228:231], v[62:65]
	v_mfma_f32_16x16x32_bf16 v[58:61], v[138:141], v[228:231], v[58:61]
	v_mfma_f32_16x16x32_bf16 v[94:97], v[130:133], v[236:239], v[94:97]
	v_mfma_f32_16x16x32_bf16 v[90:93], v[138:141], v[236:239], v[90:93]
	v_mfma_f32_16x16x32_bf16 v[30:33], v[134:137], v[204:207], v[30:33]
	v_mfma_f32_16x16x32_bf16 v[26:29], v[142:145], v[204:207], v[26:29]
	v_mfma_f32_16x16x32_bf16 v[46:49], v[134:137], v[212:215], v[46:49]
	v_mfma_f32_16x16x32_bf16 v[42:45], v[142:145], v[212:215], v[42:45]
	v_mfma_f32_16x16x32_bf16 v[62:65], v[134:137], v[232:235], v[62:65]
	v_mfma_f32_16x16x32_bf16 v[58:61], v[142:145], v[232:235], v[58:61]
	v_mfma_f32_16x16x32_bf16 v[94:97], v[134:137], v[240:243], v[94:97]
	v_mfma_f32_16x16x32_bf16 v[90:93], v[142:145], v[240:243], v[90:93]
	v_mfma_f32_16x16x32_bf16 v[2:5], v[184:187], v[200:203], v[2:5]
	v_mfma_f32_16x16x32_bf16 v[6:9], v[192:195], v[200:203], v[6:9]
	v_mfma_f32_16x16x32_bf16 v[10:13], v[184:187], v[208:211], v[10:13]
	v_mfma_f32_16x16x32_bf16 v[14:17], v[192:195], v[208:211], v[14:17]
	v_mfma_f32_16x16x32_bf16 v[18:21], v[184:187], v[228:231], v[18:21]
	v_mfma_f32_16x16x32_bf16 v[22:25], v[192:195], v[228:231], v[22:25]
	v_mfma_f32_16x16x32_bf16 v[34:37], v[184:187], v[236:239], v[34:37]
	v_mfma_f32_16x16x32_bf16 v[38:41], v[192:195], v[236:239], v[38:41]
	v_mfma_f32_16x16x32_bf16 v[2:5], v[188:191], v[204:207], v[2:5]
	v_mfma_f32_16x16x32_bf16 v[6:9], v[196:199], v[204:207], v[6:9]
	v_mfma_f32_16x16x32_bf16 v[10:13], v[188:191], v[212:215], v[10:13]
	v_mfma_f32_16x16x32_bf16 v[14:17], v[196:199], v[212:215], v[14:17]
	v_mfma_f32_16x16x32_bf16 v[18:21], v[188:191], v[232:235], v[18:21]
	v_mfma_f32_16x16x32_bf16 v[22:25], v[196:199], v[232:235], v[22:25]
	v_mfma_f32_16x16x32_bf16 v[34:37], v[188:191], v[240:243], v[34:37]
	v_mfma_f32_16x16x32_bf16 v[38:41], v[196:199], v[240:243], v[38:41]
	s_barrier
	s_mov_b32 m0, s75
	v_lshl_add_u64 v[244:245], v[244:245], 0, s[22:23]
	s_add_u32 s14, s40, 0x160080
	ds_read_b128 v[200:203], v221 offset:49152
	ds_read_b128 v[204:207], v221 offset:50176
	ds_read_b128 v[208:211], v221 offset:51200
	ds_read_b128 v[212:215], v221 offset:52224
	ds_read_b128 v[228:231], v221 offset:53248
	ds_read_b128 v[232:235], v221 offset:54272
	ds_read_b128 v[236:239], v221 offset:55296
	ds_read_b128 v[240:243], v221 offset:56320
	global_load_lds_dwordx4 v[244:245], off
	v_lshl_add_u64 v[244:245], v[246:247], 0, s[22:23]
	s_mov_b32 m0, s76
	s_addc_u32 s15, s41, 0
	global_load_lds_dwordx4 v[244:245], off
	v_lshl_add_u64 v[244:245], s[14:15], 0, v[150:151]
	s_mov_b32 m0, s77
	s_nop 0
	global_load_lds_dwordx4 v[244:245], off
	v_lshl_add_u64 v[244:245], s[14:15], 0, v[146:147]
	s_mov_b32 m0, s78
	s_nop 0
	global_load_lds_dwordx4 v[244:245], off
	v_lshl_add_u64 v[244:245], v[248:249], 0, s[22:23]
	s_mov_b32 m0, s68
	s_nop 0
	global_load_lds_dwordx4 v[244:245], off
	v_lshl_add_u64 v[244:245], v[250:251], 0, s[22:23]
	s_mov_b32 m0, s69
	s_nop 0
	global_load_lds_dwordx4 v[244:245], off
	s_waitcnt vmcnt(8)
	s_waitcnt lgkmcnt(0)
	s_waitcnt lgkmcnt(0)
	v_mfma_f32_16x16x32_bf16 v[114:117], v[130:133], v[200:203], v[114:117]
	v_mfma_f32_16x16x32_bf16 v[110:113], v[138:141], v[200:203], v[110:113]
	v_mfma_f32_16x16x32_bf16 v[126:129], v[130:133], v[208:211], v[126:129]
	v_mfma_f32_16x16x32_bf16 v[122:125], v[138:141], v[208:211], v[122:125]
	s_barrier
	v_mfma_f32_16x16x32_bf16 v[118:121], v[130:133], v[228:231], v[118:121]
	v_mfma_f32_16x16x32_bf16 v[106:109], v[138:141], v[228:231], v[106:109]
	v_mfma_f32_16x16x32_bf16 v[78:81], v[130:133], v[236:239], v[78:81]
	v_mfma_f32_16x16x32_bf16 v[74:77], v[138:141], v[236:239], v[74:77]
	v_mfma_f32_16x16x32_bf16 v[114:117], v[134:137], v[204:207], v[114:117]
	v_mfma_f32_16x16x32_bf16 v[110:113], v[142:145], v[204:207], v[110:113]
	v_mfma_f32_16x16x32_bf16 v[126:129], v[134:137], v[212:215], v[126:129]
	v_mfma_f32_16x16x32_bf16 v[122:125], v[142:145], v[212:215], v[122:125]
	v_mfma_f32_16x16x32_bf16 v[118:121], v[134:137], v[232:235], v[118:121]
	v_mfma_f32_16x16x32_bf16 v[106:109], v[142:145], v[232:235], v[106:109]
	v_mfma_f32_16x16x32_bf16 v[78:81], v[134:137], v[240:243], v[78:81]
	v_mfma_f32_16x16x32_bf16 v[74:77], v[142:145], v[240:243], v[74:77]
	v_mfma_f32_16x16x32_bf16 v[50:53], v[184:187], v[200:203], v[50:53]
	v_mfma_f32_16x16x32_bf16 v[54:57], v[192:195], v[200:203], v[54:57]
	v_mfma_f32_16x16x32_bf16 v[82:85], v[184:187], v[208:211], v[82:85]
	v_mfma_f32_16x16x32_bf16 v[86:89], v[192:195], v[208:211], v[86:89]
	v_mfma_f32_16x16x32_bf16 v[102:105], v[184:187], v[228:231], v[102:105]
	v_mfma_f32_16x16x32_bf16 v[98:101], v[192:195], v[228:231], v[98:101]
	v_mfma_f32_16x16x32_bf16 v[70:73], v[184:187], v[236:239], v[70:73]
	v_mfma_f32_16x16x32_bf16 v[66:69], v[192:195], v[236:239], v[66:69]
	v_mfma_f32_16x16x32_bf16 v[50:53], v[188:191], v[204:207], v[50:53]
	v_mfma_f32_16x16x32_bf16 v[54:57], v[196:199], v[204:207], v[54:57]
	v_mfma_f32_16x16x32_bf16 v[82:85], v[188:191], v[212:215], v[82:85]
	v_mfma_f32_16x16x32_bf16 v[86:89], v[196:199], v[212:215], v[86:89]
	v_mfma_f32_16x16x32_bf16 v[102:105], v[188:191], v[232:235], v[102:105]
	v_mfma_f32_16x16x32_bf16 v[98:101], v[196:199], v[232:235], v[98:101]
	v_mfma_f32_16x16x32_bf16 v[70:73], v[188:191], v[240:243], v[70:73]
	v_mfma_f32_16x16x32_bf16 v[66:69], v[196:199], v[240:243], v[66:69]
	s_barrier
	s_add_i32 s3, s3, 2
	s_add_u32 s36, s36, 0x100
	s_addc_u32 s37, s37, 0
	s_add_u32 s38, s38, 0x100
	s_addc_u32 s39, s39, 0
	s_cmpk_gt_u32 s3, 0x55
	s_cbranch_scc0 .LBB0_877
	s_and_b64 vcc, exec, s[24:25]
	s_cbranch_vccz .LBB0_880
	s_barrier

.LBB0_986:
	ds_read_b128 v[130:133], v172
	ds_read_b128 v[134:137], v172 offset:1024
	ds_read_b128 v[138:141], v172 offset:2048
	ds_read_b128 v[142:145], v172 offset:3072
	ds_read_b128 v[166:169], v173
	ds_read_b128 v[176:179], v173 offset:1024
	ds_read_b128 v[180:183], v173 offset:2048
	ds_read_b128 v[184:187], v173 offset:3072
	s_add_u32 s20, s52, 0xfff80080
	s_addc_u32 s21, s53, -1
	s_cmp_eq_u32 s19, 28
	s_cselect_b32 s57, s3, s21
	s_cselect_b32 s56, s14, s20
	s_cselect_b32 s55, s15, s18
	s_cselect_b32 s54, s16, s17
	v_lshl_add_u64 v[220:221], s[52:53], 0, v[156:157]
	s_add_i32 m0, s65, 0xc000
	ds_read_b128 v[188:191], v174
	ds_read_b128 v[192:195], v174 offset:1024
	ds_read_b128 v[196:199], v174 offset:2048
	ds_read_b128 v[200:203], v174 offset:3072
	ds_read_b128 v[204:207], v174 offset:4096
	ds_read_b128 v[208:211], v174 offset:5120
	ds_read_b128 v[212:215], v174 offset:6144
	ds_read_b128 v[216:219], v174 offset:7168
	global_load_lds_dwordx4 v[220:221], off
	v_lshl_add_u64 v[220:221], s[52:53], 0, v[158:159]
	s_add_i32 m0, s65, 0xe000
	s_nop 0
	global_load_lds_dwordx4 v[220:221], off
	s_waitcnt vmcnt(8)
	s_waitcnt lgkmcnt(0)
	s_waitcnt lgkmcnt(0)
	v_mfma_f32_16x16x32_bf16 v[126:129], v[130:133], v[188:191], v[126:129]
	v_mfma_f32_16x16x32_bf16 v[122:125], v[138:141], v[188:191], v[122:125]
	v_mfma_f32_16x16x32_bf16 v[110:113], v[130:133], v[196:199], v[110:113]
	v_mfma_f32_16x16x32_bf16 v[106:109], v[138:141], v[196:199], v[106:109]
	s_barrier
	v_mfma_f32_16x16x32_bf16 v[94:97], v[130:133], v[204:207], v[94:97]
	v_mfma_f32_16x16x32_bf16 v[90:93], v[138:141], v[204:207], v[90:93]
	v_mfma_f32_16x16x32_bf16 v[78:81], v[130:133], v[212:215], v[78:81]
	v_mfma_f32_16x16x32_bf16 v[74:77], v[138:141], v[212:215], v[74:77]
	v_mfma_f32_16x16x32_bf16 v[126:129], v[134:137], v[192:195], v[126:129]
	v_mfma_f32_16x16x32_bf16 v[122:125], v[142:145], v[192:195], v[122:125]
	v_mfma_f32_16x16x32_bf16 v[110:113], v[134:137], v[200:203], v[110:113]
	v_mfma_f32_16x16x32_bf16 v[106:109], v[142:145], v[200:203], v[106:109]
	v_mfma_f32_16x16x32_bf16 v[94:97], v[134:137], v[208:211], v[94:97]
	v_mfma_f32_16x16x32_bf16 v[90:93], v[142:145], v[208:211], v[90:93]
	v_mfma_f32_16x16x32_bf16 v[78:81], v[134:137], v[216:219], v[78:81]
	v_mfma_f32_16x16x32_bf16 v[74:77], v[142:145], v[216:219], v[74:77]
	v_mfma_f32_16x16x32_bf16 v[118:121], v[166:169], v[188:191], v[118:121]
	v_mfma_f32_16x16x32_bf16 v[114:117], v[180:183], v[188:191], v[114:117]
	v_mfma_f32_16x16x32_bf16 v[102:105], v[166:169], v[196:199], v[102:105]
	v_mfma_f32_16x16x32_bf16 v[98:101], v[180:183], v[196:199], v[98:101]
	v_mfma_f32_16x16x32_bf16 v[86:89], v[166:169], v[204:207], v[86:89]
	v_mfma_f32_16x16x32_bf16 v[82:85], v[180:183], v[204:207], v[82:85]
	v_mfma_f32_16x16x32_bf16 v[70:73], v[166:169], v[212:215], v[70:73]
	v_mfma_f32_16x16x32_bf16 v[66:69], v[180:183], v[212:215], v[66:69]
	v_mfma_f32_16x16x32_bf16 v[118:121], v[176:179], v[192:195], v[118:121]
	v_mfma_f32_16x16x32_bf16 v[114:117], v[184:187], v[192:195], v[114:117]
	v_mfma_f32_16x16x32_bf16 v[102:105], v[176:179], v[200:203], v[102:105]
	v_mfma_f32_16x16x32_bf16 v[98:101], v[184:187], v[200:203], v[98:101]
	v_mfma_f32_16x16x32_bf16 v[86:89], v[176:179], v[208:211], v[86:89]
	v_mfma_f32_16x16x32_bf16 v[82:85], v[184:187], v[208:211], v[82:85]
	v_mfma_f32_16x16x32_bf16 v[70:73], v[176:179], v[216:219], v[70:73]
	v_mfma_f32_16x16x32_bf16 v[66:69], v[184:187], v[216:219], v[66:69]
	s_barrier
	s_add_i32 s20, s77, s64
	v_lshl_add_u64 v[220:221], s[54:55], 0, v[146:147]
	s_mov_b32 m0, s20
	ds_read_b128 v[188:191], v174 offset:16384
	ds_read_b128 v[192:195], v174 offset:17408
	ds_read_b128 v[196:199], v174 offset:18432
	ds_read_b128 v[200:203], v174 offset:19456
	ds_read_b128 v[204:207], v174 offset:20480
	ds_read_b128 v[208:211], v174 offset:21504
	ds_read_b128 v[212:215], v174 offset:22528
	ds_read_b128 v[216:219], v174 offset:23552
	global_load_lds_dwordx4 v[220:221], off
	s_add_i32 m0, s20, 0x2000
	s_add_u32 s20, s54, 0x80000
	v_lshl_add_u64 v[222:223], s[54:55], 0, v[148:149]
	s_addc_u32 s21, s55, 0
	s_add_i32 s43, s78, s64
	global_load_lds_dwordx4 v[222:223], off
	v_lshl_add_u64 v[224:225], s[20:21], 0, v[146:147]
	s_mov_b32 m0, s43
	v_lshl_add_u64 v[226:227], s[56:57], 0, v[148:149]
	global_load_lds_dwordx4 v[224:225], off
	v_lshl_add_u64 v[224:225], s[20:21], 0, v[148:149]
	s_add_i32 m0, s43, 0x2000
	s_nop 0
	global_load_lds_dwordx4 v[224:225], off
	v_lshl_add_u64 v[224:225], s[56:57], 0, v[146:147]
	s_mov_b32 m0, s65
	s_nop 0
	global_load_lds_dwordx4 v[224:225], off
	s_mov_b32 m0, s66
	s_nop 0
	global_load_lds_dwordx4 v[226:227], off
	s_waitcnt vmcnt(8)
	s_waitcnt lgkmcnt(0)
	s_waitcnt lgkmcnt(0)
	v_mfma_f32_16x16x32_bf16 v[62:65], v[130:133], v[188:191], v[62:65]
	v_mfma_f32_16x16x32_bf16 v[58:61], v[138:141], v[188:191], v[58:61]
	v_mfma_f32_16x16x32_bf16 v[46:49], v[130:133], v[196:199], v[46:49]
	v_mfma_f32_16x16x32_bf16 v[42:45], v[138:141], v[196:199], v[42:45]
	s_barrier
	v_mfma_f32_16x16x32_bf16 v[30:33], v[130:133], v[204:207], v[30:33]
	v_mfma_f32_16x16x32_bf16 v[26:29], v[138:141], v[204:207], v[26:29]
	v_mfma_f32_16x16x32_bf16 v[14:17], v[130:133], v[212:215], v[14:17]
	v_mfma_f32_16x16x32_bf16 v[10:13], v[138:141], v[212:215], v[10:13]
	v_mfma_f32_16x16x32_bf16 v[62:65], v[134:137], v[192:195], v[62:65]
	v_mfma_f32_16x16x32_bf16 v[58:61], v[142:145], v[192:195], v[58:61]
	v_mfma_f32_16x16x32_bf16 v[46:49], v[134:137], v[200:203], v[46:49]
	v_mfma_f32_16x16x32_bf16 v[42:45], v[142:145], v[200:203], v[42:45]
	v_mfma_f32_16x16x32_bf16 v[30:33], v[134:137], v[208:211], v[30:33]
	v_mfma_f32_16x16x32_bf16 v[26:29], v[142:145], v[208:211], v[26:29]
	v_mfma_f32_16x16x32_bf16 v[14:17], v[134:137], v[216:219], v[14:17]
	v_mfma_f32_16x16x32_bf16 v[10:13], v[142:145], v[216:219], v[10:13]
	v_mfma_f32_16x16x32_bf16 v[54:57], v[166:169], v[188:191], v[54:57]
	v_mfma_f32_16x16x32_bf16 v[50:53], v[180:183], v[188:191], v[50:53]
	v_mfma_f32_16x16x32_bf16 v[38:41], v[166:169], v[196:199], v[38:41]
	v_mfma_f32_16x16x32_bf16 v[34:37], v[180:183], v[196:199], v[34:37]
	v_mfma_f32_16x16x32_bf16 v[22:25], v[166:169], v[204:207], v[22:25]
	v_mfma_f32_16x16x32_bf16 v[18:21], v[180:183], v[204:207], v[18:21]
	v_mfma_f32_16x16x32_bf16 v[6:9], v[166:169], v[212:215], v[6:9]
	v_mfma_f32_16x16x32_bf16 v[2:5], v[180:183], v[212:215], v[2:5]
	v_mfma_f32_16x16x32_bf16 v[54:57], v[176:179], v[192:195], v[54:57]
	v_mfma_f32_16x16x32_bf16 v[50:53], v[184:187], v[192:195], v[50:53]
	v_mfma_f32_16x16x32_bf16 v[38:41], v[176:179], v[200:203], v[38:41]
	v_mfma_f32_16x16x32_bf16 v[34:37], v[184:187], v[200:203], v[34:37]
	v_mfma_f32_16x16x32_bf16 v[22:25], v[176:179], v[208:211], v[22:25]
	v_mfma_f32_16x16x32_bf16 v[18:21], v[184:187], v[208:211], v[18:21]
	v_mfma_f32_16x16x32_bf16 v[6:9], v[176:179], v[216:219], v[6:9]
	v_mfma_f32_16x16x32_bf16 v[2:5], v[184:187], v[216:219], v[2:5]
	s_barrier
	s_add_i32 s43, 0, 0x18000
	s_add_i32 s45, 0, 0x1c000
	v_add_u32_e32 v142, s43, v170
	v_add_u32_e32 v184, s45, v170
	ds_read_b128 v[130:133], v142
	ds_read_b128 v[134:137], v142 offset:1024
	ds_read_b128 v[138:141], v142 offset:2048
	ds_read_b128 v[142:145], v142 offset:3072
	ds_read_b128 v[166:169], v184
	ds_read_b128 v[176:179], v184 offset:1024
	ds_read_b128 v[180:183], v184 offset:2048
	ds_read_b128 v[184:187], v184 offset:3072
	s_add_u32 s20, s56, 0x80000
	s_addc_u32 s21, s57, 0
	s_mov_b32 m0, s67
	v_lshl_add_u64 v[228:229], s[20:21], 0, v[146:147]
	ds_read_b128 v[188:191], v174 offset:32768
	ds_read_b128 v[192:195], v174 offset:33792
	ds_read_b128 v[196:199], v174 offset:34816
	ds_read_b128 v[200:203], v174 offset:35840
	ds_read_b128 v[204:207], v174 offset:36864
	ds_read_b128 v[208:211], v174 offset:37888
	ds_read_b128 v[212:215], v174 offset:38912
	ds_read_b128 v[216:219], v174 offset:39936
	global_load_lds_dwordx4 v[228:229], off
	v_lshl_add_u64 v[228:229], s[20:21], 0, v[148:149]
	s_mov_b32 m0, s68
	s_nop 0
	global_load_lds_dwordx4 v[228:229], off
	s_waitcnt vmcnt(8)
	s_waitcnt lgkmcnt(0)
	s_waitcnt lgkmcnt(0)
	v_mfma_f32_16x16x32_bf16 v[126:129], v[130:133], v[188:191], v[126:129]
	v_mfma_f32_16x16x32_bf16 v[122:125], v[138:141], v[188:191], v[122:125]
	v_mfma_f32_16x16x32_bf16 v[110:113], v[130:133], v[196:199], v[110:113]
	v_mfma_f32_16x16x32_bf16 v[106:109], v[138:141], v[196:199], v[106:109]
	s_barrier
	v_mfma_f32_16x16x32_bf16 v[94:97], v[130:133], v[204:207], v[94:97]
	v_mfma_f32_16x16x32_bf16 v[90:93], v[138:141], v[204:207], v[90:93]
	v_mfma_f32_16x16x32_bf16 v[78:81], v[130:133], v[212:215], v[78:81]
	v_mfma_f32_16x16x32_bf16 v[74:77], v[138:141], v[212:215], v[74:77]
	v_mfma_f32_16x16x32_bf16 v[126:129], v[134:137], v[192:195], v[126:129]
	v_mfma_f32_16x16x32_bf16 v[122:125], v[142:145], v[192:195], v[122:125]
	v_mfma_f32_16x16x32_bf16 v[110:113], v[134:137], v[200:203], v[110:113]
	v_mfma_f32_16x16x32_bf16 v[106:109], v[142:145], v[200:203], v[106:109]
	v_mfma_f32_16x16x32_bf16 v[94:97], v[134:137], v[208:211], v[94:97]
	v_mfma_f32_16x16x32_bf16 v[90:93], v[142:145], v[208:211], v[90:93]
	v_mfma_f32_16x16x32_bf16 v[78:81], v[134:137], v[216:219], v[78:81]
	v_mfma_f32_16x16x32_bf16 v[74:77], v[142:145], v[216:219], v[74:77]
	v_mfma_f32_16x16x32_bf16 v[118:121], v[166:169], v[188:191], v[118:121]
	v_mfma_f32_16x16x32_bf16 v[114:117], v[180:183], v[188:191], v[114:117]
	v_mfma_f32_16x16x32_bf16 v[102:105], v[166:169], v[196:199], v[102:105]
	v_mfma_f32_16x16x32_bf16 v[98:101], v[180:183], v[196:199], v[98:101]
	v_mfma_f32_16x16x32_bf16 v[86:89], v[166:169], v[204:207], v[86:89]
	v_mfma_f32_16x16x32_bf16 v[82:85], v[180:183], v[204:207], v[82:85]
	v_mfma_f32_16x16x32_bf16 v[70:73], v[166:169], v[212:215], v[70:73]
	v_mfma_f32_16x16x32_bf16 v[66:69], v[180:183], v[212:215], v[66:69]
	v_mfma_f32_16x16x32_bf16 v[118:121], v[176:179], v[192:195], v[118:121]
	v_mfma_f32_16x16x32_bf16 v[114:117], v[184:187], v[192:195], v[114:117]
	v_mfma_f32_16x16x32_bf16 v[102:105], v[176:179], v[200:203], v[102:105]
	v_mfma_f32_16x16x32_bf16 v[98:101], v[184:187], v[200:203], v[98:101]
	v_mfma_f32_16x16x32_bf16 v[86:89], v[176:179], v[208:211], v[86:89]
	v_mfma_f32_16x16x32_bf16 v[82:85], v[184:187], v[208:211], v[82:85]
	v_mfma_f32_16x16x32_bf16 v[70:73], v[176:179], v[216:219], v[70:73]
	v_mfma_f32_16x16x32_bf16 v[66:69], v[184:187], v[216:219], v[66:69]
	s_barrier
	s_add_i32 s20, s43, s64
	v_lshl_add_u64 v[220:221], v[220:221], 0, s[26:27]
	s_mov_b32 m0, s20
	ds_read_b128 v[188:191], v174 offset:49152
	ds_read_b128 v[192:195], v174 offset:50176
	ds_read_b128 v[196:199], v174 offset:51200
	ds_read_b128 v[200:203], v174 offset:52224
	ds_read_b128 v[204:207], v174 offset:53248
	ds_read_b128 v[208:211], v174 offset:54272
	ds_read_b128 v[212:215], v174 offset:55296
	ds_read_b128 v[216:219], v174 offset:56320
	global_load_lds_dwordx4 v[220:221], off
	s_add_i32 m0, s20, 0x2000
	s_add_u32 s20, s54, 0x80080
	v_lshl_add_u64 v[220:221], v[222:223], 0, s[26:27]
	s_addc_u32 s21, s55, 0
	s_add_i32 s43, s45, s64
	global_load_lds_dwordx4 v[220:221], off
	v_lshl_add_u64 v[220:221], s[20:21], 0, v[146:147]
	s_mov_b32 m0, s43
	s_nop 0
	global_load_lds_dwordx4 v[220:221], off
	v_lshl_add_u64 v[220:221], s[20:21], 0, v[148:149]
	s_add_i32 m0, s43, 0x2000
	s_nop 0
	global_load_lds_dwordx4 v[220:221], off
	v_lshl_add_u64 v[220:221], v[224:225], 0, s[26:27]
	s_mov_b32 m0, s73
	s_nop 0
	global_load_lds_dwordx4 v[220:221], off
	v_lshl_add_u64 v[220:221], v[226:227], 0, s[26:27]
	s_mov_b32 m0, s74
	s_nop 0
	global_load_lds_dwordx4 v[220:221], off
	s_waitcnt vmcnt(8)
	s_waitcnt lgkmcnt(0)
	s_waitcnt lgkmcnt(0)
	v_mfma_f32_16x16x32_bf16 v[62:65], v[130:133], v[188:191], v[62:65]
	v_mfma_f32_16x16x32_bf16 v[58:61], v[138:141], v[188:191], v[58:61]
	v_mfma_f32_16x16x32_bf16 v[46:49], v[130:133], v[196:199], v[46:49]
	v_mfma_f32_16x16x32_bf16 v[42:45], v[138:141], v[196:199], v[42:45]
	s_barrier
	v_mfma_f32_16x16x32_bf16 v[30:33], v[130:133], v[204:207], v[30:33]
	v_mfma_f32_16x16x32_bf16 v[26:29], v[138:141], v[204:207], v[26:29]
	v_mfma_f32_16x16x32_bf16 v[14:17], v[130:133], v[212:215], v[14:17]
	v_mfma_f32_16x16x32_bf16 v[10:13], v[138:141], v[212:215], v[10:13]
	v_mfma_f32_16x16x32_bf16 v[62:65], v[134:137], v[192:195], v[62:65]
	v_mfma_f32_16x16x32_bf16 v[58:61], v[142:145], v[192:195], v[58:61]
	v_mfma_f32_16x16x32_bf16 v[46:49], v[134:137], v[200:203], v[46:49]
	v_mfma_f32_16x16x32_bf16 v[42:45], v[142:145], v[200:203], v[42:45]
	v_mfma_f32_16x16x32_bf16 v[30:33], v[134:137], v[208:211], v[30:33]
	v_mfma_f32_16x16x32_bf16 v[26:29], v[142:145], v[208:211], v[26:29]
	v_mfma_f32_16x16x32_bf16 v[14:17], v[134:137], v[216:219], v[14:17]
	v_mfma_f32_16x16x32_bf16 v[10:13], v[142:145], v[216:219], v[10:13]
	v_mfma_f32_16x16x32_bf16 v[54:57], v[166:169], v[188:191], v[54:57]
	v_mfma_f32_16x16x32_bf16 v[50:53], v[180:183], v[188:191], v[50:53]
	v_mfma_f32_16x16x32_bf16 v[38:41], v[166:169], v[196:199], v[38:41]
	v_mfma_f32_16x16x32_bf16 v[34:37], v[180:183], v[196:199], v[34:37]
	v_mfma_f32_16x16x32_bf16 v[22:25], v[166:169], v[204:207], v[22:25]
	v_mfma_f32_16x16x32_bf16 v[18:21], v[180:183], v[204:207], v[18:21]
	v_mfma_f32_16x16x32_bf16 v[6:9], v[166:169], v[212:215], v[6:9]
	v_mfma_f32_16x16x32_bf16 v[2:5], v[180:183], v[212:215], v[2:5]
	v_mfma_f32_16x16x32_bf16 v[54:57], v[176:179], v[192:195], v[54:57]
	v_mfma_f32_16x16x32_bf16 v[50:53], v[184:187], v[192:195], v[50:53]
	v_mfma_f32_16x16x32_bf16 v[38:41], v[176:179], v[200:203], v[38:41]
	v_mfma_f32_16x16x32_bf16 v[34:37], v[184:187], v[200:203], v[34:37]
	v_mfma_f32_16x16x32_bf16 v[22:25], v[176:179], v[208:211], v[22:25]
	v_mfma_f32_16x16x32_bf16 v[18:21], v[184:187], v[208:211], v[18:21]
	v_mfma_f32_16x16x32_bf16 v[6:9], v[176:179], v[216:219], v[6:9]
	v_mfma_f32_16x16x32_bf16 v[2:5], v[184:187], v[216:219], v[2:5]
	s_barrier
	s_add_i32 s19, s19, 2
	s_add_u32 s52, s52, 0x100
	s_addc_u32 s53, s53, 0
	s_add_u32 s17, s17, 0x100
	s_addc_u32 s18, s18, 0
	s_cmp_gt_u32 s19, 29
	s_cbranch_scc0 .LBB0_986
	s_and_b64 vcc, exec, s[28:29]
	s_cbranch_vccnz .LBB0_991
	v_lshl_add_u32 v166, s50, 8, v163
	s_cmp_gt_i32 s10, 1
	s_mov_b64 s[50:51], -1
	s_cbranch_scc1 .LBB0_992

.LBB0_1213:
	ds_read_b128 v[130:133], v189
	ds_read_b128 v[134:137], v189 offset:1024
	ds_read_b128 v[138:141], v189 offset:2048
	ds_read_b128 v[142:145], v189 offset:3072
	ds_read_b128 v[164:167], v190
	ds_read_b128 v[168:171], v190 offset:1024
	ds_read_b128 v[172:175], v190 offset:2048
	ds_read_b128 v[194:197], v190 offset:3072
	s_add_u32 s20, s52, 0xfff80080
	s_addc_u32 s21, s53, -1
	s_cmp_eq_u32 s19, 28
	s_cselect_b32 s57, s3, s21
	s_cselect_b32 s56, s14, s20
	s_cselect_b32 s55, s15, s18
	s_cselect_b32 s54, s16, s17
	v_lshl_add_u64 v[230:231], s[52:53], 0, v[154:155]
	s_add_i32 m0, s65, 0xc000
	ds_read_b128 v[198:201], v191
	ds_read_b128 v[202:205], v191 offset:1024
	ds_read_b128 v[206:209], v191 offset:2048
	ds_read_b128 v[210:213], v191 offset:3072
	ds_read_b128 v[214:217], v191 offset:4096
	ds_read_b128 v[218:221], v191 offset:5120
	ds_read_b128 v[222:225], v191 offset:6144
	ds_read_b128 v[226:229], v191 offset:7168
	global_load_lds_dwordx4 v[230:231], off
	v_lshl_add_u64 v[230:231], s[52:53], 0, v[156:157]
	s_add_i32 m0, s65, 0xe000
	s_nop 0
	global_load_lds_dwordx4 v[230:231], off
	s_waitcnt vmcnt(8)
	s_waitcnt lgkmcnt(0)
	s_waitcnt lgkmcnt(0)
	v_mfma_f32_16x16x32_bf16 v[126:129], v[130:133], v[198:201], v[126:129]
	v_mfma_f32_16x16x32_bf16 v[122:125], v[138:141], v[198:201], v[122:125]
	v_mfma_f32_16x16x32_bf16 v[110:113], v[130:133], v[206:209], v[110:113]
	v_mfma_f32_16x16x32_bf16 v[106:109], v[138:141], v[206:209], v[106:109]
	s_barrier
	v_mfma_f32_16x16x32_bf16 v[94:97], v[130:133], v[214:217], v[94:97]
	v_mfma_f32_16x16x32_bf16 v[90:93], v[138:141], v[214:217], v[90:93]
	v_mfma_f32_16x16x32_bf16 v[78:81], v[130:133], v[222:225], v[78:81]
	v_mfma_f32_16x16x32_bf16 v[74:77], v[138:141], v[222:225], v[74:77]
	v_mfma_f32_16x16x32_bf16 v[126:129], v[134:137], v[202:205], v[126:129]
	v_mfma_f32_16x16x32_bf16 v[122:125], v[142:145], v[202:205], v[122:125]
	v_mfma_f32_16x16x32_bf16 v[110:113], v[134:137], v[210:213], v[110:113]
	v_mfma_f32_16x16x32_bf16 v[106:109], v[142:145], v[210:213], v[106:109]
	v_mfma_f32_16x16x32_bf16 v[94:97], v[134:137], v[218:221], v[94:97]
	v_mfma_f32_16x16x32_bf16 v[90:93], v[142:145], v[218:221], v[90:93]
	v_mfma_f32_16x16x32_bf16 v[78:81], v[134:137], v[226:229], v[78:81]
	v_mfma_f32_16x16x32_bf16 v[74:77], v[142:145], v[226:229], v[74:77]
	v_mfma_f32_16x16x32_bf16 v[118:121], v[164:167], v[198:201], v[118:121]
	v_mfma_f32_16x16x32_bf16 v[114:117], v[172:175], v[198:201], v[114:117]
	v_mfma_f32_16x16x32_bf16 v[102:105], v[164:167], v[206:209], v[102:105]
	v_mfma_f32_16x16x32_bf16 v[98:101], v[172:175], v[206:209], v[98:101]
	v_mfma_f32_16x16x32_bf16 v[86:89], v[164:167], v[214:217], v[86:89]
	v_mfma_f32_16x16x32_bf16 v[82:85], v[172:175], v[214:217], v[82:85]
	v_mfma_f32_16x16x32_bf16 v[70:73], v[164:167], v[222:225], v[70:73]
	v_mfma_f32_16x16x32_bf16 v[66:69], v[172:175], v[222:225], v[66:69]
	v_mfma_f32_16x16x32_bf16 v[118:121], v[168:171], v[202:205], v[118:121]
	v_mfma_f32_16x16x32_bf16 v[114:117], v[194:197], v[202:205], v[114:117]
	v_mfma_f32_16x16x32_bf16 v[102:105], v[168:171], v[210:213], v[102:105]
	v_mfma_f32_16x16x32_bf16 v[98:101], v[194:197], v[210:213], v[98:101]
	v_mfma_f32_16x16x32_bf16 v[86:89], v[168:171], v[218:221], v[86:89]
	v_mfma_f32_16x16x32_bf16 v[82:85], v[194:197], v[218:221], v[82:85]
	v_mfma_f32_16x16x32_bf16 v[70:73], v[168:171], v[226:229], v[70:73]
	v_mfma_f32_16x16x32_bf16 v[66:69], v[194:197], v[226:229], v[66:69]
	s_barrier
	s_add_i32 s20, s77, s64
	v_lshl_add_u64 v[230:231], s[54:55], 0, v[146:147]
	s_mov_b32 m0, s20
	ds_read_b128 v[198:201], v191 offset:16384
	ds_read_b128 v[202:205], v191 offset:17408
	ds_read_b128 v[206:209], v191 offset:18432
	ds_read_b128 v[210:213], v191 offset:19456
	ds_read_b128 v[214:217], v191 offset:20480
	ds_read_b128 v[218:221], v191 offset:21504
	ds_read_b128 v[222:225], v191 offset:22528
	ds_read_b128 v[226:229], v191 offset:23552
	global_load_lds_dwordx4 v[230:231], off
	s_add_i32 m0, s20, 0x2000
	s_add_u32 s20, s54, 0x80000
	v_lshl_add_u64 v[232:233], s[54:55], 0, v[148:149]
	s_addc_u32 s21, s55, 0
	s_add_i32 s43, s78, s64
	global_load_lds_dwordx4 v[232:233], off
	v_lshl_add_u64 v[234:235], s[20:21], 0, v[146:147]
	s_mov_b32 m0, s43
	v_lshl_add_u64 v[236:237], s[56:57], 0, v[148:149]
	global_load_lds_dwordx4 v[234:235], off
	v_lshl_add_u64 v[234:235], s[20:21], 0, v[148:149]
	s_add_i32 m0, s43, 0x2000
	s_nop 0
	global_load_lds_dwordx4 v[234:235], off
	v_lshl_add_u64 v[234:235], s[56:57], 0, v[146:147]
	s_mov_b32 m0, s65
	s_nop 0
	global_load_lds_dwordx4 v[234:235], off
	s_mov_b32 m0, s66
	s_nop 0
	global_load_lds_dwordx4 v[236:237], off
	s_waitcnt vmcnt(8)
	s_waitcnt lgkmcnt(0)
	s_waitcnt lgkmcnt(0)
	v_mfma_f32_16x16x32_bf16 v[62:65], v[130:133], v[198:201], v[62:65]
	v_mfma_f32_16x16x32_bf16 v[58:61], v[138:141], v[198:201], v[58:61]
	v_mfma_f32_16x16x32_bf16 v[46:49], v[130:133], v[206:209], v[46:49]
	v_mfma_f32_16x16x32_bf16 v[42:45], v[138:141], v[206:209], v[42:45]
	s_barrier
	v_mfma_f32_16x16x32_bf16 v[30:33], v[130:133], v[214:217], v[30:33]
	v_mfma_f32_16x16x32_bf16 v[26:29], v[138:141], v[214:217], v[26:29]
	v_mfma_f32_16x16x32_bf16 v[14:17], v[130:133], v[222:225], v[14:17]
	v_mfma_f32_16x16x32_bf16 v[10:13], v[138:141], v[222:225], v[10:13]
	v_mfma_f32_16x16x32_bf16 v[62:65], v[134:137], v[202:205], v[62:65]
	v_mfma_f32_16x16x32_bf16 v[58:61], v[142:145], v[202:205], v[58:61]
	v_mfma_f32_16x16x32_bf16 v[46:49], v[134:137], v[210:213], v[46:49]
	v_mfma_f32_16x16x32_bf16 v[42:45], v[142:145], v[210:213], v[42:45]
	v_mfma_f32_16x16x32_bf16 v[30:33], v[134:137], v[218:221], v[30:33]
	v_mfma_f32_16x16x32_bf16 v[26:29], v[142:145], v[218:221], v[26:29]
	v_mfma_f32_16x16x32_bf16 v[14:17], v[134:137], v[226:229], v[14:17]
	v_mfma_f32_16x16x32_bf16 v[10:13], v[142:145], v[226:229], v[10:13]
	v_mfma_f32_16x16x32_bf16 v[54:57], v[164:167], v[198:201], v[54:57]
	v_mfma_f32_16x16x32_bf16 v[50:53], v[172:175], v[198:201], v[50:53]
	v_mfma_f32_16x16x32_bf16 v[38:41], v[164:167], v[206:209], v[38:41]
	v_mfma_f32_16x16x32_bf16 v[34:37], v[172:175], v[206:209], v[34:37]
	v_mfma_f32_16x16x32_bf16 v[22:25], v[164:167], v[214:217], v[22:25]
	v_mfma_f32_16x16x32_bf16 v[18:21], v[172:175], v[214:217], v[18:21]
	v_mfma_f32_16x16x32_bf16 v[6:9], v[164:167], v[222:225], v[6:9]
	v_mfma_f32_16x16x32_bf16 v[2:5], v[172:175], v[222:225], v[2:5]
	v_mfma_f32_16x16x32_bf16 v[54:57], v[168:171], v[202:205], v[54:57]
	v_mfma_f32_16x16x32_bf16 v[50:53], v[194:197], v[202:205], v[50:53]
	v_mfma_f32_16x16x32_bf16 v[38:41], v[168:171], v[210:213], v[38:41]
	v_mfma_f32_16x16x32_bf16 v[34:37], v[194:197], v[210:213], v[34:37]
	v_mfma_f32_16x16x32_bf16 v[22:25], v[168:171], v[218:221], v[22:25]
	v_mfma_f32_16x16x32_bf16 v[18:21], v[194:197], v[218:221], v[18:21]
	v_mfma_f32_16x16x32_bf16 v[6:9], v[168:171], v[226:229], v[6:9]
	v_mfma_f32_16x16x32_bf16 v[2:5], v[194:197], v[226:229], v[2:5]
	s_barrier
	s_add_i32 s43, 0, 0x18000
	s_add_i32 s45, 0, 0x1c000
	v_add_u32_e32 v142, s43, v187
	v_add_u32_e32 v193, s45, v187
	ds_read_b128 v[130:133], v142
	ds_read_b128 v[134:137], v142 offset:1024
	ds_read_b128 v[138:141], v142 offset:2048
	ds_read_b128 v[142:145], v142 offset:3072
	ds_read_b128 v[164:167], v193
	ds_read_b128 v[168:171], v193 offset:1024
	ds_read_b128 v[172:175], v193 offset:2048
	ds_read_b128 v[194:197], v193 offset:3072
	s_add_u32 s20, s56, 0x80000
	s_addc_u32 s21, s57, 0
	s_mov_b32 m0, s67
	v_lshl_add_u64 v[238:239], s[20:21], 0, v[146:147]
	ds_read_b128 v[198:201], v191 offset:32768
	ds_read_b128 v[202:205], v191 offset:33792
	ds_read_b128 v[206:209], v191 offset:34816
	ds_read_b128 v[210:213], v191 offset:35840
	ds_read_b128 v[214:217], v191 offset:36864
	ds_read_b128 v[218:221], v191 offset:37888
	ds_read_b128 v[222:225], v191 offset:38912
	ds_read_b128 v[226:229], v191 offset:39936
	global_load_lds_dwordx4 v[238:239], off
	v_lshl_add_u64 v[238:239], s[20:21], 0, v[148:149]
	s_mov_b32 m0, s68
	s_nop 0
	global_load_lds_dwordx4 v[238:239], off
	s_waitcnt vmcnt(8)
	s_waitcnt lgkmcnt(0)
	s_waitcnt lgkmcnt(0)
	v_mfma_f32_16x16x32_bf16 v[126:129], v[130:133], v[198:201], v[126:129]
	v_mfma_f32_16x16x32_bf16 v[122:125], v[138:141], v[198:201], v[122:125]
	v_mfma_f32_16x16x32_bf16 v[110:113], v[130:133], v[206:209], v[110:113]
	v_mfma_f32_16x16x32_bf16 v[106:109], v[138:141], v[206:209], v[106:109]
	s_barrier
	v_mfma_f32_16x16x32_bf16 v[94:97], v[130:133], v[214:217], v[94:97]
	v_mfma_f32_16x16x32_bf16 v[90:93], v[138:141], v[214:217], v[90:93]
	v_mfma_f32_16x16x32_bf16 v[78:81], v[130:133], v[222:225], v[78:81]
	v_mfma_f32_16x16x32_bf16 v[74:77], v[138:141], v[222:225], v[74:77]
	v_mfma_f32_16x16x32_bf16 v[126:129], v[134:137], v[202:205], v[126:129]
	v_mfma_f32_16x16x32_bf16 v[122:125], v[142:145], v[202:205], v[122:125]
	v_mfma_f32_16x16x32_bf16 v[110:113], v[134:137], v[210:213], v[110:113]
	v_mfma_f32_16x16x32_bf16 v[106:109], v[142:145], v[210:213], v[106:109]
	v_mfma_f32_16x16x32_bf16 v[94:97], v[134:137], v[218:221], v[94:97]
	v_mfma_f32_16x16x32_bf16 v[90:93], v[142:145], v[218:221], v[90:93]
	v_mfma_f32_16x16x32_bf16 v[78:81], v[134:137], v[226:229], v[78:81]
	v_mfma_f32_16x16x32_bf16 v[74:77], v[142:145], v[226:229], v[74:77]
	v_mfma_f32_16x16x32_bf16 v[118:121], v[164:167], v[198:201], v[118:121]
	v_mfma_f32_16x16x32_bf16 v[114:117], v[172:175], v[198:201], v[114:117]
	v_mfma_f32_16x16x32_bf16 v[102:105], v[164:167], v[206:209], v[102:105]
	v_mfma_f32_16x16x32_bf16 v[98:101], v[172:175], v[206:209], v[98:101]
	v_mfma_f32_16x16x32_bf16 v[86:89], v[164:167], v[214:217], v[86:89]
	v_mfma_f32_16x16x32_bf16 v[82:85], v[172:175], v[214:217], v[82:85]
	v_mfma_f32_16x16x32_bf16 v[70:73], v[164:167], v[222:225], v[70:73]
	v_mfma_f32_16x16x32_bf16 v[66:69], v[172:175], v[222:225], v[66:69]
	v_mfma_f32_16x16x32_bf16 v[118:121], v[168:171], v[202:205], v[118:121]
	v_mfma_f32_16x16x32_bf16 v[114:117], v[194:197], v[202:205], v[114:117]
	v_mfma_f32_16x16x32_bf16 v[102:105], v[168:171], v[210:213], v[102:105]
	v_mfma_f32_16x16x32_bf16 v[98:101], v[194:197], v[210:213], v[98:101]
	v_mfma_f32_16x16x32_bf16 v[86:89], v[168:171], v[218:221], v[86:89]
	v_mfma_f32_16x16x32_bf16 v[82:85], v[194:197], v[218:221], v[82:85]
	v_mfma_f32_16x16x32_bf16 v[70:73], v[168:171], v[226:229], v[70:73]
	v_mfma_f32_16x16x32_bf16 v[66:69], v[194:197], v[226:229], v[66:69]
	s_barrier
	s_add_i32 s20, s43, s64
	v_lshl_add_u64 v[230:231], v[230:231], 0, s[26:27]
	s_mov_b32 m0, s20
	ds_read_b128 v[198:201], v191 offset:49152
	ds_read_b128 v[202:205], v191 offset:50176
	ds_read_b128 v[206:209], v191 offset:51200
	ds_read_b128 v[210:213], v191 offset:52224
	ds_read_b128 v[214:217], v191 offset:53248
	ds_read_b128 v[218:221], v191 offset:54272
	ds_read_b128 v[222:225], v191 offset:55296
	ds_read_b128 v[226:229], v191 offset:56320
	global_load_lds_dwordx4 v[230:231], off
	s_add_i32 m0, s20, 0x2000
	s_add_u32 s20, s54, 0x80080
	v_lshl_add_u64 v[230:231], v[232:233], 0, s[26:27]
	s_addc_u32 s21, s55, 0
	s_add_i32 s43, s45, s64
	global_load_lds_dwordx4 v[230:231], off
	v_lshl_add_u64 v[230:231], s[20:21], 0, v[146:147]
	s_mov_b32 m0, s43
	s_nop 0
	global_load_lds_dwordx4 v[230:231], off
	v_lshl_add_u64 v[230:231], s[20:21], 0, v[148:149]
	s_add_i32 m0, s43, 0x2000
	s_nop 0
	global_load_lds_dwordx4 v[230:231], off
	v_lshl_add_u64 v[230:231], v[234:235], 0, s[26:27]
	s_mov_b32 m0, s73
	s_nop 0
	global_load_lds_dwordx4 v[230:231], off
	v_lshl_add_u64 v[230:231], v[236:237], 0, s[26:27]
	s_mov_b32 m0, s74
	s_nop 0
	global_load_lds_dwordx4 v[230:231], off
	s_waitcnt vmcnt(8)
	s_waitcnt lgkmcnt(0)
	s_waitcnt lgkmcnt(0)
	v_mfma_f32_16x16x32_bf16 v[62:65], v[130:133], v[198:201], v[62:65]
	v_mfma_f32_16x16x32_bf16 v[58:61], v[138:141], v[198:201], v[58:61]
	v_mfma_f32_16x16x32_bf16 v[46:49], v[130:133], v[206:209], v[46:49]
	v_mfma_f32_16x16x32_bf16 v[42:45], v[138:141], v[206:209], v[42:45]
	s_barrier
	v_mfma_f32_16x16x32_bf16 v[30:33], v[130:133], v[214:217], v[30:33]
	v_mfma_f32_16x16x32_bf16 v[26:29], v[138:141], v[214:217], v[26:29]
	v_mfma_f32_16x16x32_bf16 v[14:17], v[130:133], v[222:225], v[14:17]
	v_mfma_f32_16x16x32_bf16 v[10:13], v[138:141], v[222:225], v[10:13]
	v_mfma_f32_16x16x32_bf16 v[62:65], v[134:137], v[202:205], v[62:65]
	v_mfma_f32_16x16x32_bf16 v[58:61], v[142:145], v[202:205], v[58:61]
	v_mfma_f32_16x16x32_bf16 v[46:49], v[134:137], v[210:213], v[46:49]
	v_mfma_f32_16x16x32_bf16 v[42:45], v[142:145], v[210:213], v[42:45]
	v_mfma_f32_16x16x32_bf16 v[30:33], v[134:137], v[218:221], v[30:33]
	v_mfma_f32_16x16x32_bf16 v[26:29], v[142:145], v[218:221], v[26:29]
	v_mfma_f32_16x16x32_bf16 v[14:17], v[134:137], v[226:229], v[14:17]
	v_mfma_f32_16x16x32_bf16 v[10:13], v[142:145], v[226:229], v[10:13]
	v_mfma_f32_16x16x32_bf16 v[54:57], v[164:167], v[198:201], v[54:57]
	v_mfma_f32_16x16x32_bf16 v[50:53], v[172:175], v[198:201], v[50:53]
	v_mfma_f32_16x16x32_bf16 v[38:41], v[164:167], v[206:209], v[38:41]
	v_mfma_f32_16x16x32_bf16 v[34:37], v[172:175], v[206:209], v[34:37]
	v_mfma_f32_16x16x32_bf16 v[22:25], v[164:167], v[214:217], v[22:25]
	v_mfma_f32_16x16x32_bf16 v[18:21], v[172:175], v[214:217], v[18:21]
	v_mfma_f32_16x16x32_bf16 v[6:9], v[164:167], v[222:225], v[6:9]
	v_mfma_f32_16x16x32_bf16 v[2:5], v[172:175], v[222:225], v[2:5]
	v_mfma_f32_16x16x32_bf16 v[54:57], v[168:171], v[202:205], v[54:57]
	v_mfma_f32_16x16x32_bf16 v[50:53], v[194:197], v[202:205], v[50:53]
	v_mfma_f32_16x16x32_bf16 v[38:41], v[168:171], v[210:213], v[38:41]
	v_mfma_f32_16x16x32_bf16 v[34:37], v[194:197], v[210:213], v[34:37]
	v_mfma_f32_16x16x32_bf16 v[22:25], v[168:171], v[218:221], v[22:25]
	v_mfma_f32_16x16x32_bf16 v[18:21], v[194:197], v[218:221], v[18:21]
	v_mfma_f32_16x16x32_bf16 v[6:9], v[168:171], v[226:229], v[6:9]
	v_mfma_f32_16x16x32_bf16 v[2:5], v[194:197], v[226:229], v[2:5]
	s_barrier
	s_add_i32 s19, s19, 2
	s_add_u32 s52, s52, 0x100
	s_addc_u32 s53, s53, 0
	s_add_u32 s17, s17, 0x100
	s_addc_u32 s18, s18, 0
	s_cmp_gt_u32 s19, 29
	s_cbranch_scc0 .LBB0_1213
	s_and_b64 vcc, exec, s[28:29]
	s_cbranch_vccnz .LBB0_1218
	v_lshl_add_u32 v164, s50, 8, v186
	s_cmp_gt_i32 s10, 1
	s_mov_b64 s[50:51], -1
	s_cbranch_scc1 .LBB0_1219

.LBB0_1264:
	ds_read_b128 v[142:145], v163
	ds_read_b128 v[146:149], v163 offset:1024
	ds_read_b128 v[150:153], v163 offset:2048
	ds_read_b128 v[154:157], v163 offset:3072
	ds_read_b128 v[170:173], v166
	ds_read_b128 v[174:177], v166 offset:1024
	ds_read_b128 v[178:181], v166 offset:2048
	ds_read_b128 v[182:185], v166 offset:3072
	s_add_u32 s44, s42, 0xfffe0080
	s_addc_u32 s45, s43, -1
	s_cmp_eq_u32 s29, 4
	s_cselect_b32 s47, s3, s45
	s_cselect_b32 s46, s16, s44
	s_cselect_b32 s45, s17, s27
	s_cselect_b32 s44, s18, s19
	v_lshl_add_u64 v[218:219], s[42:43], 0, v[138:139]
	s_add_i32 m0, s39, 0xc000
	ds_read_b128 v[186:189], v167
	ds_read_b128 v[190:193], v167 offset:1024
	ds_read_b128 v[194:197], v167 offset:2048
	ds_read_b128 v[198:201], v167 offset:3072
	ds_read_b128 v[202:205], v167 offset:4096
	ds_read_b128 v[206:209], v167 offset:5120
	ds_read_b128 v[210:213], v167 offset:6144
	ds_read_b128 v[214:217], v167 offset:7168
	global_load_lds_dwordx4 v[218:219], off
	v_lshl_add_u64 v[218:219], s[42:43], 0, v[140:141]
	s_add_i32 m0, s39, 0xe000
	s_nop 0
	global_load_lds_dwordx4 v[218:219], off
	s_waitcnt vmcnt(8)
	s_waitcnt lgkmcnt(0)
	s_waitcnt lgkmcnt(0)
	v_mfma_f32_16x16x32_bf16 v[126:129], v[142:145], v[186:189], v[126:129]
	v_mfma_f32_16x16x32_bf16 v[122:125], v[150:153], v[186:189], v[122:125]
	v_mfma_f32_16x16x32_bf16 v[118:121], v[142:145], v[194:197], v[118:121]
	v_mfma_f32_16x16x32_bf16 v[110:113], v[150:153], v[194:197], v[110:113]
	s_barrier
	v_mfma_f32_16x16x32_bf16 v[102:105], v[142:145], v[202:205], v[102:105]
	v_mfma_f32_16x16x32_bf16 v[94:97], v[150:153], v[202:205], v[94:97]
	v_mfma_f32_16x16x32_bf16 v[86:89], v[142:145], v[210:213], v[86:89]
	v_mfma_f32_16x16x32_bf16 v[78:81], v[150:153], v[210:213], v[78:81]
	v_mfma_f32_16x16x32_bf16 v[126:129], v[146:149], v[190:193], v[126:129]
	v_mfma_f32_16x16x32_bf16 v[122:125], v[154:157], v[190:193], v[122:125]
	v_mfma_f32_16x16x32_bf16 v[118:121], v[146:149], v[198:201], v[118:121]
	v_mfma_f32_16x16x32_bf16 v[110:113], v[154:157], v[198:201], v[110:113]
	v_mfma_f32_16x16x32_bf16 v[102:105], v[146:149], v[206:209], v[102:105]
	v_mfma_f32_16x16x32_bf16 v[94:97], v[154:157], v[206:209], v[94:97]
	v_mfma_f32_16x16x32_bf16 v[86:89], v[146:149], v[214:217], v[86:89]
	v_mfma_f32_16x16x32_bf16 v[78:81], v[154:157], v[214:217], v[78:81]
	v_mfma_f32_16x16x32_bf16 v[114:117], v[170:173], v[186:189], v[114:117]
	v_mfma_f32_16x16x32_bf16 v[106:109], v[178:181], v[186:189], v[106:109]
	v_mfma_f32_16x16x32_bf16 v[98:101], v[170:173], v[194:197], v[98:101]
	v_mfma_f32_16x16x32_bf16 v[90:93], v[178:181], v[194:197], v[90:93]
	v_mfma_f32_16x16x32_bf16 v[82:85], v[170:173], v[202:205], v[82:85]
	v_mfma_f32_16x16x32_bf16 v[74:77], v[178:181], v[202:205], v[74:77]
	v_mfma_f32_16x16x32_bf16 v[70:73], v[170:173], v[210:213], v[70:73]
	v_mfma_f32_16x16x32_bf16 v[66:69], v[178:181], v[210:213], v[66:69]
	v_mfma_f32_16x16x32_bf16 v[114:117], v[174:177], v[190:193], v[114:117]
	v_mfma_f32_16x16x32_bf16 v[106:109], v[182:185], v[190:193], v[106:109]
	v_mfma_f32_16x16x32_bf16 v[98:101], v[174:177], v[198:201], v[98:101]
	v_mfma_f32_16x16x32_bf16 v[90:93], v[182:185], v[198:201], v[90:93]
	v_mfma_f32_16x16x32_bf16 v[82:85], v[174:177], v[206:209], v[82:85]
	v_mfma_f32_16x16x32_bf16 v[74:77], v[182:185], v[206:209], v[74:77]
	v_mfma_f32_16x16x32_bf16 v[70:73], v[174:177], v[214:217], v[70:73]
	v_mfma_f32_16x16x32_bf16 v[66:69], v[182:185], v[214:217], v[66:69]
	s_barrier
	s_add_i32 s62, s60, s54
	v_lshl_add_u64 v[218:219], s[44:45], 0, v[132:133]
	s_mov_b32 m0, s62
	ds_read_b128 v[186:189], v167 offset:16384
	ds_read_b128 v[190:193], v167 offset:17408
	ds_read_b128 v[194:197], v167 offset:18432
	ds_read_b128 v[198:201], v167 offset:19456
	ds_read_b128 v[202:205], v167 offset:20480
	ds_read_b128 v[206:209], v167 offset:21504
	ds_read_b128 v[210:213], v167 offset:22528
	ds_read_b128 v[214:217], v167 offset:23552
	global_load_lds_dwordx4 v[218:219], off
	s_add_i32 m0, s62, 0x2000
	s_add_u32 s62, s44, 0x20000
	v_lshl_add_u64 v[220:221], s[44:45], 0, v[136:137]
	s_addc_u32 s63, s45, 0
	s_add_i32 s64, s61, s54
	global_load_lds_dwordx4 v[220:221], off
	v_lshl_add_u64 v[222:223], s[62:63], 0, v[132:133]
	s_mov_b32 m0, s64
	v_lshl_add_u64 v[224:225], s[46:47], 0, v[134:135]
	global_load_lds_dwordx4 v[222:223], off
	v_lshl_add_u64 v[222:223], s[62:63], 0, v[136:137]
	s_add_i32 m0, s64, 0x2000
	s_nop 0
	global_load_lds_dwordx4 v[222:223], off
	v_lshl_add_u64 v[222:223], s[46:47], 0, v[130:131]
	s_mov_b32 m0, s39
	s_nop 0
	global_load_lds_dwordx4 v[222:223], off
	s_mov_b32 m0, s41
	s_nop 0
	global_load_lds_dwordx4 v[224:225], off
	s_waitcnt vmcnt(8)
	s_waitcnt lgkmcnt(0)
	s_waitcnt lgkmcnt(0)
	v_mfma_f32_16x16x32_bf16 v[62:65], v[142:145], v[186:189], v[62:65]
	v_mfma_f32_16x16x32_bf16 v[58:61], v[150:153], v[186:189], v[58:61]
	v_mfma_f32_16x16x32_bf16 v[54:57], v[142:145], v[194:197], v[54:57]
	v_mfma_f32_16x16x32_bf16 v[46:49], v[150:153], v[194:197], v[46:49]
	s_barrier
	v_mfma_f32_16x16x32_bf16 v[38:41], v[142:145], v[202:205], v[38:41]
	v_mfma_f32_16x16x32_bf16 v[30:33], v[150:153], v[202:205], v[30:33]
	v_mfma_f32_16x16x32_bf16 v[22:25], v[142:145], v[210:213], v[22:25]
	v_mfma_f32_16x16x32_bf16 v[14:17], v[150:153], v[210:213], v[14:17]
	v_mfma_f32_16x16x32_bf16 v[62:65], v[146:149], v[190:193], v[62:65]
	v_mfma_f32_16x16x32_bf16 v[58:61], v[154:157], v[190:193], v[58:61]
	v_mfma_f32_16x16x32_bf16 v[54:57], v[146:149], v[198:201], v[54:57]
	v_mfma_f32_16x16x32_bf16 v[46:49], v[154:157], v[198:201], v[46:49]
	v_mfma_f32_16x16x32_bf16 v[38:41], v[146:149], v[206:209], v[38:41]
	v_mfma_f32_16x16x32_bf16 v[30:33], v[154:157], v[206:209], v[30:33]
	v_mfma_f32_16x16x32_bf16 v[22:25], v[146:149], v[214:217], v[22:25]
	v_mfma_f32_16x16x32_bf16 v[14:17], v[154:157], v[214:217], v[14:17]
	v_mfma_f32_16x16x32_bf16 v[50:53], v[170:173], v[186:189], v[50:53]
	v_mfma_f32_16x16x32_bf16 v[42:45], v[178:181], v[186:189], v[42:45]
	v_mfma_f32_16x16x32_bf16 v[34:37], v[170:173], v[194:197], v[34:37]
	v_mfma_f32_16x16x32_bf16 v[26:29], v[178:181], v[194:197], v[26:29]
	v_mfma_f32_16x16x32_bf16 v[18:21], v[170:173], v[202:205], v[18:21]
	v_mfma_f32_16x16x32_bf16 v[10:13], v[178:181], v[202:205], v[10:13]
	v_mfma_f32_16x16x32_bf16 v[6:9], v[170:173], v[210:213], v[6:9]
	v_mfma_f32_16x16x32_bf16 v[2:5], v[178:181], v[210:213], v[2:5]
	v_mfma_f32_16x16x32_bf16 v[50:53], v[174:177], v[190:193], v[50:53]
	v_mfma_f32_16x16x32_bf16 v[42:45], v[182:185], v[190:193], v[42:45]
	v_mfma_f32_16x16x32_bf16 v[34:37], v[174:177], v[198:201], v[34:37]
	v_mfma_f32_16x16x32_bf16 v[26:29], v[182:185], v[198:201], v[26:29]
	v_mfma_f32_16x16x32_bf16 v[18:21], v[174:177], v[206:209], v[18:21]
	v_mfma_f32_16x16x32_bf16 v[10:13], v[182:185], v[206:209], v[10:13]
	v_mfma_f32_16x16x32_bf16 v[6:9], v[174:177], v[214:217], v[6:9]
	v_mfma_f32_16x16x32_bf16 v[2:5], v[182:185], v[214:217], v[2:5]
	s_barrier
	s_add_i32 s62, 0, 0x18000
	s_add_i32 s63, 0, 0x1c000
	v_add_u32_e32 v154, s62, v161
	v_add_u32_e32 v158, s63, v161
	ds_read_b128 v[142:145], v154
	ds_read_b128 v[146:149], v154 offset:1024
	ds_read_b128 v[150:153], v154 offset:2048
	ds_read_b128 v[154:157], v154 offset:3072
	ds_read_b128 v[170:173], v158
	ds_read_b128 v[174:177], v158 offset:1024
	ds_read_b128 v[178:181], v158 offset:2048
	ds_read_b128 v[182:185], v158 offset:3072
	s_add_u32 s46, s46, 0x20000
	s_addc_u32 s47, s47, 0
	s_mov_b32 m0, s55
	v_lshl_add_u64 v[226:227], s[46:47], 0, v[130:131]
	ds_read_b128 v[186:189], v167 offset:32768
	ds_read_b128 v[190:193], v167 offset:33792
	ds_read_b128 v[194:197], v167 offset:34816
	ds_read_b128 v[198:201], v167 offset:35840
	ds_read_b128 v[202:205], v167 offset:36864
	ds_read_b128 v[206:209], v167 offset:37888
	ds_read_b128 v[210:213], v167 offset:38912
	ds_read_b128 v[214:217], v167 offset:39936
	global_load_lds_dwordx4 v[226:227], off
	v_lshl_add_u64 v[226:227], s[46:47], 0, v[134:135]
	s_mov_b32 m0, s56
	s_nop 0
	global_load_lds_dwordx4 v[226:227], off
	s_waitcnt vmcnt(8)
	s_waitcnt lgkmcnt(0)
	s_waitcnt lgkmcnt(0)
	v_mfma_f32_16x16x32_bf16 v[126:129], v[142:145], v[186:189], v[126:129]
	v_mfma_f32_16x16x32_bf16 v[122:125], v[150:153], v[186:189], v[122:125]
	v_mfma_f32_16x16x32_bf16 v[118:121], v[142:145], v[194:197], v[118:121]
	v_mfma_f32_16x16x32_bf16 v[110:113], v[150:153], v[194:197], v[110:113]
	s_barrier
	v_mfma_f32_16x16x32_bf16 v[102:105], v[142:145], v[202:205], v[102:105]
	v_mfma_f32_16x16x32_bf16 v[94:97], v[150:153], v[202:205], v[94:97]
	v_mfma_f32_16x16x32_bf16 v[86:89], v[142:145], v[210:213], v[86:89]
	v_mfma_f32_16x16x32_bf16 v[78:81], v[150:153], v[210:213], v[78:81]
	v_mfma_f32_16x16x32_bf16 v[126:129], v[146:149], v[190:193], v[126:129]
	v_mfma_f32_16x16x32_bf16 v[122:125], v[154:157], v[190:193], v[122:125]
	v_mfma_f32_16x16x32_bf16 v[118:121], v[146:149], v[198:201], v[118:121]
	v_mfma_f32_16x16x32_bf16 v[110:113], v[154:157], v[198:201], v[110:113]
	v_mfma_f32_16x16x32_bf16 v[102:105], v[146:149], v[206:209], v[102:105]
	v_mfma_f32_16x16x32_bf16 v[94:97], v[154:157], v[206:209], v[94:97]
	v_mfma_f32_16x16x32_bf16 v[86:89], v[146:149], v[214:217], v[86:89]
	v_mfma_f32_16x16x32_bf16 v[78:81], v[154:157], v[214:217], v[78:81]
	v_mfma_f32_16x16x32_bf16 v[114:117], v[170:173], v[186:189], v[114:117]
	v_mfma_f32_16x16x32_bf16 v[106:109], v[178:181], v[186:189], v[106:109]
	v_mfma_f32_16x16x32_bf16 v[98:101], v[170:173], v[194:197], v[98:101]
	v_mfma_f32_16x16x32_bf16 v[90:93], v[178:181], v[194:197], v[90:93]
	v_mfma_f32_16x16x32_bf16 v[82:85], v[170:173], v[202:205], v[82:85]
	v_mfma_f32_16x16x32_bf16 v[74:77], v[178:181], v[202:205], v[74:77]
	v_mfma_f32_16x16x32_bf16 v[70:73], v[170:173], v[210:213], v[70:73]
	v_mfma_f32_16x16x32_bf16 v[66:69], v[178:181], v[210:213], v[66:69]
	v_mfma_f32_16x16x32_bf16 v[114:117], v[174:177], v[190:193], v[114:117]
	v_mfma_f32_16x16x32_bf16 v[106:109], v[182:185], v[190:193], v[106:109]
	v_mfma_f32_16x16x32_bf16 v[98:101], v[174:177], v[198:201], v[98:101]
	v_mfma_f32_16x16x32_bf16 v[90:93], v[182:185], v[198:201], v[90:93]
	v_mfma_f32_16x16x32_bf16 v[82:85], v[174:177], v[206:209], v[82:85]
	v_mfma_f32_16x16x32_bf16 v[74:77], v[182:185], v[206:209], v[74:77]
	v_mfma_f32_16x16x32_bf16 v[70:73], v[174:177], v[214:217], v[70:73]
	v_mfma_f32_16x16x32_bf16 v[66:69], v[182:185], v[214:217], v[66:69]
	s_barrier
	s_add_i32 s46, s62, s54
	v_lshl_add_u64 v[218:219], v[218:219], 0, s[22:23]
	s_mov_b32 m0, s46
	ds_read_b128 v[186:189], v167 offset:49152
	ds_read_b128 v[190:193], v167 offset:50176
	ds_read_b128 v[194:197], v167 offset:51200
	ds_read_b128 v[198:201], v167 offset:52224
	ds_read_b128 v[202:205], v167 offset:53248
	ds_read_b128 v[206:209], v167 offset:54272
	ds_read_b128 v[210:213], v167 offset:55296
	ds_read_b128 v[214:217], v167 offset:56320
	global_load_lds_dwordx4 v[218:219], off
	s_add_i32 m0, s46, 0x2000
	s_add_u32 s44, s44, 0x20080
	v_lshl_add_u64 v[218:219], v[220:221], 0, s[22:23]
	s_addc_u32 s45, s45, 0
	s_add_i32 s46, s63, s54
	global_load_lds_dwordx4 v[218:219], off
	v_lshl_add_u64 v[218:219], s[44:45], 0, v[132:133]
	s_mov_b32 m0, s46
	s_nop 0
	global_load_lds_dwordx4 v[218:219], off
	v_lshl_add_u64 v[218:219], s[44:45], 0, v[136:137]
	s_add_i32 m0, s46, 0x2000
	s_nop 0
	global_load_lds_dwordx4 v[218:219], off
	v_lshl_add_u64 v[218:219], v[222:223], 0, s[22:23]
	s_mov_b32 m0, s14
	s_nop 0
	global_load_lds_dwordx4 v[218:219], off
	v_lshl_add_u64 v[218:219], v[224:225], 0, s[22:23]
	s_mov_b32 m0, s15
	s_nop 0
	global_load_lds_dwordx4 v[218:219], off
	s_waitcnt vmcnt(8)
	s_waitcnt lgkmcnt(0)
	s_waitcnt lgkmcnt(0)
	v_mfma_f32_16x16x32_bf16 v[62:65], v[142:145], v[186:189], v[62:65]
	v_mfma_f32_16x16x32_bf16 v[58:61], v[150:153], v[186:189], v[58:61]
	v_mfma_f32_16x16x32_bf16 v[54:57], v[142:145], v[194:197], v[54:57]
	v_mfma_f32_16x16x32_bf16 v[46:49], v[150:153], v[194:197], v[46:49]
	s_barrier
	v_mfma_f32_16x16x32_bf16 v[38:41], v[142:145], v[202:205], v[38:41]
	v_mfma_f32_16x16x32_bf16 v[30:33], v[150:153], v[202:205], v[30:33]
	v_mfma_f32_16x16x32_bf16 v[22:25], v[142:145], v[210:213], v[22:25]
	v_mfma_f32_16x16x32_bf16 v[14:17], v[150:153], v[210:213], v[14:17]
	v_mfma_f32_16x16x32_bf16 v[62:65], v[146:149], v[190:193], v[62:65]
	v_mfma_f32_16x16x32_bf16 v[58:61], v[154:157], v[190:193], v[58:61]
	v_mfma_f32_16x16x32_bf16 v[54:57], v[146:149], v[198:201], v[54:57]
	v_mfma_f32_16x16x32_bf16 v[46:49], v[154:157], v[198:201], v[46:49]
	v_mfma_f32_16x16x32_bf16 v[38:41], v[146:149], v[206:209], v[38:41]
	v_mfma_f32_16x16x32_bf16 v[30:33], v[154:157], v[206:209], v[30:33]
	v_mfma_f32_16x16x32_bf16 v[22:25], v[146:149], v[214:217], v[22:25]
	v_mfma_f32_16x16x32_bf16 v[14:17], v[154:157], v[214:217], v[14:17]
	v_mfma_f32_16x16x32_bf16 v[50:53], v[170:173], v[186:189], v[50:53]
	v_mfma_f32_16x16x32_bf16 v[42:45], v[178:181], v[186:189], v[42:45]
	v_mfma_f32_16x16x32_bf16 v[34:37], v[170:173], v[194:197], v[34:37]
	v_mfma_f32_16x16x32_bf16 v[26:29], v[178:181], v[194:197], v[26:29]
	v_mfma_f32_16x16x32_bf16 v[18:21], v[170:173], v[202:205], v[18:21]
	v_mfma_f32_16x16x32_bf16 v[10:13], v[178:181], v[202:205], v[10:13]
	v_mfma_f32_16x16x32_bf16 v[6:9], v[170:173], v[210:213], v[6:9]
	v_mfma_f32_16x16x32_bf16 v[2:5], v[178:181], v[210:213], v[2:5]
	v_mfma_f32_16x16x32_bf16 v[50:53], v[174:177], v[190:193], v[50:53]
	v_mfma_f32_16x16x32_bf16 v[42:45], v[182:185], v[190:193], v[42:45]
	v_mfma_f32_16x16x32_bf16 v[34:37], v[174:177], v[198:201], v[34:37]
	v_mfma_f32_16x16x32_bf16 v[26:29], v[182:185], v[198:201], v[26:29]
	v_mfma_f32_16x16x32_bf16 v[18:21], v[174:177], v[206:209], v[18:21]
	v_mfma_f32_16x16x32_bf16 v[10:13], v[182:185], v[206:209], v[10:13]
	v_mfma_f32_16x16x32_bf16 v[6:9], v[174:177], v[214:217], v[6:9]
	v_mfma_f32_16x16x32_bf16 v[2:5], v[182:185], v[214:217], v[2:5]
	s_barrier
	s_add_i32 s29, s29, 2
	s_add_u32 s42, s42, 0x100
	s_addc_u32 s43, s43, 0
	s_add_u32 s19, s19, 0x100
	s_addc_u32 s27, s27, 0
	s_cmp_gt_u32 s29, 5
	s_cbranch_scc0 .LBB0_1264
	s_and_b64 vcc, exec, s[24:25]
	s_cbranch_vccz .LBB0_1267
	s_barrier

.LBB0_1336:
	ds_read_b128 v[154:157], v175
	ds_read_b128 v[158:161], v175 offset:1024
	ds_read_b128 v[164:167], v175 offset:2048
	ds_read_b128 v[168:171], v175 offset:3072
	ds_read_b128 v[180:183], v176
	ds_read_b128 v[184:187], v176 offset:1024
	ds_read_b128 v[188:191], v176 offset:2048
	ds_read_b128 v[192:195], v176 offset:3072
	s_add_u32 s20, s36, 0xfffe0080
	s_addc_u32 s21, s37, -1
	s_cmp_eq_u32 s19, 4
	s_cselect_b32 s41, s3, s21
	s_cselect_b32 s40, s14, s20
	s_cselect_b32 s39, s15, s18
	s_cselect_b32 s38, s16, s17
	v_lshl_add_u64 v[228:229], s[36:37], 0, v[144:145]
	s_add_i32 m0, s49, 0xc000
	ds_read_b128 v[196:199], v177
	ds_read_b128 v[200:203], v177 offset:1024
	ds_read_b128 v[204:207], v177 offset:2048
	ds_read_b128 v[208:211], v177 offset:3072
	ds_read_b128 v[212:215], v177 offset:4096
	ds_read_b128 v[216:219], v177 offset:5120
	ds_read_b128 v[220:223], v177 offset:6144
	ds_read_b128 v[224:227], v177 offset:7168
	global_load_lds_dwordx4 v[228:229], off
	v_lshl_add_u64 v[228:229], s[36:37], 0, v[146:147]
	s_add_i32 m0, s49, 0xe000
	s_nop 0
	global_load_lds_dwordx4 v[228:229], off
	s_waitcnt vmcnt(8)
	s_waitcnt lgkmcnt(0)
	s_waitcnt lgkmcnt(0)
	v_mfma_f32_16x16x32_bf16 v[126:129], v[154:157], v[196:199], v[126:129]
	v_mfma_f32_16x16x32_bf16 v[122:125], v[164:167], v[196:199], v[122:125]
	v_mfma_f32_16x16x32_bf16 v[118:121], v[154:157], v[204:207], v[118:121]
	v_mfma_f32_16x16x32_bf16 v[110:113], v[164:167], v[204:207], v[110:113]
	s_barrier
	v_mfma_f32_16x16x32_bf16 v[102:105], v[154:157], v[212:215], v[102:105]
	v_mfma_f32_16x16x32_bf16 v[94:97], v[164:167], v[212:215], v[94:97]
	v_mfma_f32_16x16x32_bf16 v[86:89], v[154:157], v[220:223], v[86:89]
	v_mfma_f32_16x16x32_bf16 v[78:81], v[164:167], v[220:223], v[78:81]
	v_mfma_f32_16x16x32_bf16 v[126:129], v[158:161], v[200:203], v[126:129]
	v_mfma_f32_16x16x32_bf16 v[122:125], v[168:171], v[200:203], v[122:125]
	v_mfma_f32_16x16x32_bf16 v[118:121], v[158:161], v[208:211], v[118:121]
	v_mfma_f32_16x16x32_bf16 v[110:113], v[168:171], v[208:211], v[110:113]
	v_mfma_f32_16x16x32_bf16 v[102:105], v[158:161], v[216:219], v[102:105]
	v_mfma_f32_16x16x32_bf16 v[94:97], v[168:171], v[216:219], v[94:97]
	v_mfma_f32_16x16x32_bf16 v[86:89], v[158:161], v[224:227], v[86:89]
	v_mfma_f32_16x16x32_bf16 v[78:81], v[168:171], v[224:227], v[78:81]
	v_mfma_f32_16x16x32_bf16 v[114:117], v[180:183], v[196:199], v[114:117]
	v_mfma_f32_16x16x32_bf16 v[106:109], v[188:191], v[196:199], v[106:109]
	v_mfma_f32_16x16x32_bf16 v[98:101], v[180:183], v[204:207], v[98:101]
	v_mfma_f32_16x16x32_bf16 v[90:93], v[188:191], v[204:207], v[90:93]
	v_mfma_f32_16x16x32_bf16 v[82:85], v[180:183], v[212:215], v[82:85]
	v_mfma_f32_16x16x32_bf16 v[74:77], v[188:191], v[212:215], v[74:77]
	v_mfma_f32_16x16x32_bf16 v[70:73], v[180:183], v[220:223], v[70:73]
	v_mfma_f32_16x16x32_bf16 v[66:69], v[188:191], v[220:223], v[66:69]
	v_mfma_f32_16x16x32_bf16 v[114:117], v[184:187], v[200:203], v[114:117]
	v_mfma_f32_16x16x32_bf16 v[106:109], v[192:195], v[200:203], v[106:109]
	v_mfma_f32_16x16x32_bf16 v[98:101], v[184:187], v[208:211], v[98:101]
	v_mfma_f32_16x16x32_bf16 v[90:93], v[192:195], v[208:211], v[90:93]
	v_mfma_f32_16x16x32_bf16 v[82:85], v[184:187], v[216:219], v[82:85]
	v_mfma_f32_16x16x32_bf16 v[74:77], v[192:195], v[216:219], v[74:77]
	v_mfma_f32_16x16x32_bf16 v[70:73], v[184:187], v[224:227], v[70:73]
	v_mfma_f32_16x16x32_bf16 v[66:69], v[192:195], v[224:227], v[66:69]
	s_barrier
	s_add_i32 s20, s57, s46
	v_lshl_add_u64 v[228:229], s[38:39], 0, v[134:135]
	s_mov_b32 m0, s20
	ds_read_b128 v[196:199], v177 offset:16384
	ds_read_b128 v[200:203], v177 offset:17408
	ds_read_b128 v[204:207], v177 offset:18432
	ds_read_b128 v[208:211], v177 offset:19456
	ds_read_b128 v[212:215], v177 offset:20480
	ds_read_b128 v[216:219], v177 offset:21504
	ds_read_b128 v[220:223], v177 offset:22528
	ds_read_b128 v[224:227], v177 offset:23552
	global_load_lds_dwordx4 v[228:229], off
	s_add_i32 m0, s20, 0x2000
	s_add_u32 s20, s38, 0x20000
	v_lshl_add_u64 v[230:231], s[38:39], 0, v[130:131]
	s_addc_u32 s21, s39, 0
	s_add_i32 s27, s60, s46
	global_load_lds_dwordx4 v[230:231], off
	v_lshl_add_u64 v[232:233], s[20:21], 0, v[134:135]
	s_mov_b32 m0, s27
	v_lshl_add_u64 v[234:235], s[40:41], 0, v[132:133]
	global_load_lds_dwordx4 v[232:233], off
	v_lshl_add_u64 v[232:233], s[20:21], 0, v[130:131]
	s_add_i32 m0, s27, 0x2000
	s_nop 0
	global_load_lds_dwordx4 v[232:233], off
	v_lshl_add_u64 v[232:233], s[40:41], 0, v[136:137]
	s_mov_b32 m0, s49
	s_nop 0
	global_load_lds_dwordx4 v[232:233], off
	s_mov_b32 m0, s50
	s_nop 0
	global_load_lds_dwordx4 v[234:235], off
	s_waitcnt vmcnt(8)
	s_waitcnt lgkmcnt(0)
	s_waitcnt lgkmcnt(0)
	v_mfma_f32_16x16x32_bf16 v[62:65], v[154:157], v[196:199], v[62:65]
	v_mfma_f32_16x16x32_bf16 v[58:61], v[164:167], v[196:199], v[58:61]
	v_mfma_f32_16x16x32_bf16 v[54:57], v[154:157], v[204:207], v[54:57]
	v_mfma_f32_16x16x32_bf16 v[46:49], v[164:167], v[204:207], v[46:49]
	s_barrier
	v_mfma_f32_16x16x32_bf16 v[38:41], v[154:157], v[212:215], v[38:41]
	v_mfma_f32_16x16x32_bf16 v[30:33], v[164:167], v[212:215], v[30:33]
	v_mfma_f32_16x16x32_bf16 v[22:25], v[154:157], v[220:223], v[22:25]
	v_mfma_f32_16x16x32_bf16 v[14:17], v[164:167], v[220:223], v[14:17]
	v_mfma_f32_16x16x32_bf16 v[62:65], v[158:161], v[200:203], v[62:65]
	v_mfma_f32_16x16x32_bf16 v[58:61], v[168:171], v[200:203], v[58:61]
	v_mfma_f32_16x16x32_bf16 v[54:57], v[158:161], v[208:211], v[54:57]
	v_mfma_f32_16x16x32_bf16 v[46:49], v[168:171], v[208:211], v[46:49]
	v_mfma_f32_16x16x32_bf16 v[38:41], v[158:161], v[216:219], v[38:41]
	v_mfma_f32_16x16x32_bf16 v[30:33], v[168:171], v[216:219], v[30:33]
	v_mfma_f32_16x16x32_bf16 v[22:25], v[158:161], v[224:227], v[22:25]
	v_mfma_f32_16x16x32_bf16 v[14:17], v[168:171], v[224:227], v[14:17]
	v_mfma_f32_16x16x32_bf16 v[50:53], v[180:183], v[196:199], v[50:53]
	v_mfma_f32_16x16x32_bf16 v[42:45], v[188:191], v[196:199], v[42:45]
	v_mfma_f32_16x16x32_bf16 v[34:37], v[180:183], v[204:207], v[34:37]
	v_mfma_f32_16x16x32_bf16 v[26:29], v[188:191], v[204:207], v[26:29]
	v_mfma_f32_16x16x32_bf16 v[18:21], v[180:183], v[212:215], v[18:21]
	v_mfma_f32_16x16x32_bf16 v[10:13], v[188:191], v[212:215], v[10:13]
	v_mfma_f32_16x16x32_bf16 v[6:9], v[180:183], v[220:223], v[6:9]
	v_mfma_f32_16x16x32_bf16 v[2:5], v[188:191], v[220:223], v[2:5]
	v_mfma_f32_16x16x32_bf16 v[50:53], v[184:187], v[200:203], v[50:53]
	v_mfma_f32_16x16x32_bf16 v[42:45], v[192:195], v[200:203], v[42:45]
	v_mfma_f32_16x16x32_bf16 v[34:37], v[184:187], v[208:211], v[34:37]
	v_mfma_f32_16x16x32_bf16 v[26:29], v[192:195], v[208:211], v[26:29]
	v_mfma_f32_16x16x32_bf16 v[18:21], v[184:187], v[216:219], v[18:21]
	v_mfma_f32_16x16x32_bf16 v[10:13], v[192:195], v[216:219], v[10:13]
	v_mfma_f32_16x16x32_bf16 v[6:9], v[184:187], v[224:227], v[6:9]
	v_mfma_f32_16x16x32_bf16 v[2:5], v[192:195], v[224:227], v[2:5]
	s_barrier
	s_add_i32 s27, 0, 0x18000
	v_add_u32_e32 v153, s27, v173
	s_add_i32 s29, 0, 0x1c000
	ds_read_b128 v[154:157], v153
	ds_read_b128 v[158:161], v153 offset:1024
	ds_read_b128 v[164:167], v153 offset:2048
	ds_read_b128 v[168:171], v153 offset:3072
	v_add_u32_e32 v153, s29, v173
	ds_read_b128 v[180:183], v153
	ds_read_b128 v[184:187], v153 offset:1024
	ds_read_b128 v[188:191], v153 offset:2048
	ds_read_b128 v[192:195], v153 offset:3072
	s_add_u32 s20, s40, 0x20000
	s_addc_u32 s21, s41, 0
	s_mov_b32 m0, s51
	v_lshl_add_u64 v[236:237], s[20:21], 0, v[136:137]
	ds_read_b128 v[196:199], v177 offset:32768
	ds_read_b128 v[200:203], v177 offset:33792
	ds_read_b128 v[204:207], v177 offset:34816
	ds_read_b128 v[208:211], v177 offset:35840
	ds_read_b128 v[212:215], v177 offset:36864
	ds_read_b128 v[216:219], v177 offset:37888
	ds_read_b128 v[220:223], v177 offset:38912
	ds_read_b128 v[224:227], v177 offset:39936
	global_load_lds_dwordx4 v[236:237], off
	v_lshl_add_u64 v[236:237], s[20:21], 0, v[132:133]
	s_mov_b32 m0, s52
	s_nop 0
	global_load_lds_dwordx4 v[236:237], off
	s_waitcnt vmcnt(8)
	s_waitcnt lgkmcnt(0)
	s_waitcnt lgkmcnt(0)
	v_mfma_f32_16x16x32_bf16 v[126:129], v[154:157], v[196:199], v[126:129]
	v_mfma_f32_16x16x32_bf16 v[122:125], v[164:167], v[196:199], v[122:125]
	v_mfma_f32_16x16x32_bf16 v[118:121], v[154:157], v[204:207], v[118:121]
	v_mfma_f32_16x16x32_bf16 v[110:113], v[164:167], v[204:207], v[110:113]
	s_barrier
	v_mfma_f32_16x16x32_bf16 v[102:105], v[154:157], v[212:215], v[102:105]
	v_mfma_f32_16x16x32_bf16 v[94:97], v[164:167], v[212:215], v[94:97]
	v_mfma_f32_16x16x32_bf16 v[86:89], v[154:157], v[220:223], v[86:89]
	v_mfma_f32_16x16x32_bf16 v[78:81], v[164:167], v[220:223], v[78:81]
	v_mfma_f32_16x16x32_bf16 v[126:129], v[158:161], v[200:203], v[126:129]
	v_mfma_f32_16x16x32_bf16 v[122:125], v[168:171], v[200:203], v[122:125]
	v_mfma_f32_16x16x32_bf16 v[118:121], v[158:161], v[208:211], v[118:121]
	v_mfma_f32_16x16x32_bf16 v[110:113], v[168:171], v[208:211], v[110:113]
	v_mfma_f32_16x16x32_bf16 v[102:105], v[158:161], v[216:219], v[102:105]
	v_mfma_f32_16x16x32_bf16 v[94:97], v[168:171], v[216:219], v[94:97]
	v_mfma_f32_16x16x32_bf16 v[86:89], v[158:161], v[224:227], v[86:89]
	v_mfma_f32_16x16x32_bf16 v[78:81], v[168:171], v[224:227], v[78:81]
	v_mfma_f32_16x16x32_bf16 v[114:117], v[180:183], v[196:199], v[114:117]
	v_mfma_f32_16x16x32_bf16 v[106:109], v[188:191], v[196:199], v[106:109]
	v_mfma_f32_16x16x32_bf16 v[98:101], v[180:183], v[204:207], v[98:101]
	v_mfma_f32_16x16x32_bf16 v[90:93], v[188:191], v[204:207], v[90:93]
	v_mfma_f32_16x16x32_bf16 v[82:85], v[180:183], v[212:215], v[82:85]
	v_mfma_f32_16x16x32_bf16 v[74:77], v[188:191], v[212:215], v[74:77]
	v_mfma_f32_16x16x32_bf16 v[70:73], v[180:183], v[220:223], v[70:73]
	v_mfma_f32_16x16x32_bf16 v[66:69], v[188:191], v[220:223], v[66:69]
	v_mfma_f32_16x16x32_bf16 v[114:117], v[184:187], v[200:203], v[114:117]
	v_mfma_f32_16x16x32_bf16 v[106:109], v[192:195], v[200:203], v[106:109]
	v_mfma_f32_16x16x32_bf16 v[98:101], v[184:187], v[208:211], v[98:101]
	v_mfma_f32_16x16x32_bf16 v[90:93], v[192:195], v[208:211], v[90:93]
	v_mfma_f32_16x16x32_bf16 v[82:85], v[184:187], v[216:219], v[82:85]
	v_mfma_f32_16x16x32_bf16 v[74:77], v[192:195], v[216:219], v[74:77]
	v_mfma_f32_16x16x32_bf16 v[70:73], v[184:187], v[224:227], v[70:73]
	v_mfma_f32_16x16x32_bf16 v[66:69], v[192:195], v[224:227], v[66:69]
	s_barrier
	s_add_i32 s20, s27, s46
	v_lshl_add_u64 v[228:229], v[228:229], 0, s[22:23]
	s_mov_b32 m0, s20
	ds_read_b128 v[196:199], v177 offset:49152
	ds_read_b128 v[200:203], v177 offset:50176
	ds_read_b128 v[204:207], v177 offset:51200
	ds_read_b128 v[208:211], v177 offset:52224
	ds_read_b128 v[212:215], v177 offset:53248
	ds_read_b128 v[216:219], v177 offset:54272
	ds_read_b128 v[220:223], v177 offset:55296
	ds_read_b128 v[224:227], v177 offset:56320
	global_load_lds_dwordx4 v[228:229], off
	s_add_i32 m0, s20, 0x2000
	s_add_u32 s20, s38, 0x20080
	v_lshl_add_u64 v[228:229], v[230:231], 0, s[22:23]
	s_addc_u32 s21, s39, 0
	s_add_i32 s27, s29, s46
	global_load_lds_dwordx4 v[228:229], off
	v_lshl_add_u64 v[228:229], s[20:21], 0, v[134:135]
	s_mov_b32 m0, s27
	s_nop 0
	global_load_lds_dwordx4 v[228:229], off
	v_lshl_add_u64 v[228:229], s[20:21], 0, v[130:131]
	s_add_i32 m0, s27, 0x2000
	s_nop 0
	global_load_lds_dwordx4 v[228:229], off
	v_lshl_add_u64 v[228:229], v[232:233], 0, s[22:23]
	s_mov_b32 m0, s53
	s_nop 0
	global_load_lds_dwordx4 v[228:229], off
	v_lshl_add_u64 v[228:229], v[234:235], 0, s[22:23]
	s_mov_b32 m0, s54
	s_nop 0
	global_load_lds_dwordx4 v[228:229], off
	s_waitcnt vmcnt(8)
	s_waitcnt lgkmcnt(0)
	s_waitcnt lgkmcnt(0)
	v_mfma_f32_16x16x32_bf16 v[62:65], v[154:157], v[196:199], v[62:65]
	v_mfma_f32_16x16x32_bf16 v[58:61], v[164:167], v[196:199], v[58:61]
	v_mfma_f32_16x16x32_bf16 v[54:57], v[154:157], v[204:207], v[54:57]
	v_mfma_f32_16x16x32_bf16 v[46:49], v[164:167], v[204:207], v[46:49]
	s_barrier
	v_mfma_f32_16x16x32_bf16 v[38:41], v[154:157], v[212:215], v[38:41]
	v_mfma_f32_16x16x32_bf16 v[30:33], v[164:167], v[212:215], v[30:33]
	v_mfma_f32_16x16x32_bf16 v[22:25], v[154:157], v[220:223], v[22:25]
	v_mfma_f32_16x16x32_bf16 v[14:17], v[164:167], v[220:223], v[14:17]
	v_mfma_f32_16x16x32_bf16 v[62:65], v[158:161], v[200:203], v[62:65]
	v_mfma_f32_16x16x32_bf16 v[58:61], v[168:171], v[200:203], v[58:61]
	v_mfma_f32_16x16x32_bf16 v[54:57], v[158:161], v[208:211], v[54:57]
	v_mfma_f32_16x16x32_bf16 v[46:49], v[168:171], v[208:211], v[46:49]
	v_mfma_f32_16x16x32_bf16 v[38:41], v[158:161], v[216:219], v[38:41]
	v_mfma_f32_16x16x32_bf16 v[30:33], v[168:171], v[216:219], v[30:33]
	v_mfma_f32_16x16x32_bf16 v[22:25], v[158:161], v[224:227], v[22:25]
	v_mfma_f32_16x16x32_bf16 v[14:17], v[168:171], v[224:227], v[14:17]
	v_mfma_f32_16x16x32_bf16 v[50:53], v[180:183], v[196:199], v[50:53]
	v_mfma_f32_16x16x32_bf16 v[42:45], v[188:191], v[196:199], v[42:45]
	v_mfma_f32_16x16x32_bf16 v[34:37], v[180:183], v[204:207], v[34:37]
	v_mfma_f32_16x16x32_bf16 v[26:29], v[188:191], v[204:207], v[26:29]
	v_mfma_f32_16x16x32_bf16 v[18:21], v[180:183], v[212:215], v[18:21]
	v_mfma_f32_16x16x32_bf16 v[10:13], v[188:191], v[212:215], v[10:13]
	v_mfma_f32_16x16x32_bf16 v[6:9], v[180:183], v[220:223], v[6:9]
	v_mfma_f32_16x16x32_bf16 v[2:5], v[188:191], v[220:223], v[2:5]
	v_mfma_f32_16x16x32_bf16 v[50:53], v[184:187], v[200:203], v[50:53]
	v_mfma_f32_16x16x32_bf16 v[42:45], v[192:195], v[200:203], v[42:45]
	v_mfma_f32_16x16x32_bf16 v[34:37], v[184:187], v[208:211], v[34:37]
	v_mfma_f32_16x16x32_bf16 v[26:29], v[192:195], v[208:211], v[26:29]
	v_mfma_f32_16x16x32_bf16 v[18:21], v[184:187], v[216:219], v[18:21]
	v_mfma_f32_16x16x32_bf16 v[10:13], v[192:195], v[216:219], v[10:13]
	v_mfma_f32_16x16x32_bf16 v[6:9], v[184:187], v[224:227], v[6:9]
	v_mfma_f32_16x16x32_bf16 v[2:5], v[192:195], v[224:227], v[2:5]
	s_barrier
	s_add_i32 s19, s19, 2
	s_add_u32 s36, s36, 0x100
	s_addc_u32 s37, s37, 0
	s_add_u32 s17, s17, 0x100
	s_addc_u32 s18, s18, 0
	s_cmp_gt_u32 s19, 5
	s_cbranch_scc0 .LBB0_1336
	s_and_b64 vcc, exec, s[24:25]
	s_cbranch_vccz .LBB0_1339
	s_barrier

.LBB0_1497:
	ds_read_b128 v[134:137], v214
	ds_read_b128 v[138:141], v214 offset:1024
	ds_read_b128 v[142:145], v214 offset:2048
	ds_read_b128 v[178:181], v214 offset:3072
	ds_read_b128 v[182:185], v215
	ds_read_b128 v[186:189], v215 offset:1024
	ds_read_b128 v[190:193], v215 offset:2048
	ds_read_b128 v[194:197], v215 offset:3072
	s_add_u32 s40, s38, 0x100
	s_addc_u32 s41, s39, 0
	s_add_u32 s0, s15, s38
	s_addc_u32 s1, s16, s39
	s_cmp_eq_u32 s17, 28
	s_cselect_b32 s45, s3, s1
	s_cselect_b32 s1, 0, s40
	s_cselect_b32 s44, s14, s0
	s_cselect_b32 s0, 0, s41
	s_add_u32 s42, s10, s1
	s_addc_u32 s43, s11, s0
	s_mov_b32 m0, s64
	v_lshl_add_u64 v[244:245], v[130:131], 0, s[38:39]
	ds_read_b128 v[198:201], v216
	ds_read_b128 v[202:205], v216 offset:1024
	ds_read_b128 v[206:209], v216 offset:2048
	ds_read_b128 v[224:227], v216 offset:3072
	ds_read_b128 v[228:231], v216 offset:4096
	ds_read_b128 v[232:235], v216 offset:5120
	ds_read_b128 v[236:239], v216 offset:6144
	ds_read_b128 v[240:243], v216 offset:7168
	global_load_lds_dwordx4 v[244:245], off
	v_lshl_add_u64 v[244:245], v[132:133], 0, s[38:39]
	s_mov_b32 m0, s65
	s_nop 0
	global_load_lds_dwordx4 v[244:245], off
	s_waitcnt vmcnt(8)
	s_waitcnt lgkmcnt(0)
	s_waitcnt lgkmcnt(0)
	v_mfma_f32_16x16x32_bf16 v[82:85], v[134:137], v[198:201], v[82:85]
	v_mfma_f32_16x16x32_bf16 v[78:81], v[142:145], v[198:201], v[78:81]
	v_mfma_f32_16x16x32_bf16 v[110:113], v[134:137], v[206:209], v[110:113]
	v_mfma_f32_16x16x32_bf16 v[106:109], v[142:145], v[206:209], v[106:109]
	s_barrier
	v_mfma_f32_16x16x32_bf16 v[118:121], v[134:137], v[228:231], v[118:121]
	v_mfma_f32_16x16x32_bf16 v[114:117], v[142:145], v[228:231], v[114:117]
	v_mfma_f32_16x16x32_bf16 v[126:129], v[134:137], v[236:239], v[126:129]
	v_mfma_f32_16x16x32_bf16 v[122:125], v[142:145], v[236:239], v[122:125]
	v_mfma_f32_16x16x32_bf16 v[82:85], v[138:141], v[202:205], v[82:85]
	v_mfma_f32_16x16x32_bf16 v[78:81], v[178:181], v[202:205], v[78:81]
	v_mfma_f32_16x16x32_bf16 v[110:113], v[138:141], v[224:227], v[110:113]
	v_mfma_f32_16x16x32_bf16 v[106:109], v[178:181], v[224:227], v[106:109]
	v_mfma_f32_16x16x32_bf16 v[118:121], v[138:141], v[232:235], v[118:121]
	v_mfma_f32_16x16x32_bf16 v[114:117], v[178:181], v[232:235], v[114:117]
	v_mfma_f32_16x16x32_bf16 v[126:129], v[138:141], v[240:243], v[126:129]
	v_mfma_f32_16x16x32_bf16 v[122:125], v[178:181], v[240:243], v[122:125]
	v_mfma_f32_16x16x32_bf16 v[22:25], v[182:185], v[198:201], v[22:25]
	v_mfma_f32_16x16x32_bf16 v[26:29], v[190:193], v[198:201], v[26:29]
	v_mfma_f32_16x16x32_bf16 v[42:45], v[182:185], v[206:209], v[42:45]
	v_mfma_f32_16x16x32_bf16 v[46:49], v[190:193], v[206:209], v[46:49]
	v_mfma_f32_16x16x32_bf16 v[62:65], v[182:185], v[228:231], v[62:65]
	v_mfma_f32_16x16x32_bf16 v[70:73], v[190:193], v[228:231], v[70:73]
	v_mfma_f32_16x16x32_bf16 v[90:93], v[182:185], v[236:239], v[90:93]
	v_mfma_f32_16x16x32_bf16 v[94:97], v[190:193], v[236:239], v[94:97]
	v_mfma_f32_16x16x32_bf16 v[22:25], v[186:189], v[202:205], v[22:25]
	v_mfma_f32_16x16x32_bf16 v[26:29], v[194:197], v[202:205], v[26:29]
	v_mfma_f32_16x16x32_bf16 v[42:45], v[186:189], v[224:227], v[42:45]
	v_mfma_f32_16x16x32_bf16 v[46:49], v[194:197], v[224:227], v[46:49]
	v_mfma_f32_16x16x32_bf16 v[62:65], v[186:189], v[232:235], v[62:65]
	v_mfma_f32_16x16x32_bf16 v[70:73], v[194:197], v[232:235], v[70:73]
	v_mfma_f32_16x16x32_bf16 v[90:93], v[186:189], v[240:243], v[90:93]
	v_mfma_f32_16x16x32_bf16 v[94:97], v[194:197], v[240:243], v[94:97]
	s_barrier
	s_mov_b32 m0, s66
	v_lshl_add_u64 v[244:245], s[42:43], 0, v[150:151]
	s_add_u32 s18, s42, 0x80000
	ds_read_b128 v[198:201], v216 offset:16384
	ds_read_b128 v[202:205], v216 offset:17408
	ds_read_b128 v[206:209], v216 offset:18432
	ds_read_b128 v[224:227], v216 offset:19456
	ds_read_b128 v[228:231], v216 offset:20480
	ds_read_b128 v[232:235], v216 offset:21504
	ds_read_b128 v[236:239], v216 offset:22528
	ds_read_b128 v[240:243], v216 offset:23552
	global_load_lds_dwordx4 v[244:245], off
	v_lshl_add_u64 v[246:247], s[42:43], 0, v[146:147]
	s_mov_b32 m0, s67
	s_addc_u32 s19, s43, 0
	global_load_lds_dwordx4 v[246:247], off
	v_lshl_add_u64 v[248:249], s[18:19], 0, v[150:151]
	s_mov_b32 m0, s68
	v_lshl_add_u64 v[250:251], s[44:45], 0, v[148:149]
	global_load_lds_dwordx4 v[248:249], off
	v_lshl_add_u64 v[248:249], s[18:19], 0, v[146:147]
	s_mov_b32 m0, s69
	s_nop 0
	global_load_lds_dwordx4 v[248:249], off
	v_lshl_add_u64 v[248:249], s[44:45], 0, v[152:153]
	s_mov_b32 m0, s9
	s_nop 0
	global_load_lds_dwordx4 v[248:249], off
	s_mov_b32 m0, s55
	s_nop 0
	global_load_lds_dwordx4 v[250:251], off
	s_waitcnt vmcnt(8)
	s_waitcnt lgkmcnt(0)
	s_waitcnt lgkmcnt(0)
	v_mfma_f32_16x16x32_bf16 v[102:105], v[134:137], v[198:201], v[102:105]
	v_mfma_f32_16x16x32_bf16 v[98:101], v[142:145], v[198:201], v[98:101]
	v_mfma_f32_16x16x32_bf16 v[66:69], v[134:137], v[206:209], v[66:69]
	v_mfma_f32_16x16x32_bf16 v[58:61], v[142:145], v[206:209], v[58:61]
	s_barrier
	v_mfma_f32_16x16x32_bf16 v[38:41], v[134:137], v[228:231], v[38:41]
	v_mfma_f32_16x16x32_bf16 v[34:37], v[142:145], v[228:231], v[34:37]
	v_mfma_f32_16x16x32_bf16 v[14:17], v[134:137], v[236:239], v[14:17]
	v_mfma_f32_16x16x32_bf16 v[10:13], v[142:145], v[236:239], v[10:13]
	v_mfma_f32_16x16x32_bf16 v[102:105], v[138:141], v[202:205], v[102:105]
	v_mfma_f32_16x16x32_bf16 v[98:101], v[178:181], v[202:205], v[98:101]
	v_mfma_f32_16x16x32_bf16 v[66:69], v[138:141], v[224:227], v[66:69]
	v_mfma_f32_16x16x32_bf16 v[58:61], v[178:181], v[224:227], v[58:61]
	v_mfma_f32_16x16x32_bf16 v[38:41], v[138:141], v[232:235], v[38:41]
	v_mfma_f32_16x16x32_bf16 v[34:37], v[178:181], v[232:235], v[34:37]
	v_mfma_f32_16x16x32_bf16 v[14:17], v[138:141], v[240:243], v[14:17]
	v_mfma_f32_16x16x32_bf16 v[10:13], v[178:181], v[240:243], v[10:13]
	v_mfma_f32_16x16x32_bf16 v[86:89], v[182:185], v[198:201], v[86:89]
	v_mfma_f32_16x16x32_bf16 v[74:77], v[190:193], v[198:201], v[74:77]
	v_mfma_f32_16x16x32_bf16 v[54:57], v[182:185], v[206:209], v[54:57]
	v_mfma_f32_16x16x32_bf16 v[50:53], v[190:193], v[206:209], v[50:53]
	v_mfma_f32_16x16x32_bf16 v[30:33], v[182:185], v[228:231], v[30:33]
	v_mfma_f32_16x16x32_bf16 v[18:21], v[190:193], v[228:231], v[18:21]
	v_mfma_f32_16x16x32_bf16 v[6:9], v[182:185], v[236:239], v[6:9]
	v_mfma_f32_16x16x32_bf16 v[2:5], v[190:193], v[236:239], v[2:5]
	v_mfma_f32_16x16x32_bf16 v[86:89], v[186:189], v[202:205], v[86:89]
	v_mfma_f32_16x16x32_bf16 v[74:77], v[194:197], v[202:205], v[74:77]
	v_mfma_f32_16x16x32_bf16 v[54:57], v[186:189], v[224:227], v[54:57]
	v_mfma_f32_16x16x32_bf16 v[50:53], v[194:197], v[224:227], v[50:53]
	v_mfma_f32_16x16x32_bf16 v[30:33], v[186:189], v[232:235], v[30:33]
	v_mfma_f32_16x16x32_bf16 v[18:21], v[194:197], v[232:235], v[18:21]
	v_mfma_f32_16x16x32_bf16 v[6:9], v[186:189], v[240:243], v[6:9]
	v_mfma_f32_16x16x32_bf16 v[2:5], v[194:197], v[240:243], v[2:5]
	s_barrier
	s_add_i32 s0, 0, 0x1c000
	v_add_u32_e32 v194, s0, v212
	ds_read_b128 v[134:137], v220
	ds_read_b128 v[138:141], v220 offset:1024
	ds_read_b128 v[142:145], v220 offset:2048
	ds_read_b128 v[178:181], v220 offset:3072
	ds_read_b128 v[182:185], v194
	ds_read_b128 v[186:189], v194 offset:1024
	ds_read_b128 v[190:193], v194 offset:2048
	ds_read_b128 v[194:197], v194 offset:3072
	s_add_u32 s18, s44, 0x80000
	s_addc_u32 s19, s45, 0
	s_mov_b32 m0, s56
	v_lshl_add_u64 v[252:253], s[18:19], 0, v[152:153]
	ds_read_b128 v[198:201], v216 offset:32768
	ds_read_b128 v[202:205], v216 offset:33792
	ds_read_b128 v[206:209], v216 offset:34816
	ds_read_b128 v[224:227], v216 offset:35840
	ds_read_b128 v[228:231], v216 offset:36864
	ds_read_b128 v[232:235], v216 offset:37888
	ds_read_b128 v[236:239], v216 offset:38912
	ds_read_b128 v[240:243], v216 offset:39936
	global_load_lds_dwordx4 v[252:253], off
	v_lshl_add_u64 v[252:253], s[18:19], 0, v[148:149]
	s_mov_b32 m0, s57
	s_nop 0
	global_load_lds_dwordx4 v[252:253], off
	s_waitcnt vmcnt(8)
	s_waitcnt lgkmcnt(0)
	s_waitcnt lgkmcnt(0)
	v_mfma_f32_16x16x32_bf16 v[82:85], v[134:137], v[198:201], v[82:85]
	v_mfma_f32_16x16x32_bf16 v[78:81], v[142:145], v[198:201], v[78:81]
	v_mfma_f32_16x16x32_bf16 v[110:113], v[134:137], v[206:209], v[110:113]
	v_mfma_f32_16x16x32_bf16 v[106:109], v[142:145], v[206:209], v[106:109]
	s_barrier
	v_mfma_f32_16x16x32_bf16 v[118:121], v[134:137], v[228:231], v[118:121]
	v_mfma_f32_16x16x32_bf16 v[114:117], v[142:145], v[228:231], v[114:117]
	v_mfma_f32_16x16x32_bf16 v[126:129], v[134:137], v[236:239], v[126:129]
	v_mfma_f32_16x16x32_bf16 v[122:125], v[142:145], v[236:239], v[122:125]
	v_mfma_f32_16x16x32_bf16 v[82:85], v[138:141], v[202:205], v[82:85]
	v_mfma_f32_16x16x32_bf16 v[78:81], v[178:181], v[202:205], v[78:81]
	v_mfma_f32_16x16x32_bf16 v[110:113], v[138:141], v[224:227], v[110:113]
	v_mfma_f32_16x16x32_bf16 v[106:109], v[178:181], v[224:227], v[106:109]
	v_mfma_f32_16x16x32_bf16 v[118:121], v[138:141], v[232:235], v[118:121]
	v_mfma_f32_16x16x32_bf16 v[114:117], v[178:181], v[232:235], v[114:117]
	v_mfma_f32_16x16x32_bf16 v[126:129], v[138:141], v[240:243], v[126:129]
	v_mfma_f32_16x16x32_bf16 v[122:125], v[178:181], v[240:243], v[122:125]
	v_mfma_f32_16x16x32_bf16 v[22:25], v[182:185], v[198:201], v[22:25]
	v_mfma_f32_16x16x32_bf16 v[26:29], v[190:193], v[198:201], v[26:29]
	v_mfma_f32_16x16x32_bf16 v[42:45], v[182:185], v[206:209], v[42:45]
	v_mfma_f32_16x16x32_bf16 v[46:49], v[190:193], v[206:209], v[46:49]
	v_mfma_f32_16x16x32_bf16 v[62:65], v[182:185], v[228:231], v[62:65]
	v_mfma_f32_16x16x32_bf16 v[70:73], v[190:193], v[228:231], v[70:73]
	v_mfma_f32_16x16x32_bf16 v[90:93], v[182:185], v[236:239], v[90:93]
	v_mfma_f32_16x16x32_bf16 v[94:97], v[190:193], v[236:239], v[94:97]
	v_mfma_f32_16x16x32_bf16 v[22:25], v[186:189], v[202:205], v[22:25]
	v_mfma_f32_16x16x32_bf16 v[26:29], v[194:197], v[202:205], v[26:29]
	v_mfma_f32_16x16x32_bf16 v[42:45], v[186:189], v[224:227], v[42:45]
	v_mfma_f32_16x16x32_bf16 v[46:49], v[194:197], v[224:227], v[46:49]
	v_mfma_f32_16x16x32_bf16 v[62:65], v[186:189], v[232:235], v[62:65]
	v_mfma_f32_16x16x32_bf16 v[70:73], v[194:197], v[232:235], v[70:73]
	v_mfma_f32_16x16x32_bf16 v[90:93], v[186:189], v[240:243], v[90:93]
	v_mfma_f32_16x16x32_bf16 v[94:97], v[194:197], v[240:243], v[94:97]
	s_barrier
	s_add_i32 s1, s72, s54
	v_lshl_add_u64 v[244:245], v[244:245], 0, s[26:27]
	s_mov_b32 m0, s1
	ds_read_b128 v[198:201], v216 offset:49152
	ds_read_b128 v[202:205], v216 offset:50176
	ds_read_b128 v[206:209], v216 offset:51200
	ds_read_b128 v[224:227], v216 offset:52224
	ds_read_b128 v[228:231], v216 offset:53248
	ds_read_b128 v[232:235], v216 offset:54272
	ds_read_b128 v[236:239], v216 offset:55296
	ds_read_b128 v[240:243], v216 offset:56320
	global_load_lds_dwordx4 v[244:245], off
	s_add_i32 m0, s1, 0x2000
	s_add_u32 s18, s42, 0x80080
	v_lshl_add_u64 v[244:245], v[246:247], 0, s[26:27]
	s_addc_u32 s19, s43, 0
	s_add_i32 s0, s0, s54
	global_load_lds_dwordx4 v[244:245], off
	v_lshl_add_u64 v[244:245], s[18:19], 0, v[150:151]
	s_mov_b32 m0, s0
	s_nop 0
	global_load_lds_dwordx4 v[244:245], off
	v_lshl_add_u64 v[244:245], s[18:19], 0, v[146:147]
	s_add_i32 m0, s0, 0x2000
	s_nop 0
	global_load_lds_dwordx4 v[244:245], off
	v_lshl_add_u64 v[244:245], v[248:249], 0, s[26:27]
	s_mov_b32 m0, s61
	s_nop 0
	global_load_lds_dwordx4 v[244:245], off
	v_lshl_add_u64 v[244:245], v[250:251], 0, s[26:27]
	s_mov_b32 m0, s62
	s_nop 0
	global_load_lds_dwordx4 v[244:245], off
	s_waitcnt vmcnt(8)
	s_waitcnt lgkmcnt(0)
	s_waitcnt lgkmcnt(0)
	v_mfma_f32_16x16x32_bf16 v[102:105], v[134:137], v[198:201], v[102:105]
	v_mfma_f32_16x16x32_bf16 v[98:101], v[142:145], v[198:201], v[98:101]
	v_mfma_f32_16x16x32_bf16 v[66:69], v[134:137], v[206:209], v[66:69]
	v_mfma_f32_16x16x32_bf16 v[58:61], v[142:145], v[206:209], v[58:61]
	s_barrier
	v_mfma_f32_16x16x32_bf16 v[38:41], v[134:137], v[228:231], v[38:41]
	v_mfma_f32_16x16x32_bf16 v[34:37], v[142:145], v[228:231], v[34:37]
	v_mfma_f32_16x16x32_bf16 v[14:17], v[134:137], v[236:239], v[14:17]
	v_mfma_f32_16x16x32_bf16 v[10:13], v[142:145], v[236:239], v[10:13]
	v_mfma_f32_16x16x32_bf16 v[102:105], v[138:141], v[202:205], v[102:105]
	v_mfma_f32_16x16x32_bf16 v[98:101], v[178:181], v[202:205], v[98:101]
	v_mfma_f32_16x16x32_bf16 v[66:69], v[138:141], v[224:227], v[66:69]
	v_mfma_f32_16x16x32_bf16 v[58:61], v[178:181], v[224:227], v[58:61]
	v_mfma_f32_16x16x32_bf16 v[38:41], v[138:141], v[232:235], v[38:41]
	v_mfma_f32_16x16x32_bf16 v[34:37], v[178:181], v[232:235], v[34:37]
	v_mfma_f32_16x16x32_bf16 v[14:17], v[138:141], v[240:243], v[14:17]
	v_mfma_f32_16x16x32_bf16 v[10:13], v[178:181], v[240:243], v[10:13]
	v_mfma_f32_16x16x32_bf16 v[86:89], v[182:185], v[198:201], v[86:89]
	v_mfma_f32_16x16x32_bf16 v[74:77], v[190:193], v[198:201], v[74:77]
	v_mfma_f32_16x16x32_bf16 v[54:57], v[182:185], v[206:209], v[54:57]
	v_mfma_f32_16x16x32_bf16 v[50:53], v[190:193], v[206:209], v[50:53]
	v_mfma_f32_16x16x32_bf16 v[30:33], v[182:185], v[228:231], v[30:33]
	v_mfma_f32_16x16x32_bf16 v[18:21], v[190:193], v[228:231], v[18:21]
	v_mfma_f32_16x16x32_bf16 v[6:9], v[182:185], v[236:239], v[6:9]
	v_mfma_f32_16x16x32_bf16 v[2:5], v[190:193], v[236:239], v[2:5]
	v_mfma_f32_16x16x32_bf16 v[86:89], v[186:189], v[202:205], v[86:89]
	v_mfma_f32_16x16x32_bf16 v[74:77], v[194:197], v[202:205], v[74:77]
	v_mfma_f32_16x16x32_bf16 v[54:57], v[186:189], v[224:227], v[54:57]
	v_mfma_f32_16x16x32_bf16 v[50:53], v[194:197], v[224:227], v[50:53]
	v_mfma_f32_16x16x32_bf16 v[30:33], v[186:189], v[232:235], v[30:33]
	v_mfma_f32_16x16x32_bf16 v[18:21], v[194:197], v[232:235], v[18:21]
	v_mfma_f32_16x16x32_bf16 v[6:9], v[186:189], v[240:243], v[6:9]
	v_mfma_f32_16x16x32_bf16 v[2:5], v[194:197], v[240:243], v[2:5]
	s_barrier
	s_add_i32 s17, s17, 2
	s_cmp_gt_u32 s17, 29
	s_mov_b64 s[38:39], s[40:41]
	s_cbranch_scc0 .LBB0_1497
	s_and_b64 vcc, exec, s[28:29]
	s_cbranch_vccz .LBB0_1500
	s_barrier

.LBB0_1604:
	ds_read_b128 v[154:157], v151
	ds_read_b128 v[158:161], v151 offset:1024
	ds_read_b128 v[164:167], v151 offset:2048
	ds_read_b128 v[168:171], v151 offset:3072
	ds_read_b128 v[172:175], v152
	ds_read_b128 v[176:179], v152 offset:1024
	ds_read_b128 v[180:183], v152 offset:2048
	ds_read_b128 v[184:187], v152 offset:3072
	s_add_u32 s0, s34, 0xfff80080
	s_addc_u32 s1, s35, -1
	s_cmp_eq_u32 s53, 28
	s_cselect_b32 s39, s16, s1
	s_cselect_b32 s38, s17, s0
	s_cselect_b32 s37, s18, s25
	s_cselect_b32 s36, s19, s23
	v_lshl_add_u64 v[146:147], s[34:35], 0, v[138:139]
	s_add_i32 m0, s31, 0xc000
	ds_read_b128 v[188:191], v153
	ds_read_b128 v[192:195], v153 offset:1024
	ds_read_b128 v[196:199], v153 offset:2048
	ds_read_b128 v[200:203], v153 offset:3072
	ds_read_b128 v[204:207], v153 offset:4096
	ds_read_b128 v[208:211], v153 offset:5120
	ds_read_b128 v[212:215], v153 offset:6144
	ds_read_b128 v[216:219], v153 offset:7168
	global_load_lds_dwordx4 v[146:147], off
	v_lshl_add_u64 v[146:147], s[34:35], 0, v[140:141]
	s_add_i32 m0, s31, 0xe000
	s_nop 0
	global_load_lds_dwordx4 v[146:147], off
	s_waitcnt vmcnt(8)
	s_waitcnt lgkmcnt(0)
	s_waitcnt lgkmcnt(0)
	v_mfma_f32_16x16x32_bf16 v[126:129], v[154:157], v[188:191], v[126:129]
	v_mfma_f32_16x16x32_bf16 v[122:125], v[164:167], v[188:191], v[122:125]
	v_mfma_f32_16x16x32_bf16 v[110:113], v[154:157], v[196:199], v[110:113]
	v_mfma_f32_16x16x32_bf16 v[106:109], v[164:167], v[196:199], v[106:109]
	s_barrier
	v_mfma_f32_16x16x32_bf16 v[94:97], v[154:157], v[204:207], v[94:97]
	v_mfma_f32_16x16x32_bf16 v[90:93], v[164:167], v[204:207], v[90:93]
	v_mfma_f32_16x16x32_bf16 v[78:81], v[154:157], v[212:215], v[78:81]
	v_mfma_f32_16x16x32_bf16 v[74:77], v[164:167], v[212:215], v[74:77]
	v_mfma_f32_16x16x32_bf16 v[126:129], v[158:161], v[192:195], v[126:129]
	v_mfma_f32_16x16x32_bf16 v[122:125], v[168:171], v[192:195], v[122:125]
	v_mfma_f32_16x16x32_bf16 v[110:113], v[158:161], v[200:203], v[110:113]
	v_mfma_f32_16x16x32_bf16 v[106:109], v[168:171], v[200:203], v[106:109]
	v_mfma_f32_16x16x32_bf16 v[94:97], v[158:161], v[208:211], v[94:97]
	v_mfma_f32_16x16x32_bf16 v[90:93], v[168:171], v[208:211], v[90:93]
	v_mfma_f32_16x16x32_bf16 v[78:81], v[158:161], v[216:219], v[78:81]
	v_mfma_f32_16x16x32_bf16 v[74:77], v[168:171], v[216:219], v[74:77]
	v_mfma_f32_16x16x32_bf16 v[118:121], v[172:175], v[188:191], v[118:121]
	v_mfma_f32_16x16x32_bf16 v[114:117], v[180:183], v[188:191], v[114:117]
	v_mfma_f32_16x16x32_bf16 v[102:105], v[172:175], v[196:199], v[102:105]
	v_mfma_f32_16x16x32_bf16 v[98:101], v[180:183], v[196:199], v[98:101]
	v_mfma_f32_16x16x32_bf16 v[86:89], v[172:175], v[204:207], v[86:89]
	v_mfma_f32_16x16x32_bf16 v[82:85], v[180:183], v[204:207], v[82:85]
	v_mfma_f32_16x16x32_bf16 v[70:73], v[172:175], v[212:215], v[70:73]
	v_mfma_f32_16x16x32_bf16 v[66:69], v[180:183], v[212:215], v[66:69]
	v_mfma_f32_16x16x32_bf16 v[118:121], v[176:179], v[192:195], v[118:121]
	v_mfma_f32_16x16x32_bf16 v[114:117], v[184:187], v[192:195], v[114:117]
	v_mfma_f32_16x16x32_bf16 v[102:105], v[176:179], v[200:203], v[102:105]
	v_mfma_f32_16x16x32_bf16 v[98:101], v[184:187], v[200:203], v[98:101]
	v_mfma_f32_16x16x32_bf16 v[86:89], v[176:179], v[208:211], v[86:89]
	v_mfma_f32_16x16x32_bf16 v[82:85], v[184:187], v[208:211], v[82:85]
	v_mfma_f32_16x16x32_bf16 v[70:73], v[176:179], v[216:219], v[70:73]
	v_mfma_f32_16x16x32_bf16 v[66:69], v[184:187], v[216:219], v[66:69]
	s_barrier
	s_add_i32 s0, s15, s44
	v_lshl_add_u64 v[146:147], s[36:37], 0, v[134:135]
	s_mov_b32 m0, s0
	ds_read_b128 v[188:191], v153 offset:16384
	ds_read_b128 v[192:195], v153 offset:17408
	ds_read_b128 v[196:199], v153 offset:18432
	ds_read_b128 v[200:203], v153 offset:19456
	ds_read_b128 v[204:207], v153 offset:20480
	ds_read_b128 v[208:211], v153 offset:21504
	ds_read_b128 v[212:215], v153 offset:22528
	ds_read_b128 v[216:219], v153 offset:23552
	global_load_lds_dwordx4 v[146:147], off
	s_add_i32 m0, s0, 0x2000
	s_add_u32 s54, s36, 0x80000
	v_lshl_add_u64 v[220:221], s[36:37], 0, v[130:131]
	s_addc_u32 s55, s37, 0
	s_add_i32 s0, s51, s44
	global_load_lds_dwordx4 v[220:221], off
	v_lshl_add_u64 v[222:223], s[54:55], 0, v[134:135]
	s_mov_b32 m0, s0
	v_lshl_add_u64 v[224:225], s[38:39], 0, v[132:133]
	global_load_lds_dwordx4 v[222:223], off
	v_lshl_add_u64 v[222:223], s[54:55], 0, v[130:131]
	s_add_i32 m0, s0, 0x2000
	s_nop 0
	global_load_lds_dwordx4 v[222:223], off
	v_lshl_add_u64 v[222:223], s[38:39], 0, v[136:137]
	s_mov_b32 m0, s31
	s_nop 0
	global_load_lds_dwordx4 v[222:223], off
	s_mov_b32 m0, s47
	s_nop 0
	global_load_lds_dwordx4 v[224:225], off
	s_waitcnt vmcnt(8)
	s_waitcnt lgkmcnt(0)
	s_waitcnt lgkmcnt(0)
	v_mfma_f32_16x16x32_bf16 v[62:65], v[154:157], v[188:191], v[62:65]
	v_mfma_f32_16x16x32_bf16 v[58:61], v[164:167], v[188:191], v[58:61]
	v_mfma_f32_16x16x32_bf16 v[46:49], v[154:157], v[196:199], v[46:49]
	v_mfma_f32_16x16x32_bf16 v[42:45], v[164:167], v[196:199], v[42:45]
	s_barrier
	v_mfma_f32_16x16x32_bf16 v[30:33], v[154:157], v[204:207], v[30:33]
	v_mfma_f32_16x16x32_bf16 v[26:29], v[164:167], v[204:207], v[26:29]
	v_mfma_f32_16x16x32_bf16 v[14:17], v[154:157], v[212:215], v[14:17]
	v_mfma_f32_16x16x32_bf16 v[10:13], v[164:167], v[212:215], v[10:13]
	v_mfma_f32_16x16x32_bf16 v[62:65], v[158:161], v[192:195], v[62:65]
	v_mfma_f32_16x16x32_bf16 v[58:61], v[168:171], v[192:195], v[58:61]
	v_mfma_f32_16x16x32_bf16 v[46:49], v[158:161], v[200:203], v[46:49]
	v_mfma_f32_16x16x32_bf16 v[42:45], v[168:171], v[200:203], v[42:45]
	v_mfma_f32_16x16x32_bf16 v[30:33], v[158:161], v[208:211], v[30:33]
	v_mfma_f32_16x16x32_bf16 v[26:29], v[168:171], v[208:211], v[26:29]
	v_mfma_f32_16x16x32_bf16 v[14:17], v[158:161], v[216:219], v[14:17]
	v_mfma_f32_16x16x32_bf16 v[10:13], v[168:171], v[216:219], v[10:13]
	v_mfma_f32_16x16x32_bf16 v[54:57], v[172:175], v[188:191], v[54:57]
	v_mfma_f32_16x16x32_bf16 v[50:53], v[180:183], v[188:191], v[50:53]
	v_mfma_f32_16x16x32_bf16 v[38:41], v[172:175], v[196:199], v[38:41]
	v_mfma_f32_16x16x32_bf16 v[34:37], v[180:183], v[196:199], v[34:37]
	v_mfma_f32_16x16x32_bf16 v[22:25], v[172:175], v[204:207], v[22:25]
	v_mfma_f32_16x16x32_bf16 v[18:21], v[180:183], v[204:207], v[18:21]
	v_mfma_f32_16x16x32_bf16 v[6:9], v[172:175], v[212:215], v[6:9]
	v_mfma_f32_16x16x32_bf16 v[2:5], v[180:183], v[212:215], v[2:5]
	v_mfma_f32_16x16x32_bf16 v[54:57], v[176:179], v[192:195], v[54:57]
	v_mfma_f32_16x16x32_bf16 v[50:53], v[184:187], v[192:195], v[50:53]
	v_mfma_f32_16x16x32_bf16 v[38:41], v[176:179], v[200:203], v[38:41]
	v_mfma_f32_16x16x32_bf16 v[34:37], v[184:187], v[200:203], v[34:37]
	v_mfma_f32_16x16x32_bf16 v[22:25], v[176:179], v[208:211], v[22:25]
	v_mfma_f32_16x16x32_bf16 v[18:21], v[184:187], v[208:211], v[18:21]
	v_mfma_f32_16x16x32_bf16 v[6:9], v[176:179], v[216:219], v[6:9]
	v_mfma_f32_16x16x32_bf16 v[2:5], v[184:187], v[216:219], v[2:5]
	s_barrier
	s_add_i32 s0, 0, 0x18000
	v_add_u32_e32 v163, s0, v149
	s_add_i32 s1, 0, 0x1c000
	ds_read_b128 v[154:157], v163
	ds_read_b128 v[158:161], v163 offset:1024
	ds_read_b128 v[164:167], v163 offset:2048
	ds_read_b128 v[168:171], v163 offset:3072
	v_add_u32_e32 v163, s1, v149
	ds_read_b128 v[172:175], v163
	ds_read_b128 v[176:179], v163 offset:1024
	ds_read_b128 v[180:183], v163 offset:2048
	ds_read_b128 v[184:187], v163 offset:3072
	s_add_u32 s38, s38, 0x80000
	s_addc_u32 s39, s39, 0
	s_mov_b32 m0, s48
	v_lshl_add_u64 v[226:227], s[38:39], 0, v[136:137]
	ds_read_b128 v[188:191], v153 offset:32768
	ds_read_b128 v[192:195], v153 offset:33792
	ds_read_b128 v[196:199], v153 offset:34816
	ds_read_b128 v[200:203], v153 offset:35840
	ds_read_b128 v[204:207], v153 offset:36864
	ds_read_b128 v[208:211], v153 offset:37888
	ds_read_b128 v[212:215], v153 offset:38912
	ds_read_b128 v[216:219], v153 offset:39936
	global_load_lds_dwordx4 v[226:227], off
	v_lshl_add_u64 v[226:227], s[38:39], 0, v[132:133]
	s_mov_b32 m0, s49
	s_nop 0
	global_load_lds_dwordx4 v[226:227], off
	s_waitcnt vmcnt(8)
	s_waitcnt lgkmcnt(0)
	s_waitcnt lgkmcnt(0)
	v_mfma_f32_16x16x32_bf16 v[126:129], v[154:157], v[188:191], v[126:129]
	v_mfma_f32_16x16x32_bf16 v[122:125], v[164:167], v[188:191], v[122:125]
	v_mfma_f32_16x16x32_bf16 v[110:113], v[154:157], v[196:199], v[110:113]
	v_mfma_f32_16x16x32_bf16 v[106:109], v[164:167], v[196:199], v[106:109]
	s_barrier
	v_mfma_f32_16x16x32_bf16 v[94:97], v[154:157], v[204:207], v[94:97]
	v_mfma_f32_16x16x32_bf16 v[90:93], v[164:167], v[204:207], v[90:93]
	v_mfma_f32_16x16x32_bf16 v[78:81], v[154:157], v[212:215], v[78:81]
	v_mfma_f32_16x16x32_bf16 v[74:77], v[164:167], v[212:215], v[74:77]
	v_mfma_f32_16x16x32_bf16 v[126:129], v[158:161], v[192:195], v[126:129]
	v_mfma_f32_16x16x32_bf16 v[122:125], v[168:171], v[192:195], v[122:125]
	v_mfma_f32_16x16x32_bf16 v[110:113], v[158:161], v[200:203], v[110:113]
	v_mfma_f32_16x16x32_bf16 v[106:109], v[168:171], v[200:203], v[106:109]
	v_mfma_f32_16x16x32_bf16 v[94:97], v[158:161], v[208:211], v[94:97]
	v_mfma_f32_16x16x32_bf16 v[90:93], v[168:171], v[208:211], v[90:93]
	v_mfma_f32_16x16x32_bf16 v[78:81], v[158:161], v[216:219], v[78:81]
	v_mfma_f32_16x16x32_bf16 v[74:77], v[168:171], v[216:219], v[74:77]
	v_mfma_f32_16x16x32_bf16 v[118:121], v[172:175], v[188:191], v[118:121]
	v_mfma_f32_16x16x32_bf16 v[114:117], v[180:183], v[188:191], v[114:117]
	v_mfma_f32_16x16x32_bf16 v[102:105], v[172:175], v[196:199], v[102:105]
	v_mfma_f32_16x16x32_bf16 v[98:101], v[180:183], v[196:199], v[98:101]
	v_mfma_f32_16x16x32_bf16 v[86:89], v[172:175], v[204:207], v[86:89]
	v_mfma_f32_16x16x32_bf16 v[82:85], v[180:183], v[204:207], v[82:85]
	v_mfma_f32_16x16x32_bf16 v[70:73], v[172:175], v[212:215], v[70:73]
	v_mfma_f32_16x16x32_bf16 v[66:69], v[180:183], v[212:215], v[66:69]
	v_mfma_f32_16x16x32_bf16 v[118:121], v[176:179], v[192:195], v[118:121]
	v_mfma_f32_16x16x32_bf16 v[114:117], v[184:187], v[192:195], v[114:117]
	v_mfma_f32_16x16x32_bf16 v[102:105], v[176:179], v[200:203], v[102:105]
	v_mfma_f32_16x16x32_bf16 v[98:101], v[184:187], v[200:203], v[98:101]
	v_mfma_f32_16x16x32_bf16 v[86:89], v[176:179], v[208:211], v[86:89]
	v_mfma_f32_16x16x32_bf16 v[82:85], v[184:187], v[208:211], v[82:85]
	v_mfma_f32_16x16x32_bf16 v[70:73], v[176:179], v[216:219], v[70:73]
	v_mfma_f32_16x16x32_bf16 v[66:69], v[184:187], v[216:219], v[66:69]
	s_barrier
	s_add_i32 s0, s0, s44
	v_lshl_add_u64 v[146:147], v[146:147], 0, s[10:11]
	s_mov_b32 m0, s0
	ds_read_b128 v[188:191], v153 offset:49152
	ds_read_b128 v[192:195], v153 offset:50176
	ds_read_b128 v[196:199], v153 offset:51200
	ds_read_b128 v[200:203], v153 offset:52224
	ds_read_b128 v[204:207], v153 offset:53248
	ds_read_b128 v[208:211], v153 offset:54272
	ds_read_b128 v[212:215], v153 offset:55296
	ds_read_b128 v[216:219], v153 offset:56320
	global_load_lds_dwordx4 v[146:147], off
	s_add_i32 m0, s0, 0x2000
	s_add_u32 s36, s36, 0x80080
	v_lshl_add_u64 v[146:147], v[220:221], 0, s[10:11]
	s_addc_u32 s37, s37, 0
	s_add_i32 s0, s1, s44
	global_load_lds_dwordx4 v[146:147], off
	v_lshl_add_u64 v[146:147], s[36:37], 0, v[134:135]
	s_mov_b32 m0, s0
	s_nop 0
	global_load_lds_dwordx4 v[146:147], off
	v_lshl_add_u64 v[146:147], s[36:37], 0, v[130:131]
	s_add_i32 m0, s0, 0x2000
	s_nop 0
	global_load_lds_dwordx4 v[146:147], off
	v_lshl_add_u64 v[146:147], v[222:223], 0, s[10:11]
	s_mov_b32 m0, s20
	s_nop 0
	global_load_lds_dwordx4 v[146:147], off
	v_lshl_add_u64 v[146:147], v[224:225], 0, s[10:11]
	s_mov_b32 m0, s21
	s_nop 0
	global_load_lds_dwordx4 v[146:147], off
	s_waitcnt vmcnt(8)
	s_waitcnt lgkmcnt(0)
	s_waitcnt lgkmcnt(0)
	v_mfma_f32_16x16x32_bf16 v[62:65], v[154:157], v[188:191], v[62:65]
	v_mfma_f32_16x16x32_bf16 v[58:61], v[164:167], v[188:191], v[58:61]
	v_mfma_f32_16x16x32_bf16 v[46:49], v[154:157], v[196:199], v[46:49]
	v_mfma_f32_16x16x32_bf16 v[42:45], v[164:167], v[196:199], v[42:45]
	s_barrier
	v_mfma_f32_16x16x32_bf16 v[30:33], v[154:157], v[204:207], v[30:33]
	v_mfma_f32_16x16x32_bf16 v[26:29], v[164:167], v[204:207], v[26:29]
	v_mfma_f32_16x16x32_bf16 v[14:17], v[154:157], v[212:215], v[14:17]
	v_mfma_f32_16x16x32_bf16 v[10:13], v[164:167], v[212:215], v[10:13]
	v_mfma_f32_16x16x32_bf16 v[62:65], v[158:161], v[192:195], v[62:65]
	v_mfma_f32_16x16x32_bf16 v[58:61], v[168:171], v[192:195], v[58:61]
	v_mfma_f32_16x16x32_bf16 v[46:49], v[158:161], v[200:203], v[46:49]
	v_mfma_f32_16x16x32_bf16 v[42:45], v[168:171], v[200:203], v[42:45]
	v_mfma_f32_16x16x32_bf16 v[30:33], v[158:161], v[208:211], v[30:33]
	v_mfma_f32_16x16x32_bf16 v[26:29], v[168:171], v[208:211], v[26:29]
	v_mfma_f32_16x16x32_bf16 v[14:17], v[158:161], v[216:219], v[14:17]
	v_mfma_f32_16x16x32_bf16 v[10:13], v[168:171], v[216:219], v[10:13]
	v_mfma_f32_16x16x32_bf16 v[54:57], v[172:175], v[188:191], v[54:57]
	v_mfma_f32_16x16x32_bf16 v[50:53], v[180:183], v[188:191], v[50:53]
	v_mfma_f32_16x16x32_bf16 v[38:41], v[172:175], v[196:199], v[38:41]
	v_mfma_f32_16x16x32_bf16 v[34:37], v[180:183], v[196:199], v[34:37]
	v_mfma_f32_16x16x32_bf16 v[22:25], v[172:175], v[204:207], v[22:25]
	v_mfma_f32_16x16x32_bf16 v[18:21], v[180:183], v[204:207], v[18:21]
	v_mfma_f32_16x16x32_bf16 v[6:9], v[172:175], v[212:215], v[6:9]
	v_mfma_f32_16x16x32_bf16 v[2:5], v[180:183], v[212:215], v[2:5]
	v_mfma_f32_16x16x32_bf16 v[54:57], v[176:179], v[192:195], v[54:57]
	v_mfma_f32_16x16x32_bf16 v[50:53], v[184:187], v[192:195], v[50:53]
	v_mfma_f32_16x16x32_bf16 v[38:41], v[176:179], v[200:203], v[38:41]
	v_mfma_f32_16x16x32_bf16 v[34:37], v[184:187], v[200:203], v[34:37]
	v_mfma_f32_16x16x32_bf16 v[22:25], v[176:179], v[208:211], v[22:25]
	v_mfma_f32_16x16x32_bf16 v[18:21], v[184:187], v[208:211], v[18:21]
	v_mfma_f32_16x16x32_bf16 v[6:9], v[176:179], v[216:219], v[6:9]
	v_mfma_f32_16x16x32_bf16 v[2:5], v[184:187], v[216:219], v[2:5]
	s_barrier
	s_add_i32 s53, s53, 2
	s_add_u32 s34, s34, 0x100
	s_addc_u32 s35, s35, 0
	s_add_u32 s23, s23, 0x100
	s_addc_u32 s25, s25, 0
	s_cmp_gt_u32 s53, 29
	s_cbranch_scc0 .LBB0_1604
	s_and_b64 vcc, exec, s[12:13]
	s_cbranch_vccz .LBB0_1607
	s_barrier

.LBB0_1675:
	ds_read_b128 v[156:159], v191
	ds_read_b128 v[160:163], v191 offset:1024
	ds_read_b128 v[164:167], v191 offset:2048
	ds_read_b128 v[168:171], v191 offset:3072
	ds_read_b128 v[172:175], v192
	ds_read_b128 v[176:179], v192 offset:1024
	ds_read_b128 v[180:183], v192 offset:2048
	ds_read_b128 v[184:187], v192 offset:3072
	s_add_u32 s36, s30, 0xffea0080
	s_addc_u32 s37, s31, -1
	s_cmpk_eq_i32 s29, 0x54
	s_cselect_b32 s39, s25, s37
	s_cselect_b32 s38, s24, s36
	s_cselect_b32 s37, s5, s35
	s_cselect_b32 s36, s4, s34
	s_mov_b32 m0, s57
	v_lshl_add_u64 v[234:235], s[30:31], 0, v[150:151]
	ds_read_b128 v[202:205], v193
	ds_read_b128 v[206:209], v193 offset:1024
	ds_read_b128 v[210:213], v193 offset:2048
	ds_read_b128 v[214:217], v193 offset:3072
	ds_read_b128 v[218:221], v193 offset:4096
	ds_read_b128 v[222:225], v193 offset:5120
	ds_read_b128 v[226:229], v193 offset:6144
	ds_read_b128 v[230:233], v193 offset:7168
	global_load_lds_dwordx4 v[234:235], off
	v_lshl_add_u64 v[234:235], s[30:31], 0, v[152:153]
	s_mov_b32 m0, s58
	s_nop 0
	global_load_lds_dwordx4 v[234:235], off
	s_waitcnt vmcnt(8)
	s_waitcnt lgkmcnt(0)
	s_waitcnt lgkmcnt(0)
	v_mfma_f32_16x16x32_bf16 v[126:129], v[156:159], v[202:205], v[126:129]
	v_mfma_f32_16x16x32_bf16 v[122:125], v[164:167], v[202:205], v[122:125]
	v_mfma_f32_16x16x32_bf16 v[110:113], v[156:159], v[210:213], v[110:113]
	v_mfma_f32_16x16x32_bf16 v[106:109], v[164:167], v[210:213], v[106:109]
	s_barrier
	v_mfma_f32_16x16x32_bf16 v[94:97], v[156:159], v[218:221], v[94:97]
	v_mfma_f32_16x16x32_bf16 v[90:93], v[164:167], v[218:221], v[90:93]
	v_mfma_f32_16x16x32_bf16 v[78:81], v[156:159], v[226:229], v[78:81]
	v_mfma_f32_16x16x32_bf16 v[74:77], v[164:167], v[226:229], v[74:77]
	v_mfma_f32_16x16x32_bf16 v[126:129], v[160:163], v[206:209], v[126:129]
	v_mfma_f32_16x16x32_bf16 v[122:125], v[168:171], v[206:209], v[122:125]
	v_mfma_f32_16x16x32_bf16 v[110:113], v[160:163], v[214:217], v[110:113]
	v_mfma_f32_16x16x32_bf16 v[106:109], v[168:171], v[214:217], v[106:109]
	v_mfma_f32_16x16x32_bf16 v[94:97], v[160:163], v[222:225], v[94:97]
	v_mfma_f32_16x16x32_bf16 v[90:93], v[168:171], v[222:225], v[90:93]
	v_mfma_f32_16x16x32_bf16 v[78:81], v[160:163], v[230:233], v[78:81]
	v_mfma_f32_16x16x32_bf16 v[74:77], v[168:171], v[230:233], v[74:77]
	v_mfma_f32_16x16x32_bf16 v[118:121], v[172:175], v[202:205], v[118:121]
	v_mfma_f32_16x16x32_bf16 v[114:117], v[180:183], v[202:205], v[114:117]
	v_mfma_f32_16x16x32_bf16 v[102:105], v[172:175], v[210:213], v[102:105]
	v_mfma_f32_16x16x32_bf16 v[98:101], v[180:183], v[210:213], v[98:101]
	v_mfma_f32_16x16x32_bf16 v[86:89], v[172:175], v[218:221], v[86:89]
	v_mfma_f32_16x16x32_bf16 v[82:85], v[180:183], v[218:221], v[82:85]
	v_mfma_f32_16x16x32_bf16 v[70:73], v[172:175], v[226:229], v[70:73]
	v_mfma_f32_16x16x32_bf16 v[66:69], v[180:183], v[226:229], v[66:69]
	v_mfma_f32_16x16x32_bf16 v[118:121], v[176:179], v[206:209], v[118:121]
	v_mfma_f32_16x16x32_bf16 v[114:117], v[184:187], v[206:209], v[114:117]
	v_mfma_f32_16x16x32_bf16 v[102:105], v[176:179], v[214:217], v[102:105]
	v_mfma_f32_16x16x32_bf16 v[98:101], v[184:187], v[214:217], v[98:101]
	v_mfma_f32_16x16x32_bf16 v[86:89], v[176:179], v[222:225], v[86:89]
	v_mfma_f32_16x16x32_bf16 v[82:85], v[184:187], v[222:225], v[82:85]
	v_mfma_f32_16x16x32_bf16 v[70:73], v[176:179], v[230:233], v[70:73]
	v_mfma_f32_16x16x32_bf16 v[66:69], v[184:187], v[230:233], v[66:69]
	s_barrier
	s_mov_b32 m0, s59
	v_lshl_add_u64 v[234:235], s[36:37], 0, v[134:135]
	s_add_u32 s40, s36, 0x160000
	ds_read_b128 v[202:205], v193 offset:16384
	ds_read_b128 v[206:209], v193 offset:17408
	ds_read_b128 v[210:213], v193 offset:18432
	ds_read_b128 v[214:217], v193 offset:19456
	ds_read_b128 v[218:221], v193 offset:20480
	ds_read_b128 v[222:225], v193 offset:21504
	ds_read_b128 v[226:229], v193 offset:22528
	ds_read_b128 v[230:233], v193 offset:23552
	global_load_lds_dwordx4 v[234:235], off
	v_lshl_add_u64 v[236:237], s[36:37], 0, v[130:131]
	s_mov_b32 m0, s60
	s_addc_u32 s41, s37, 0
	global_load_lds_dwordx4 v[236:237], off
	v_lshl_add_u64 v[238:239], s[40:41], 0, v[134:135]
	s_mov_b32 m0, s61
	v_lshl_add_u64 v[240:241], s[38:39], 0, v[132:133]
	global_load_lds_dwordx4 v[238:239], off
	v_lshl_add_u64 v[238:239], s[40:41], 0, v[130:131]
	s_mov_b32 m0, s62
	s_nop 0
	global_load_lds_dwordx4 v[238:239], off
	v_lshl_add_u64 v[238:239], s[38:39], 0, v[136:137]
	s_mov_b32 m0, s48
	s_nop 0
	global_load_lds_dwordx4 v[238:239], off
	s_mov_b32 m0, s49
	s_nop 0
	global_load_lds_dwordx4 v[240:241], off
	s_waitcnt vmcnt(8)
	s_waitcnt lgkmcnt(0)
	s_waitcnt lgkmcnt(0)
	v_mfma_f32_16x16x32_bf16 v[62:65], v[156:159], v[202:205], v[62:65]
	v_mfma_f32_16x16x32_bf16 v[58:61], v[164:167], v[202:205], v[58:61]
	v_mfma_f32_16x16x32_bf16 v[46:49], v[156:159], v[210:213], v[46:49]
	v_mfma_f32_16x16x32_bf16 v[42:45], v[164:167], v[210:213], v[42:45]
	s_barrier
	v_mfma_f32_16x16x32_bf16 v[30:33], v[156:159], v[218:221], v[30:33]
	v_mfma_f32_16x16x32_bf16 v[26:29], v[164:167], v[218:221], v[26:29]
	v_mfma_f32_16x16x32_bf16 v[14:17], v[156:159], v[226:229], v[14:17]
	v_mfma_f32_16x16x32_bf16 v[10:13], v[164:167], v[226:229], v[10:13]
	v_mfma_f32_16x16x32_bf16 v[62:65], v[160:163], v[206:209], v[62:65]
	v_mfma_f32_16x16x32_bf16 v[58:61], v[168:171], v[206:209], v[58:61]
	v_mfma_f32_16x16x32_bf16 v[46:49], v[160:163], v[214:217], v[46:49]
	v_mfma_f32_16x16x32_bf16 v[42:45], v[168:171], v[214:217], v[42:45]
	v_mfma_f32_16x16x32_bf16 v[30:33], v[160:163], v[222:225], v[30:33]
	v_mfma_f32_16x16x32_bf16 v[26:29], v[168:171], v[222:225], v[26:29]
	v_mfma_f32_16x16x32_bf16 v[14:17], v[160:163], v[230:233], v[14:17]
	v_mfma_f32_16x16x32_bf16 v[10:13], v[168:171], v[230:233], v[10:13]
	v_mfma_f32_16x16x32_bf16 v[54:57], v[172:175], v[202:205], v[54:57]
	v_mfma_f32_16x16x32_bf16 v[50:53], v[180:183], v[202:205], v[50:53]
	v_mfma_f32_16x16x32_bf16 v[38:41], v[172:175], v[210:213], v[38:41]
	v_mfma_f32_16x16x32_bf16 v[34:37], v[180:183], v[210:213], v[34:37]
	v_mfma_f32_16x16x32_bf16 v[22:25], v[172:175], v[218:221], v[22:25]
	v_mfma_f32_16x16x32_bf16 v[18:21], v[180:183], v[218:221], v[18:21]
	v_mfma_f32_16x16x32_bf16 v[6:9], v[172:175], v[226:229], v[6:9]
	v_mfma_f32_16x16x32_bf16 v[2:5], v[180:183], v[226:229], v[2:5]
	v_mfma_f32_16x16x32_bf16 v[54:57], v[176:179], v[206:209], v[54:57]
	v_mfma_f32_16x16x32_bf16 v[50:53], v[184:187], v[206:209], v[50:53]
	v_mfma_f32_16x16x32_bf16 v[38:41], v[176:179], v[214:217], v[38:41]
	v_mfma_f32_16x16x32_bf16 v[34:37], v[184:187], v[214:217], v[34:37]
	v_mfma_f32_16x16x32_bf16 v[22:25], v[176:179], v[222:225], v[22:25]
	v_mfma_f32_16x16x32_bf16 v[18:21], v[184:187], v[222:225], v[18:21]
	v_mfma_f32_16x16x32_bf16 v[6:9], v[176:179], v[230:233], v[6:9]
	v_mfma_f32_16x16x32_bf16 v[2:5], v[184:187], v[230:233], v[2:5]
	s_barrier
	ds_read_b128 v[156:159], v197
	ds_read_b128 v[160:163], v197 offset:1024
	ds_read_b128 v[164:167], v197 offset:2048
	ds_read_b128 v[168:171], v197 offset:3072
	ds_read_b128 v[172:175], v198
	ds_read_b128 v[176:179], v198 offset:1024
	ds_read_b128 v[180:183], v198 offset:2048
	ds_read_b128 v[184:187], v198 offset:3072
	s_add_u32 s38, s38, 0x160000
	s_addc_u32 s39, s39, 0
	s_mov_b32 m0, s50
	v_lshl_add_u64 v[242:243], s[38:39], 0, v[136:137]
	ds_read_b128 v[202:205], v193 offset:32768
	ds_read_b128 v[206:209], v193 offset:33792
	ds_read_b128 v[210:213], v193 offset:34816
	ds_read_b128 v[214:217], v193 offset:35840
	ds_read_b128 v[218:221], v193 offset:36864
	ds_read_b128 v[222:225], v193 offset:37888
	ds_read_b128 v[226:229], v193 offset:38912
	ds_read_b128 v[230:233], v193 offset:39936
	global_load_lds_dwordx4 v[242:243], off
	v_lshl_add_u64 v[242:243], s[38:39], 0, v[132:133]
	s_mov_b32 m0, s51
	s_nop 0
	global_load_lds_dwordx4 v[242:243], off
	s_waitcnt vmcnt(8)
	s_waitcnt lgkmcnt(0)
	s_waitcnt lgkmcnt(0)
	v_mfma_f32_16x16x32_bf16 v[126:129], v[156:159], v[202:205], v[126:129]
	v_mfma_f32_16x16x32_bf16 v[122:125], v[164:167], v[202:205], v[122:125]
	v_mfma_f32_16x16x32_bf16 v[110:113], v[156:159], v[210:213], v[110:113]
	v_mfma_f32_16x16x32_bf16 v[106:109], v[164:167], v[210:213], v[106:109]
	s_barrier
	v_mfma_f32_16x16x32_bf16 v[94:97], v[156:159], v[218:221], v[94:97]
	v_mfma_f32_16x16x32_bf16 v[90:93], v[164:167], v[218:221], v[90:93]
	v_mfma_f32_16x16x32_bf16 v[78:81], v[156:159], v[226:229], v[78:81]
	v_mfma_f32_16x16x32_bf16 v[74:77], v[164:167], v[226:229], v[74:77]
	v_mfma_f32_16x16x32_bf16 v[126:129], v[160:163], v[206:209], v[126:129]
	v_mfma_f32_16x16x32_bf16 v[122:125], v[168:171], v[206:209], v[122:125]
	v_mfma_f32_16x16x32_bf16 v[110:113], v[160:163], v[214:217], v[110:113]
	v_mfma_f32_16x16x32_bf16 v[106:109], v[168:171], v[214:217], v[106:109]
	v_mfma_f32_16x16x32_bf16 v[94:97], v[160:163], v[222:225], v[94:97]
	v_mfma_f32_16x16x32_bf16 v[90:93], v[168:171], v[222:225], v[90:93]
	v_mfma_f32_16x16x32_bf16 v[78:81], v[160:163], v[230:233], v[78:81]
	v_mfma_f32_16x16x32_bf16 v[74:77], v[168:171], v[230:233], v[74:77]
	v_mfma_f32_16x16x32_bf16 v[118:121], v[172:175], v[202:205], v[118:121]
	v_mfma_f32_16x16x32_bf16 v[114:117], v[180:183], v[202:205], v[114:117]
	v_mfma_f32_16x16x32_bf16 v[102:105], v[172:175], v[210:213], v[102:105]
	v_mfma_f32_16x16x32_bf16 v[98:101], v[180:183], v[210:213], v[98:101]
	v_mfma_f32_16x16x32_bf16 v[86:89], v[172:175], v[218:221], v[86:89]
	v_mfma_f32_16x16x32_bf16 v[82:85], v[180:183], v[218:221], v[82:85]
	v_mfma_f32_16x16x32_bf16 v[70:73], v[172:175], v[226:229], v[70:73]
	v_mfma_f32_16x16x32_bf16 v[66:69], v[180:183], v[226:229], v[66:69]
	v_mfma_f32_16x16x32_bf16 v[118:121], v[176:179], v[206:209], v[118:121]
	v_mfma_f32_16x16x32_bf16 v[114:117], v[184:187], v[206:209], v[114:117]
	v_mfma_f32_16x16x32_bf16 v[102:105], v[176:179], v[214:217], v[102:105]
	v_mfma_f32_16x16x32_bf16 v[98:101], v[184:187], v[214:217], v[98:101]
	v_mfma_f32_16x16x32_bf16 v[86:89], v[176:179], v[222:225], v[86:89]
	v_mfma_f32_16x16x32_bf16 v[82:85], v[184:187], v[222:225], v[82:85]
	v_mfma_f32_16x16x32_bf16 v[70:73], v[176:179], v[230:233], v[70:73]
	v_mfma_f32_16x16x32_bf16 v[66:69], v[184:187], v[230:233], v[66:69]
	s_barrier
	s_mov_b32 m0, s64
	v_lshl_add_u64 v[234:235], v[234:235], 0, s[12:13]
	s_add_u32 s36, s36, 0x160080
	ds_read_b128 v[202:205], v193 offset:49152
	ds_read_b128 v[206:209], v193 offset:50176
	ds_read_b128 v[210:213], v193 offset:51200
	ds_read_b128 v[214:217], v193 offset:52224
	ds_read_b128 v[218:221], v193 offset:53248
	ds_read_b128 v[222:225], v193 offset:54272
	ds_read_b128 v[226:229], v193 offset:55296
	ds_read_b128 v[230:233], v193 offset:56320
	global_load_lds_dwordx4 v[234:235], off
	v_lshl_add_u64 v[234:235], v[236:237], 0, s[12:13]
	s_mov_b32 m0, s65
	s_addc_u32 s37, s37, 0
	s_add_i32 s38, s63, s47
	global_load_lds_dwordx4 v[234:235], off
	v_lshl_add_u64 v[234:235], s[36:37], 0, v[134:135]
	s_mov_b32 m0, s38
	s_nop 0
	global_load_lds_dwordx4 v[234:235], off
	v_lshl_add_u64 v[234:235], s[36:37], 0, v[130:131]
	s_add_i32 m0, s38, 0x2000
	s_nop 0
	global_load_lds_dwordx4 v[234:235], off
	v_lshl_add_u64 v[234:235], v[238:239], 0, s[12:13]
	s_mov_b32 m0, s55
	s_nop 0
	global_load_lds_dwordx4 v[234:235], off
	v_lshl_add_u64 v[234:235], v[240:241], 0, s[12:13]
	s_mov_b32 m0, s56
	s_nop 0
	global_load_lds_dwordx4 v[234:235], off
	s_waitcnt vmcnt(8)
	s_waitcnt lgkmcnt(0)
	s_waitcnt lgkmcnt(0)
	v_mfma_f32_16x16x32_bf16 v[62:65], v[156:159], v[202:205], v[62:65]
	v_mfma_f32_16x16x32_bf16 v[58:61], v[164:167], v[202:205], v[58:61]
	v_mfma_f32_16x16x32_bf16 v[46:49], v[156:159], v[210:213], v[46:49]
	v_mfma_f32_16x16x32_bf16 v[42:45], v[164:167], v[210:213], v[42:45]
	s_barrier
	v_mfma_f32_16x16x32_bf16 v[30:33], v[156:159], v[218:221], v[30:33]
	v_mfma_f32_16x16x32_bf16 v[26:29], v[164:167], v[218:221], v[26:29]
	v_mfma_f32_16x16x32_bf16 v[14:17], v[156:159], v[226:229], v[14:17]
	v_mfma_f32_16x16x32_bf16 v[10:13], v[164:167], v[226:229], v[10:13]
	v_mfma_f32_16x16x32_bf16 v[62:65], v[160:163], v[206:209], v[62:65]
	v_mfma_f32_16x16x32_bf16 v[58:61], v[168:171], v[206:209], v[58:61]
	v_mfma_f32_16x16x32_bf16 v[46:49], v[160:163], v[214:217], v[46:49]
	v_mfma_f32_16x16x32_bf16 v[42:45], v[168:171], v[214:217], v[42:45]
	v_mfma_f32_16x16x32_bf16 v[30:33], v[160:163], v[222:225], v[30:33]
	v_mfma_f32_16x16x32_bf16 v[26:29], v[168:171], v[222:225], v[26:29]
	v_mfma_f32_16x16x32_bf16 v[14:17], v[160:163], v[230:233], v[14:17]
	v_mfma_f32_16x16x32_bf16 v[10:13], v[168:171], v[230:233], v[10:13]
	v_mfma_f32_16x16x32_bf16 v[54:57], v[172:175], v[202:205], v[54:57]
	v_mfma_f32_16x16x32_bf16 v[50:53], v[180:183], v[202:205], v[50:53]
	v_mfma_f32_16x16x32_bf16 v[38:41], v[172:175], v[210:213], v[38:41]
	v_mfma_f32_16x16x32_bf16 v[34:37], v[180:183], v[210:213], v[34:37]
	v_mfma_f32_16x16x32_bf16 v[22:25], v[172:175], v[218:221], v[22:25]
	v_mfma_f32_16x16x32_bf16 v[18:21], v[180:183], v[218:221], v[18:21]
	v_mfma_f32_16x16x32_bf16 v[6:9], v[172:175], v[226:229], v[6:9]
	v_mfma_f32_16x16x32_bf16 v[2:5], v[180:183], v[226:229], v[2:5]
	v_mfma_f32_16x16x32_bf16 v[54:57], v[176:179], v[206:209], v[54:57]
	v_mfma_f32_16x16x32_bf16 v[50:53], v[184:187], v[206:209], v[50:53]
	v_mfma_f32_16x16x32_bf16 v[38:41], v[176:179], v[214:217], v[38:41]
	v_mfma_f32_16x16x32_bf16 v[34:37], v[184:187], v[214:217], v[34:37]
	v_mfma_f32_16x16x32_bf16 v[22:25], v[176:179], v[222:225], v[22:25]
	v_mfma_f32_16x16x32_bf16 v[18:21], v[184:187], v[222:225], v[18:21]
	v_mfma_f32_16x16x32_bf16 v[6:9], v[176:179], v[230:233], v[6:9]
	v_mfma_f32_16x16x32_bf16 v[2:5], v[184:187], v[230:233], v[2:5]
	s_barrier
	s_add_i32 s29, s29, 2
	s_add_u32 s30, s30, 0x100
	s_addc_u32 s31, s31, 0
	s_add_u32 s34, s34, 0x100
	s_addc_u32 s35, s35, 0
	s_cmpk_gt_u32 s29, 0x55
	s_cbranch_scc0 .LBB0_1675
	s_and_b64 vcc, exec, s[14:15]
	s_cbranch_vccz .LBB0_1678
	s_barrier
